# adds DeltaNet DK forward-substitution LDS read prefetch (renamed destinations, recomputed waits) on top of attention LDS-DMA staging
# speedup vs baseline: 1.0035x; 1.0035x over previous
; __device__ __forceinline__ unsigned pk2(float lo, float hi) { const f32x2_cv v = {lo, hi}; const bf16x2_cv b = __builtin_convertvector(v, bf16x2_cv); return __builtin_bit_cast(unsigned, b); }
; __device__ __forceinline__ int crow16(int r, int hi) { return (r & 3) + 8 * (r >> 2) + 4 * hi; }
; __device__ __forceinline__ void dk_phase(const Frame& F, const bf16* QKrm, const unsigned char* KT, const unsigned char* VT, const float* BG, unsigned char* ITEMS) {
;     ...
;             bf16x8_t Qn[2][8];
; #pragma unroll
;             for (int mi = 0; mi < 2; ++mi)
; #pragma unroll
;                 for (int ks = 0; ks < 8; ++ks) Qn[mi][ks] = as_frag(*(const v4u*)(Qb + (size_t)(32 * mi + r32) * 4096 + 16 * ks));
; #pragma unroll
;             for (int ri = 0; ri < 2; ++ri) { const int r = 32 * ri + r32; const float gr = gamL[r];
; #pragma unroll
;                 for (int si = 0; si < 2; ++si) { f32x16_t p = f32x16_t{};
; #pragma unroll
;                     for (int ks = 0; ks < 8; ++ks) p = __builtin_amdgcn_mfma_f32_32x32x16_bf16(Kn[si][ks], Qn[ri][ks], p, 0, 0, 0);
;                     float pv[16];
; #pragma unroll
;                     for (int rg = 0; rg < 16; ++rg) { const int s = 32 * si + crow16(rg, hi); const float gs = gamL[s];
;                         const bool ok = dir ? (s >= r) : (s <= r);
;                         pv[rg] = ok ? p[rg] * __expf(gr - gs) : 0.f; }
; #pragma unroll
;                     for (int st = 0; st < 2; ++st) { v4u wv; wv.x = pk2(pv[8 * st + 0], pv[8 * st + 1]); wv.y = pk2(pv[8 * st + 2], pv[8 * st + 3]); wv.z = pk2(pv[8 * st + 4], pv[8 * st + 5]); wv.w = pk2(pv[8 * st + 6], pv[8 * st + 7]);
;                         *(v4u*)(item + ITEM_AQK + ((ri * 2 + si) * 2 + st) * 1024 + lane * 16) = wv; } } }
.LBB0_460:
	s_or_b64 exec, exec, s[20:21]
	v_add_u32_e32 v5, v20, v50
	ds_write_b32 v5, v4
	s_lshl_b32 s20, s46, 1
	s_add_u32 s42, s44, s20
	s_addc_u32 s43, s45, 0
	s_ashr_i32 s20, s52, 6
	v_lshl_add_u64 v[4:5], v[164:165], 1, s[42:43]
	v_lshlrev_b32_e32 v6, 1, v132
	v_mov_b32_e32 v7, v3
	v_lshl_add_u64 v[6:7], v[4:5], 0, v[6:7]
	global_load_dwordx4 v[160:163], v[6:7], off
	global_load_dwordx4 v[156:159], v[6:7], off offset:32
	global_load_dwordx4 v[152:155], v[6:7], off offset:64
	global_load_dwordx4 v[148:151], v[6:7], off offset:96
	global_load_dwordx4 v[144:147], v[6:7], off offset:128
	global_load_dwordx4 v[140:143], v[6:7], off offset:160
	global_load_dwordx4 v[132:135], v[6:7], off offset:192
	global_load_dwordx4 v[136:139], v[6:7], off offset:224
	v_lshl_add_u64 v[4:5], v[4:5], 0, v[2:3]
	s_waitcnt lgkmcnt(14)
	global_load_dwordx4 v[48:51], v[4:5], off
	global_load_dwordx4 v[44:47], v[4:5], off offset:32
	global_load_dwordx4 v[40:43], v[4:5], off offset:64
	global_load_dwordx4 v[36:39], v[4:5], off offset:96
	global_load_dwordx4 v[32:35], v[4:5], off offset:128
	global_load_dwordx4 v[28:31], v[4:5], off offset:160
	global_load_dwordx4 v[20:23], v[4:5], off offset:192
	global_load_dwordx4 v[24:27], v[4:5], off offset:224
	v_add_u32_e32 v2, 0x4400, v170
	ds_read2_b32 v[180:181], v2 offset1:32
	ds_read_b128 v[56:59], v226 offset:17408
	ds_read_b128 v[52:55], v226 offset:17440
	v_cmp_ge_i32_e64 s[42:43], v223, v186
	v_cmp_le_i32_e64 s[44:45], v223, v186
	v_cmp_lt_i32_e64 s[46:47], v223, v186
	v_cndmask_b32_e64 v61, 0, 1, s[42:43]
	v_cndmask_b32_e64 v60, 0, 1, s[44:45]
	v_cndmask_b32_e64 v60, v61, v60, s[40:41]
	v_and_b32_e32 v60, 1, v60
	v_cmp_eq_u32_e64 s[42:43], 1, v60
	s_waitcnt lgkmcnt(1)
	v_sub_f32_e32 v60, v180, v56
	v_mul_f32_e32 v60, 0x3fb8aa3b, v60
	v_exp_f32_e32 v60, v60
	v_cmp_ge_i32_e64 s[44:45], v225, v186
	v_cndmask_b32_e64 v165, 0, 1, s[46:47]
	v_cmp_le_i32_e64 s[46:47], v224, v186
	v_lshlrev_b32_e32 v168, 4, v185
	v_ashrrev_i32_e32 v169, 31, v168
	v_lshl_add_u64 v[166:167], s[18:19], 0, v[168:169]
	s_movk_i32 s21, 0xa000
	v_sub_f32_e32 v56, v181, v56
	v_mul_f32_e32 v56, 0x3fb8aa3b, v56
	v_exp_f32_e32 v56, v56
	v_mov_b32_e32 v2, s53
	s_waitcnt vmcnt(15)
	v_mfma_f32_32x32x16_bf16 v[4:19], v[124:127], v[160:163], 0
	s_waitcnt vmcnt(14)
	v_mfma_f32_32x32x16_bf16 v[4:19], v[120:123], v[156:159], v[4:19]
	s_waitcnt vmcnt(13)
	v_mfma_f32_32x32x16_bf16 v[4:19], v[128:131], v[152:155], v[4:19]
	s_waitcnt vmcnt(12)
	v_mfma_f32_32x32x16_bf16 v[4:19], v[116:119], v[148:151], v[4:19]
	s_waitcnt vmcnt(11)
	v_mfma_f32_32x32x16_bf16 v[4:19], v[112:115], v[144:147], v[4:19]
	s_waitcnt vmcnt(10)
	v_mfma_f32_32x32x16_bf16 v[4:19], v[108:111], v[140:143], v[4:19]
	s_waitcnt vmcnt(9)
	v_mfma_f32_32x32x16_bf16 v[4:19], v[104:107], v[132:135], v[4:19]
	s_waitcnt vmcnt(8)
	v_mfma_f32_32x32x16_bf16 v[4:19], v[100:103], v[136:139], v[4:19]
	s_nop 11
	v_mul_f32_e32 v4, v4, v60
	v_cndmask_b32_e64 v60, 0, 1, s[44:45]
	v_cndmask_b32_e64 v60, v60, v165, s[40:41]
	v_and_b32_e32 v60, 1, v60
	v_cmp_eq_u32_e64 s[44:45], 1, v60
	v_sub_f32_e32 v60, v180, v57
	v_mul_f32_e32 v60, 0x3fb8aa3b, v60
	v_exp_f32_e32 v60, v60
	v_cndmask_b32_e64 v4, 0, v4, s[42:43]
	v_mul_f32_e32 v5, v5, v60
	v_cndmask_b32_e64 v5, 0, v5, s[44:45]
	v_cmp_ge_i32_e64 s[44:45], v224, v186
	v_cndmask_b32_e64 v60, 0, 1, s[46:47]
	v_cmp_le_i32_e64 s[46:47], v222, v186
	v_cndmask_b32_e64 v61, 0, 1, s[44:45]
	v_cndmask_b32_e64 v60, v61, v60, s[40:41]
	v_and_b32_e32 v60, 1, v60
	v_cmp_eq_u32_e64 s[44:45], 1, v60
	v_sub_f32_e32 v60, v180, v58
	v_mul_f32_e32 v60, 0x3fb8aa3b, v60
	v_exp_f32_e32 v60, v60
	v_cvt_pk_bf16_f32 v4, v4, v5
	v_mul_f32_e32 v6, v6, v60
	v_cndmask_b32_e64 v6, 0, v6, s[44:45]
	v_cmp_ge_i32_e64 s[44:45], v222, v186
	v_cndmask_b32_e64 v60, 0, 1, s[46:47]
	v_cmp_le_i32_e64 s[46:47], v221, v186
	v_cndmask_b32_e64 v61, 0, 1, s[44:45]
	v_cndmask_b32_e64 v60, v61, v60, s[40:41]
	v_and_b32_e32 v60, 1, v60
	v_cmp_eq_u32_e64 s[44:45], 1, v60
	v_sub_f32_e32 v60, v180, v59
	v_mul_f32_e32 v60, 0x3fb8aa3b, v60
	v_exp_f32_e32 v60, v60
	s_nop 0
	v_mul_f32_e32 v7, v7, v60
	v_cndmask_b32_e64 v7, 0, v7, s[44:45]
	v_cmp_ge_i32_e64 s[44:45], v221, v186
	v_cndmask_b32_e64 v60, 0, 1, s[46:47]
	v_cmp_le_i32_e64 s[46:47], v220, v186
	v_cndmask_b32_e64 v61, 0, 1, s[44:45]
	v_cndmask_b32_e64 v60, v61, v60, s[40:41]
	v_and_b32_e32 v60, 1, v60
	v_cmp_eq_u32_e64 s[44:45], 1, v60
	s_waitcnt lgkmcnt(0)
	v_sub_f32_e32 v60, v180, v52
	v_mul_f32_e32 v60, 0x3fb8aa3b, v60
	v_exp_f32_e32 v60, v60
	v_cvt_pk_bf16_f32 v5, v6, v7
	v_sub_f32_e32 v52, v181, v52
	v_mul_f32_e32 v52, 0x3fb8aa3b, v52
	v_mul_f32_e32 v8, v8, v60
	v_cndmask_b32_e64 v8, 0, v8, s[44:45]
	v_cmp_ge_i32_e64 s[44:45], v220, v186
	v_cndmask_b32_e64 v60, 0, 1, s[46:47]
	v_cmp_le_i32_e64 s[46:47], v219, v186
	v_cndmask_b32_e64 v61, 0, 1, s[44:45]
	v_cndmask_b32_e64 v60, v61, v60, s[40:41]
	v_and_b32_e32 v60, 1, v60
	v_cmp_eq_u32_e64 s[44:45], 1, v60
	v_sub_f32_e32 v60, v180, v53
	v_mul_f32_e32 v60, 0x3fb8aa3b, v60
	v_exp_f32_e32 v60, v60
	v_exp_f32_e32 v52, v52
	v_mul_f32_e32 v9, v9, v60
	v_cndmask_b32_e64 v9, 0, v9, s[44:45]
	v_cmp_ge_i32_e64 s[44:45], v219, v186
	v_cndmask_b32_e64 v60, 0, 1, s[46:47]
	v_cmp_le_i32_e64 s[46:47], v218, v186
	v_cndmask_b32_e64 v61, 0, 1, s[44:45]
	v_cndmask_b32_e64 v60, v61, v60, s[40:41]
	v_and_b32_e32 v60, 1, v60
	v_cmp_eq_u32_e64 s[44:45], 1, v60
	v_sub_f32_e32 v60, v180, v54
	v_mul_f32_e32 v60, 0x3fb8aa3b, v60
	v_exp_f32_e32 v60, v60
	v_cvt_pk_bf16_f32 v6, v8, v9
	v_mul_f32_e32 v10, v10, v60
	v_cndmask_b32_e64 v10, 0, v10, s[44:45]
	v_cmp_ge_i32_e64 s[44:45], v218, v186
	v_cndmask_b32_e64 v60, 0, 1, s[46:47]
	v_cmp_le_i32_e64 s[46:47], v217, v186
	v_cndmask_b32_e64 v61, 0, 1, s[44:45]
	v_cndmask_b32_e64 v60, v61, v60, s[40:41]
	v_and_b32_e32 v60, 1, v60
	v_cmp_eq_u32_e64 s[44:45], 1, v60
	v_sub_f32_e32 v60, v180, v55
	v_mul_f32_e32 v60, 0x3fb8aa3b, v60
	v_exp_f32_e32 v60, v60
	v_cndmask_b32_e64 v64, 0, 1, s[46:47]
	v_cmp_le_i32_e64 s[46:47], v216, v186
	v_mul_f32_e32 v11, v11, v60
	ds_read_b128 v[60:63], v226 offset:17472
	v_cndmask_b32_e64 v11, 0, v11, s[44:45]
	v_cmp_ge_i32_e64 s[44:45], v217, v186
	v_cvt_pk_bf16_f32 v7, v10, v11
	s_nop 0
	v_cndmask_b32_e64 v65, 0, 1, s[44:45]
	v_cndmask_b32_e64 v64, v65, v64, s[40:41]
	v_and_b32_e32 v64, 1, v64
	v_cmp_eq_u32_e64 s[44:45], 1, v64
	s_waitcnt lgkmcnt(0)
; __device__ __forceinline__ unsigned pk2(float lo, float hi) { const f32x2_cv v = {lo, hi}; const bf16x2_cv b = __builtin_convertvector(v, bf16x2_cv); return __builtin_bit_cast(unsigned, b); }
; __device__ __forceinline__ int crow16(int r, int hi) { return (r & 3) + 8 * (r >> 2) + 4 * hi; }
; __device__ __forceinline__ void dk_phase(const Frame& F, const bf16* QKrm, const unsigned char* KT, const unsigned char* VT, const float* BG, unsigned char* ITEMS) {
;     ...
;             for (int ri = 0; ri < 2; ++ri) { const int r = 32 * ri + r32; const float gr = gamL[r];
; #pragma unroll
;                 for (int si = 0; si < 2; ++si) { f32x16_t p = f32x16_t{};
; #pragma unroll
;                     for (int ks = 0; ks < 8; ++ks) p = __builtin_amdgcn_mfma_f32_32x32x16_bf16(Kn[si][ks], Qn[ri][ks], p, 0, 0, 0);
;                     float pv[16];
; #pragma unroll
;                     for (int rg = 0; rg < 16; ++rg) { const int s = 32 * si + crow16(rg, hi); const float gs = gamL[s];
;                         const bool ok = dir ? (s >= r) : (s <= r);
;                         pv[rg] = ok ? p[rg] * __expf(gr - gs) : 0.f; }
; #pragma unroll
;                     for (int st = 0; st < 2; ++st) { v4u wv; wv.x = pk2(pv[8 * st + 0], pv[8 * st + 1]); wv.y = pk2(pv[8 * st + 2], pv[8 * st + 3]); wv.z = pk2(pv[8 * st + 4], pv[8 * st + 5]); wv.w = pk2(pv[8 * st + 6], pv[8 * st + 7]);
;                         *(v4u*)(item + ITEM_AQK + ((ri * 2 + si) * 2 + st) * 1024 + lane * 16) = wv; } } }
	v_sub_f32_e32 v64, v180, v60
	v_mul_f32_e32 v64, 0x3fb8aa3b, v64
	v_exp_f32_e32 v64, v64
	s_nop 0
	v_mul_f32_e32 v12, v12, v64
	v_cndmask_b32_e64 v12, 0, v12, s[44:45]
	v_cmp_ge_i32_e64 s[44:45], v216, v186
	v_cndmask_b32_e64 v64, 0, 1, s[46:47]
	v_cmp_le_i32_e64 s[46:47], v215, v186
	v_cndmask_b32_e64 v65, 0, 1, s[44:45]
	v_cndmask_b32_e64 v64, v65, v64, s[40:41]
	v_and_b32_e32 v64, 1, v64
	v_cmp_eq_u32_e64 s[44:45], 1, v64
	v_sub_f32_e32 v64, v180, v61
	v_mul_f32_e32 v64, 0x3fb8aa3b, v64
	v_exp_f32_e32 v64, v64
	s_nop 0
	v_mul_f32_e32 v13, v13, v64
	v_cndmask_b32_e64 v13, 0, v13, s[44:45]
	v_cmp_ge_i32_e64 s[44:45], v215, v186
	v_cndmask_b32_e64 v64, 0, 1, s[46:47]
	v_cmp_le_i32_e64 s[46:47], v214, v186
	v_cndmask_b32_e64 v65, 0, 1, s[44:45]
	v_cndmask_b32_e64 v64, v65, v64, s[40:41]
	v_and_b32_e32 v64, 1, v64
	v_cmp_eq_u32_e64 s[44:45], 1, v64
	v_sub_f32_e32 v64, v180, v62
	v_mul_f32_e32 v64, 0x3fb8aa3b, v64
	v_exp_f32_e32 v64, v64
	s_nop 0
	v_mul_f32_e32 v14, v14, v64
	v_cndmask_b32_e64 v14, 0, v14, s[44:45]
	v_cmp_ge_i32_e64 s[44:45], v214, v186
	v_cndmask_b32_e64 v64, 0, 1, s[46:47]
	v_cmp_le_i32_e64 s[46:47], v213, v186
	v_cndmask_b32_e64 v65, 0, 1, s[44:45]
	v_cndmask_b32_e64 v64, v65, v64, s[40:41]
	v_and_b32_e32 v64, 1, v64
	v_cmp_eq_u32_e64 s[44:45], 1, v64
	v_sub_f32_e32 v64, v180, v63
	v_mul_f32_e32 v64, 0x3fb8aa3b, v64
	v_exp_f32_e32 v64, v64
	v_cndmask_b32_e64 v170, 0, 1, s[46:47]
	v_cmp_le_i32_e64 s[46:47], v203, v186
	v_mul_f32_e32 v15, v15, v64
	ds_read_b128 v[64:67], v226 offset:17504
	v_cndmask_b32_e64 v15, 0, v15, s[44:45]
	v_cmp_ge_i32_e64 s[44:45], v213, v186
	s_nop 1
	v_cndmask_b32_e64 v171, 0, 1, s[44:45]
	v_cndmask_b32_e64 v170, v171, v170, s[40:41]
	v_and_b32_e32 v170, 1, v170
	v_cmp_eq_u32_e64 s[44:45], 1, v170
	s_waitcnt lgkmcnt(0)
	v_sub_f32_e32 v170, v180, v64
	v_mul_f32_e32 v170, 0x3fb8aa3b, v170
	v_exp_f32_e32 v170, v170
	s_nop 0
	v_mul_f32_e32 v16, v16, v170
	v_cndmask_b32_e64 v16, 0, v16, s[44:45]
	v_cmp_ge_i32_e64 s[44:45], v203, v186
	v_cndmask_b32_e64 v170, 0, 1, s[46:47]
	v_cmp_le_i32_e64 s[46:47], v211, v186
	v_cndmask_b32_e64 v171, 0, 1, s[44:45]
	v_cndmask_b32_e64 v170, v171, v170, s[40:41]
	v_and_b32_e32 v170, 1, v170
	v_cmp_eq_u32_e64 s[44:45], 1, v170
	v_sub_f32_e32 v170, v180, v65
	v_mul_f32_e32 v170, 0x3fb8aa3b, v170
	v_exp_f32_e32 v170, v170
	s_nop 0
	v_mul_f32_e32 v17, v17, v170
	v_cndmask_b32_e64 v17, 0, v17, s[44:45]
	v_cmp_ge_i32_e64 s[44:45], v211, v186
	v_cndmask_b32_e64 v170, 0, 1, s[46:47]
	v_cmp_le_i32_e64 s[46:47], v212, v186
	v_cndmask_b32_e64 v171, 0, 1, s[44:45]
	v_cndmask_b32_e64 v170, v171, v170, s[40:41]
	v_and_b32_e32 v170, 1, v170
	v_cmp_eq_u32_e64 s[44:45], 1, v170
	v_sub_f32_e32 v170, v180, v66
	v_mul_f32_e32 v170, 0x3fb8aa3b, v170
	v_exp_f32_e32 v170, v170
	s_nop 0
	v_mul_f32_e32 v18, v18, v170
	v_cndmask_b32_e64 v18, 0, v18, s[44:45]
	v_cmp_ge_i32_e64 s[44:45], v212, v186
	v_cndmask_b32_e64 v170, 0, 1, s[46:47]
	v_cmp_le_i32_e64 s[46:47], v227, v186
	v_cndmask_b32_e64 v171, 0, 1, s[44:45]
	v_cndmask_b32_e64 v170, v171, v170, s[40:41]
	v_and_b32_e32 v170, 1, v170
	v_cmp_eq_u32_e64 s[44:45], 1, v170
	v_sub_f32_e32 v170, v180, v67
	v_mul_f32_e32 v170, 0x3fb8aa3b, v170
	v_exp_f32_e32 v170, v170
	s_nop 0
	v_mul_f32_e32 v19, v19, v170
	v_cndmask_b32_e64 v19, 0, v19, s[44:45]
	v_add_co_u32_e64 v170, s[44:45], s21, v166
	s_movk_i32 s21, 0xb000
	s_nop 0
	v_addc_co_u32_e64 v171, s[44:45], -1, v167, s[44:45]
	v_add_co_u32_e64 v182, s[44:45], s21, v166
	global_store_dwordx4 v[170:171], v[4:7], off offset:-512
	s_nop 0
	v_addc_co_u32_e64 v183, s[44:45], -1, v167, s[44:45]
	v_cvt_pk_bf16_f32 v4, v12, v13
	v_cvt_pk_bf16_f32 v5, v14, v15
	v_cvt_pk_bf16_f32 v6, v16, v17
	v_cvt_pk_bf16_f32 v7, v18, v19
	global_store_dwordx4 v[182:183], v[4:7], off offset:-3584
	v_cmp_ge_i32_e64 s[44:45], v227, v186
	s_nop 0
	v_mfma_f32_32x32x16_bf16 v[4:19], v[96:99], v[160:163], 0
	v_mfma_f32_32x32x16_bf16 v[4:19], v[88:91], v[156:159], v[4:19]
	v_mfma_f32_32x32x16_bf16 v[4:19], v[92:95], v[152:155], v[4:19]
	v_mfma_f32_32x32x16_bf16 v[4:19], v[84:87], v[148:151], v[4:19]
	v_mfma_f32_32x32x16_bf16 v[4:19], v[80:83], v[144:147], v[4:19]
	v_mfma_f32_32x32x16_bf16 v[4:19], v[76:79], v[140:143], v[4:19]
	v_cndmask_b32_e64 v140, 0, 1, s[46:47]
	v_cndmask_b32_e64 v141, 0, 1, s[44:45]
	v_cndmask_b32_e64 v140, v141, v140, s[40:41]
	v_and_b32_e32 v140, 1, v140
	v_cmp_eq_u32_e64 s[44:45], 1, v140
	v_cmp_lt_i32_e64 s[46:47], v227, v186
	v_mfma_f32_32x32x16_bf16 v[4:19], v[68:71], v[132:135], v[4:19]
	v_mfma_f32_32x32x16_bf16 v[4:19], v[72:75], v[136:139], v[4:19]
	ds_read_b128 v[136:139], v226 offset:17536
	ds_read_b128 v[132:135], v226 offset:17568
	s_waitcnt lgkmcnt(1)
	v_sub_f32_e32 v140, v180, v136
	v_mul_f32_e32 v140, 0x3fb8aa3b, v140
	v_exp_f32_e32 v140, v140
	s_nop 5
	v_mul_f32_e32 v4, v4, v140
	v_cndmask_b32_e64 v4, 0, v4, s[44:45]
	v_cmp_ge_i32_e64 s[44:45], v202, v186
	v_cndmask_b32_e64 v140, 0, 1, s[46:47]
	v_cmp_le_i32_e64 s[46:47], v201, v186
	v_cndmask_b32_e64 v141, 0, 1, s[44:45]
	v_cndmask_b32_e64 v140, v141, v140, s[40:41]
	v_and_b32_e32 v140, 1, v140
	v_cmp_eq_u32_e64 s[44:45], 1, v140
	v_sub_f32_e32 v140, v180, v137
	v_mul_f32_e32 v140, 0x3fb8aa3b, v140
	v_exp_f32_e32 v140, v140
	s_nop 0
	v_mul_f32_e32 v5, v5, v140
	v_cndmask_b32_e64 v5, 0, v5, s[44:45]
	v_cmp_ge_i32_e64 s[44:45], v201, v186
	v_cndmask_b32_e64 v140, 0, 1, s[46:47]
	v_cmp_le_i32_e64 s[46:47], v200, v186
	v_cndmask_b32_e64 v141, 0, 1, s[44:45]
	v_cndmask_b32_e64 v140, v141, v140, s[40:41]
	v_and_b32_e32 v140, 1, v140
	v_cmp_eq_u32_e64 s[44:45], 1, v140
	v_sub_f32_e32 v140, v180, v138
	v_mul_f32_e32 v140, 0x3fb8aa3b, v140
	v_exp_f32_e32 v140, v140
	v_cvt_pk_bf16_f32 v4, v4, v5
	v_mul_f32_e32 v6, v6, v140
	v_cndmask_b32_e64 v6, 0, v6, s[44:45]
	v_cmp_ge_i32_e64 s[44:45], v200, v186
	v_cndmask_b32_e64 v140, 0, 1, s[46:47]
	v_cmp_le_i32_e64 s[46:47], v199, v186
	v_cndmask_b32_e64 v141, 0, 1, s[44:45]
	v_cndmask_b32_e64 v140, v141, v140, s[40:41]
	v_and_b32_e32 v140, 1, v140
	v_cmp_eq_u32_e64 s[44:45], 1, v140
	v_sub_f32_e32 v140, v180, v139
	v_mul_f32_e32 v140, 0x3fb8aa3b, v140
	v_exp_f32_e32 v140, v140
	s_nop 0
	v_mul_f32_e32 v7, v7, v140
	v_cndmask_b32_e64 v7, 0, v7, s[44:45]
	v_cmp_ge_i32_e64 s[44:45], v199, v186
	v_cndmask_b32_e64 v140, 0, 1, s[46:47]
	v_cmp_le_i32_e64 s[46:47], v198, v186
	v_cndmask_b32_e64 v141, 0, 1, s[44:45]
	v_cndmask_b32_e64 v140, v141, v140, s[40:41]
	v_and_b32_e32 v140, 1, v140
	v_cmp_eq_u32_e64 s[44:45], 1, v140
	s_waitcnt lgkmcnt(0)
; __device__ __forceinline__ unsigned pk2(float lo, float hi) { const f32x2_cv v = {lo, hi}; const bf16x2_cv b = __builtin_convertvector(v, bf16x2_cv); return __builtin_bit_cast(unsigned, b); }
; __device__ __forceinline__ int crow16(int r, int hi) { return (r & 3) + 8 * (r >> 2) + 4 * hi; }
; __device__ __forceinline__ void dk_phase(const Frame& F, const bf16* QKrm, const unsigned char* KT, const unsigned char* VT, const float* BG, unsigned char* ITEMS) {
;     ...
;             for (int ri = 0; ri < 2; ++ri) { const int r = 32 * ri + r32; const float gr = gamL[r];
; #pragma unroll
;                 for (int si = 0; si < 2; ++si) { f32x16_t p = f32x16_t{};
; #pragma unroll
;                     for (int ks = 0; ks < 8; ++ks) p = __builtin_amdgcn_mfma_f32_32x32x16_bf16(Kn[si][ks], Qn[ri][ks], p, 0, 0, 0);
;                     float pv[16];
; #pragma unroll
;                     for (int rg = 0; rg < 16; ++rg) { const int s = 32 * si + crow16(rg, hi); const float gs = gamL[s];
;                         const bool ok = dir ? (s >= r) : (s <= r);
;                         pv[rg] = ok ? p[rg] * __expf(gr - gs) : 0.f; }
; #pragma unroll
;                     for (int st = 0; st < 2; ++st) { v4u wv; wv.x = pk2(pv[8 * st + 0], pv[8 * st + 1]); wv.y = pk2(pv[8 * st + 2], pv[8 * st + 3]); wv.z = pk2(pv[8 * st + 4], pv[8 * st + 5]); wv.w = pk2(pv[8 * st + 6], pv[8 * st + 7]);
;                         *(v4u*)(item + ITEM_AQK + ((ri * 2 + si) * 2 + st) * 1024 + lane * 16) = wv; } } }
	v_sub_f32_e32 v140, v180, v132
	v_mul_f32_e32 v140, 0x3fb8aa3b, v140
	v_exp_f32_e32 v140, v140
	v_cvt_pk_bf16_f32 v5, v6, v7
	v_mul_f32_e32 v8, v8, v140
	v_cndmask_b32_e64 v8, 0, v8, s[44:45]
	v_cmp_ge_i32_e64 s[44:45], v198, v186
	v_cndmask_b32_e64 v140, 0, 1, s[46:47]
	v_cmp_le_i32_e64 s[46:47], v197, v186
	v_cndmask_b32_e64 v141, 0, 1, s[44:45]
	v_cndmask_b32_e64 v140, v141, v140, s[40:41]
	v_and_b32_e32 v140, 1, v140
	v_cmp_eq_u32_e64 s[44:45], 1, v140
	v_sub_f32_e32 v140, v180, v133
	v_mul_f32_e32 v140, 0x3fb8aa3b, v140
	v_exp_f32_e32 v140, v140
	s_nop 0
	v_mul_f32_e32 v9, v9, v140
	v_cndmask_b32_e64 v9, 0, v9, s[44:45]
	v_cmp_ge_i32_e64 s[44:45], v197, v186
	v_cndmask_b32_e64 v140, 0, 1, s[46:47]
	v_cmp_le_i32_e64 s[46:47], v196, v186
	v_cndmask_b32_e64 v141, 0, 1, s[44:45]
	v_cndmask_b32_e64 v140, v141, v140, s[40:41]
	v_and_b32_e32 v140, 1, v140
	v_cmp_eq_u32_e64 s[44:45], 1, v140
	v_sub_f32_e32 v140, v180, v134
	v_mul_f32_e32 v140, 0x3fb8aa3b, v140
	v_exp_f32_e32 v140, v140
	v_cvt_pk_bf16_f32 v6, v8, v9
	v_mul_f32_e32 v10, v10, v140
	v_cndmask_b32_e64 v10, 0, v10, s[44:45]
	v_cmp_ge_i32_e64 s[44:45], v196, v186
	v_cndmask_b32_e64 v140, 0, 1, s[46:47]
	v_cmp_le_i32_e64 s[46:47], v195, v186
	v_cndmask_b32_e64 v141, 0, 1, s[44:45]
	v_cndmask_b32_e64 v140, v141, v140, s[40:41]
	v_and_b32_e32 v140, 1, v140
	v_cmp_eq_u32_e64 s[44:45], 1, v140
	v_sub_f32_e32 v140, v180, v135
	v_mul_f32_e32 v140, 0x3fb8aa3b, v140
	v_exp_f32_e32 v140, v140
	v_cndmask_b32_e64 v144, 0, 1, s[46:47]
	v_cmp_le_i32_e64 s[46:47], v194, v186
	v_mul_f32_e32 v11, v11, v140
	ds_read_b128 v[140:143], v226 offset:17600
	v_cndmask_b32_e64 v11, 0, v11, s[44:45]
	v_cmp_ge_i32_e64 s[44:45], v195, v186
	v_cvt_pk_bf16_f32 v7, v10, v11
	global_store_dwordx4 v[182:183], v[4:7], off offset:-2560
	v_cndmask_b32_e64 v145, 0, 1, s[44:45]
	v_cndmask_b32_e64 v144, v145, v144, s[40:41]
	v_and_b32_e32 v144, 1, v144
	v_cmp_eq_u32_e64 s[44:45], 1, v144
	s_waitcnt lgkmcnt(0)
	v_sub_f32_e32 v144, v180, v140
	v_mul_f32_e32 v144, 0x3fb8aa3b, v144
	v_exp_f32_e32 v144, v144
	s_nop 0
	v_mul_f32_e32 v12, v12, v144
	v_cndmask_b32_e64 v12, 0, v12, s[44:45]
	v_cmp_ge_i32_e64 s[44:45], v194, v186
	v_cndmask_b32_e64 v144, 0, 1, s[46:47]
	v_cmp_le_i32_e64 s[46:47], v193, v186
	v_cndmask_b32_e64 v145, 0, 1, s[44:45]
	v_cndmask_b32_e64 v144, v145, v144, s[40:41]
	v_and_b32_e32 v144, 1, v144
	v_cmp_eq_u32_e64 s[44:45], 1, v144
	v_sub_f32_e32 v144, v180, v141
	v_mul_f32_e32 v144, 0x3fb8aa3b, v144
	v_exp_f32_e32 v144, v144
	s_nop 0
	v_mul_f32_e32 v13, v13, v144
	v_cndmask_b32_e64 v13, 0, v13, s[44:45]
	v_cmp_ge_i32_e64 s[44:45], v193, v186
	v_cndmask_b32_e64 v144, 0, 1, s[46:47]
	v_cmp_le_i32_e64 s[46:47], v192, v186
	v_cndmask_b32_e64 v145, 0, 1, s[44:45]
	v_cndmask_b32_e64 v144, v145, v144, s[40:41]
	v_and_b32_e32 v144, 1, v144
	v_cmp_eq_u32_e64 s[44:45], 1, v144
	v_sub_f32_e32 v144, v180, v142
	v_mul_f32_e32 v144, 0x3fb8aa3b, v144
	v_exp_f32_e32 v144, v144
	v_cvt_pk_bf16_f32 v4, v12, v13
	v_mul_f32_e32 v14, v14, v144
	v_cndmask_b32_e64 v14, 0, v14, s[44:45]
	v_cmp_ge_i32_e64 s[44:45], v192, v186
	v_cndmask_b32_e64 v144, 0, 1, s[46:47]
	v_cmp_le_i32_e64 s[46:47], v191, v186
	v_cndmask_b32_e64 v145, 0, 1, s[44:45]
	v_cndmask_b32_e64 v144, v145, v144, s[40:41]
	v_and_b32_e32 v144, 1, v144
	v_cmp_eq_u32_e64 s[44:45], 1, v144
	v_sub_f32_e32 v144, v180, v143
	v_mul_f32_e32 v144, 0x3fb8aa3b, v144
	v_exp_f32_e32 v144, v144
	v_cndmask_b32_e64 v148, 0, 1, s[46:47]
	v_cmp_le_i32_e64 s[46:47], v190, v186
	v_mul_f32_e32 v15, v15, v144
	ds_read_b128 v[144:147], v226 offset:17632
	v_cndmask_b32_e64 v15, 0, v15, s[44:45]
	v_cmp_ge_i32_e64 s[44:45], v191, v186
	v_cvt_pk_bf16_f32 v5, v14, v15
	s_nop 0
	v_cndmask_b32_e64 v149, 0, 1, s[44:45]
	v_cndmask_b32_e64 v148, v149, v148, s[40:41]
	v_and_b32_e32 v148, 1, v148
	v_cmp_eq_u32_e64 s[44:45], 1, v148
	s_waitcnt lgkmcnt(0)
	v_sub_f32_e32 v148, v180, v144
	v_mul_f32_e32 v148, 0x3fb8aa3b, v148
	v_exp_f32_e32 v148, v148
	s_nop 0
	v_mul_f32_e32 v16, v16, v148
	v_cndmask_b32_e64 v16, 0, v16, s[44:45]
	v_cmp_ge_i32_e64 s[44:45], v190, v186
	v_cndmask_b32_e64 v148, 0, 1, s[46:47]
	v_cmp_le_i32_e64 s[46:47], v189, v186
	v_cndmask_b32_e64 v149, 0, 1, s[44:45]
	v_cndmask_b32_e64 v148, v149, v148, s[40:41]
	v_and_b32_e32 v148, 1, v148
	v_cmp_eq_u32_e64 s[44:45], 1, v148
	v_sub_f32_e32 v148, v180, v145
	v_mul_f32_e32 v148, 0x3fb8aa3b, v148
	v_exp_f32_e32 v148, v148
	s_nop 0
	v_mul_f32_e32 v17, v17, v148
	v_cndmask_b32_e64 v17, 0, v17, s[44:45]
	v_cmp_ge_i32_e64 s[44:45], v189, v186
	v_cndmask_b32_e64 v148, 0, 1, s[46:47]
	v_cmp_le_i32_e64 s[46:47], v188, v186
	v_cndmask_b32_e64 v149, 0, 1, s[44:45]
	v_cndmask_b32_e64 v148, v149, v148, s[40:41]
	v_and_b32_e32 v148, 1, v148
	v_cmp_eq_u32_e64 s[44:45], 1, v148
	v_sub_f32_e32 v148, v180, v146
	v_mul_f32_e32 v148, 0x3fb8aa3b, v148
	v_exp_f32_e32 v148, v148
	v_cvt_pk_bf16_f32 v6, v16, v17
	v_mul_f32_e32 v18, v18, v148
	v_cndmask_b32_e64 v18, 0, v18, s[44:45]
	v_cmp_ge_i32_e64 s[44:45], v188, v186
	v_cndmask_b32_e64 v148, 0, 1, s[46:47]
	v_cmp_le_i32_e64 s[46:47], v223, v187
	v_cndmask_b32_e64 v149, 0, 1, s[44:45]
	v_cndmask_b32_e64 v148, v149, v148, s[40:41]
	v_and_b32_e32 v148, 1, v148
	v_cmp_eq_u32_e64 s[44:45], 1, v148
	v_sub_f32_e32 v148, v180, v147
	v_mul_f32_e32 v148, 0x3fb8aa3b, v148
	v_exp_f32_e32 v148, v148
	s_nop 0
	v_mul_f32_e32 v19, v19, v148
	v_cndmask_b32_e64 v19, 0, v19, s[44:45]
	v_cvt_pk_bf16_f32 v7, v18, v19
	global_store_dwordx4 v[182:183], v[4:7], off offset:-1536
	v_cmp_ge_i32_e64 s[44:45], v223, v187
	s_waitcnt vmcnt(11)
	v_mfma_f32_32x32x16_bf16 v[4:19], v[124:127], v[48:51], 0
	s_waitcnt vmcnt(10)
; __device__ __forceinline__ unsigned pk2(float lo, float hi) { const f32x2_cv v = {lo, hi}; const bf16x2_cv b = __builtin_convertvector(v, bf16x2_cv); return __builtin_bit_cast(unsigned, b); }
; __device__ __forceinline__ int crow16(int r, int hi) { return (r & 3) + 8 * (r >> 2) + 4 * hi; }
; __device__ __forceinline__ void dk_phase(const Frame& F, const bf16* QKrm, const unsigned char* KT, const unsigned char* VT, const float* BG, unsigned char* ITEMS) {
;     ...
;             for (int ri = 0; ri < 2; ++ri) { const int r = 32 * ri + r32; const float gr = gamL[r];
; #pragma unroll
;                 for (int si = 0; si < 2; ++si) { f32x16_t p = f32x16_t{};
; #pragma unroll
;                     for (int ks = 0; ks < 8; ++ks) p = __builtin_amdgcn_mfma_f32_32x32x16_bf16(Kn[si][ks], Qn[ri][ks], p, 0, 0, 0);
;                     float pv[16];
; #pragma unroll
;                     for (int rg = 0; rg < 16; ++rg) { const int s = 32 * si + crow16(rg, hi); const float gs = gamL[s];
;                         const bool ok = dir ? (s >= r) : (s <= r);
;                         pv[rg] = ok ? p[rg] * __expf(gr - gs) : 0.f; }
; #pragma unroll
;                     for (int st = 0; st < 2; ++st) { v4u wv; wv.x = pk2(pv[8 * st + 0], pv[8 * st + 1]); wv.y = pk2(pv[8 * st + 2], pv[8 * st + 3]); wv.z = pk2(pv[8 * st + 4], pv[8 * st + 5]); wv.w = pk2(pv[8 * st + 6], pv[8 * st + 7]);
;                         *(v4u*)(item + ITEM_AQK + ((ri * 2 + si) * 2 + st) * 1024 + lane * 16) = wv; } } }
	v_mfma_f32_32x32x16_bf16 v[4:19], v[120:123], v[44:47], v[4:19]
	s_waitcnt vmcnt(9)
	v_mfma_f32_32x32x16_bf16 v[4:19], v[128:131], v[40:43], v[4:19]
	s_waitcnt vmcnt(8)
	v_mfma_f32_32x32x16_bf16 v[4:19], v[116:119], v[36:39], v[4:19]
	s_waitcnt vmcnt(7)
	v_mfma_f32_32x32x16_bf16 v[4:19], v[112:115], v[32:35], v[4:19]
	s_waitcnt vmcnt(6)
	v_mfma_f32_32x32x16_bf16 v[4:19], v[108:111], v[28:31], v[4:19]
	s_waitcnt vmcnt(5)
	v_mfma_f32_32x32x16_bf16 v[4:19], v[104:107], v[20:23], v[4:19]
	s_waitcnt vmcnt(4)
	v_mfma_f32_32x32x16_bf16 v[4:19], v[100:103], v[24:27], v[4:19]
	v_cndmask_b32_e64 v100, 0, 1, s[46:47]
	v_cndmask_b32_e64 v101, 0, 1, s[44:45]
	v_cndmask_b32_e64 v100, v101, v100, s[40:41]
	v_and_b32_e32 v100, 1, v100
	v_cmp_eq_u32_e64 s[44:45], 1, v100
	v_cmp_lt_i32_e64 s[46:47], v223, v187
	s_nop 5
	v_mul_f32_e32 v4, v56, v4
	v_cndmask_b32_e64 v4, 0, v4, s[44:45]
	v_cmp_ge_i32_e64 s[44:45], v225, v187
	v_cndmask_b32_e64 v56, 0, 1, s[46:47]
	v_cmp_le_i32_e64 s[46:47], v224, v187
	v_cndmask_b32_e64 v100, 0, 1, s[44:45]
	v_cndmask_b32_e64 v56, v100, v56, s[40:41]
	v_and_b32_e32 v56, 1, v56
	v_cmp_eq_u32_e64 s[44:45], 1, v56
	v_sub_f32_e32 v56, v181, v57
	v_mul_f32_e32 v56, 0x3fb8aa3b, v56
	v_exp_f32_e32 v56, v56
	v_mul_f32_e32 v8, v52, v8
	v_mul_f32_e32 v5, v56, v5
	v_cndmask_b32_e64 v5, 0, v5, s[44:45]
	v_cmp_ge_i32_e64 s[44:45], v224, v187
	v_cndmask_b32_e64 v56, 0, 1, s[46:47]
	v_cmp_le_i32_e64 s[46:47], v222, v187
	v_cndmask_b32_e64 v57, 0, 1, s[44:45]
	v_cndmask_b32_e64 v56, v57, v56, s[40:41]
	v_and_b32_e32 v56, 1, v56
	v_cmp_eq_u32_e64 s[44:45], 1, v56
	v_sub_f32_e32 v56, v181, v58
	v_mul_f32_e32 v56, 0x3fb8aa3b, v56
	v_exp_f32_e32 v56, v56
	v_cvt_pk_bf16_f32 v4, v4, v5
	v_mul_f32_e32 v6, v56, v6
	v_cndmask_b32_e64 v6, 0, v6, s[44:45]
	v_cmp_ge_i32_e64 s[44:45], v222, v187
	v_cndmask_b32_e64 v56, 0, 1, s[46:47]
	v_cmp_le_i32_e64 s[46:47], v221, v187
	v_cndmask_b32_e64 v57, 0, 1, s[44:45]
	v_cndmask_b32_e64 v56, v57, v56, s[40:41]
	v_and_b32_e32 v56, 1, v56
	v_cmp_eq_u32_e64 s[44:45], 1, v56
	v_sub_f32_e32 v56, v181, v59
	v_mul_f32_e32 v56, 0x3fb8aa3b, v56
	v_exp_f32_e32 v56, v56
	s_nop 0
	v_mul_f32_e32 v7, v56, v7
	v_cndmask_b32_e64 v7, 0, v7, s[44:45]
	v_cmp_ge_i32_e64 s[44:45], v221, v187
	v_cndmask_b32_e64 v56, 0, 1, s[46:47]
	v_cmp_le_i32_e64 s[46:47], v220, v187
	v_cndmask_b32_e64 v57, 0, 1, s[44:45]
	v_cndmask_b32_e64 v56, v57, v56, s[40:41]
	v_and_b32_e32 v56, 1, v56
	v_cmp_eq_u32_e64 s[44:45], 1, v56
	v_cndmask_b32_e64 v52, 0, 1, s[46:47]
	v_cmp_le_i32_e64 s[46:47], v219, v187
	v_cndmask_b32_e64 v8, 0, v8, s[44:45]
	v_cmp_ge_i32_e64 s[44:45], v220, v187
	v_cvt_pk_bf16_f32 v5, v6, v7
	s_nop 0
	v_cndmask_b32_e64 v56, 0, 1, s[44:45]
	v_cndmask_b32_e64 v52, v56, v52, s[40:41]
	v_and_b32_e32 v52, 1, v52
	v_cmp_eq_u32_e64 s[44:45], 1, v52
	v_sub_f32_e32 v52, v181, v53
	v_mul_f32_e32 v52, 0x3fb8aa3b, v52
	v_exp_f32_e32 v52, v52
	s_nop 0
	v_mul_f32_e32 v9, v52, v9
	v_cndmask_b32_e64 v9, 0, v9, s[44:45]
	v_cmp_ge_i32_e64 s[44:45], v219, v187
	v_cndmask_b32_e64 v52, 0, 1, s[46:47]
	v_cmp_le_i32_e64 s[46:47], v218, v187
	v_cndmask_b32_e64 v53, 0, 1, s[44:45]
	v_cndmask_b32_e64 v52, v53, v52, s[40:41]
	v_and_b32_e32 v52, 1, v52
	v_cmp_eq_u32_e64 s[44:45], 1, v52
	v_sub_f32_e32 v52, v181, v54
	v_mul_f32_e32 v52, 0x3fb8aa3b, v52
	v_exp_f32_e32 v52, v52
	v_cvt_pk_bf16_f32 v6, v8, v9
	v_mul_f32_e32 v10, v52, v10
	v_cndmask_b32_e64 v10, 0, v10, s[44:45]
	v_cmp_ge_i32_e64 s[44:45], v218, v187
	v_cndmask_b32_e64 v52, 0, 1, s[46:47]
	v_cmp_le_i32_e64 s[46:47], v217, v187
	v_cndmask_b32_e64 v53, 0, 1, s[44:45]
	v_cndmask_b32_e64 v52, v53, v52, s[40:41]
	v_and_b32_e32 v52, 1, v52
	v_cmp_eq_u32_e64 s[44:45], 1, v52
	v_sub_f32_e32 v52, v181, v55
	v_mul_f32_e32 v52, 0x3fb8aa3b, v52
	v_exp_f32_e32 v52, v52
	s_nop 0
	v_mul_f32_e32 v11, v52, v11
	v_cndmask_b32_e64 v11, 0, v11, s[44:45]
	v_cmp_ge_i32_e64 s[44:45], v217, v187
	v_cndmask_b32_e64 v52, 0, 1, s[46:47]
	v_cmp_le_i32_e64 s[46:47], v216, v187
	v_cndmask_b32_e64 v53, 0, 1, s[44:45]
	v_cndmask_b32_e64 v52, v53, v52, s[40:41]
	v_and_b32_e32 v52, 1, v52
	v_cmp_eq_u32_e64 s[44:45], 1, v52
	v_sub_f32_e32 v52, v181, v60
	v_mul_f32_e32 v52, 0x3fb8aa3b, v52
	v_exp_f32_e32 v52, v52
	v_cvt_pk_bf16_f32 v7, v10, v11
	global_store_dwordx4 v[182:183], v[4:7], off offset:-512
	v_mul_f32_e32 v12, v52, v12
	v_cndmask_b32_e64 v12, 0, v12, s[44:45]
	v_cmp_ge_i32_e64 s[44:45], v216, v187
	v_cndmask_b32_e64 v52, 0, 1, s[46:47]
	v_cmp_le_i32_e64 s[46:47], v215, v187
	v_cndmask_b32_e64 v53, 0, 1, s[44:45]
	v_cndmask_b32_e64 v52, v53, v52, s[40:41]
	v_and_b32_e32 v52, 1, v52
	v_cmp_eq_u32_e64 s[44:45], 1, v52
	v_sub_f32_e32 v52, v181, v61
	v_mul_f32_e32 v52, 0x3fb8aa3b, v52
	v_exp_f32_e32 v52, v52
	s_nop 0
	v_mul_f32_e32 v13, v52, v13
	v_cndmask_b32_e64 v13, 0, v13, s[44:45]
	v_cmp_ge_i32_e64 s[44:45], v215, v187
	v_cndmask_b32_e64 v52, 0, 1, s[46:47]
	v_cmp_le_i32_e64 s[46:47], v214, v187
	v_cndmask_b32_e64 v53, 0, 1, s[44:45]
	v_cndmask_b32_e64 v52, v53, v52, s[40:41]
	v_and_b32_e32 v52, 1, v52
	v_cmp_eq_u32_e64 s[44:45], 1, v52
	v_sub_f32_e32 v52, v181, v62
	v_mul_f32_e32 v52, 0x3fb8aa3b, v52
	v_exp_f32_e32 v52, v52
	v_cvt_pk_bf16_f32 v4, v12, v13
	v_mul_f32_e32 v14, v52, v14
	v_cndmask_b32_e64 v14, 0, v14, s[44:45]
	v_cmp_ge_i32_e64 s[44:45], v214, v187
	v_cndmask_b32_e64 v52, 0, 1, s[46:47]
	v_cmp_le_i32_e64 s[46:47], v213, v187
	v_cndmask_b32_e64 v53, 0, 1, s[44:45]
	v_cndmask_b32_e64 v52, v53, v52, s[40:41]
	v_and_b32_e32 v52, 1, v52
	v_cmp_eq_u32_e64 s[44:45], 1, v52
	v_sub_f32_e32 v52, v181, v63
	v_mul_f32_e32 v52, 0x3fb8aa3b, v52
	v_exp_f32_e32 v52, v52
	s_nop 0
	v_mul_f32_e32 v15, v52, v15
; __device__ __forceinline__ unsigned pk2(float lo, float hi) { const f32x2_cv v = {lo, hi}; const bf16x2_cv b = __builtin_convertvector(v, bf16x2_cv); return __builtin_bit_cast(unsigned, b); }
; __device__ __forceinline__ int crow16(int r, int hi) { return (r & 3) + 8 * (r >> 2) + 4 * hi; }
; __device__ __forceinline__ void dk_phase(const Frame& F, const bf16* QKrm, const unsigned char* KT, const unsigned char* VT, const float* BG, unsigned char* ITEMS) {
;     ...
;             for (int ri = 0; ri < 2; ++ri) { const int r = 32 * ri + r32; const float gr = gamL[r];
; #pragma unroll
;                 for (int si = 0; si < 2; ++si) { f32x16_t p = f32x16_t{};
; #pragma unroll
;                     for (int ks = 0; ks < 8; ++ks) p = __builtin_amdgcn_mfma_f32_32x32x16_bf16(Kn[si][ks], Qn[ri][ks], p, 0, 0, 0);
;                     float pv[16];
; #pragma unroll
;                     for (int rg = 0; rg < 16; ++rg) { const int s = 32 * si + crow16(rg, hi); const float gs = gamL[s];
;                         const bool ok = dir ? (s >= r) : (s <= r);
;                         pv[rg] = ok ? p[rg] * __expf(gr - gs) : 0.f; }
; #pragma unroll
;                     for (int st = 0; st < 2; ++st) { v4u wv; wv.x = pk2(pv[8 * st + 0], pv[8 * st + 1]); wv.y = pk2(pv[8 * st + 2], pv[8 * st + 3]); wv.z = pk2(pv[8 * st + 4], pv[8 * st + 5]); wv.w = pk2(pv[8 * st + 6], pv[8 * st + 7]);
;                         *(v4u*)(item + ITEM_AQK + ((ri * 2 + si) * 2 + st) * 1024 + lane * 16) = wv; } } }
	v_cndmask_b32_e64 v15, 0, v15, s[44:45]
	v_cmp_ge_i32_e64 s[44:45], v213, v187
	v_cndmask_b32_e64 v52, 0, 1, s[46:47]
	v_cmp_le_i32_e64 s[46:47], v203, v187
	v_cndmask_b32_e64 v53, 0, 1, s[44:45]
	v_cndmask_b32_e64 v52, v53, v52, s[40:41]
	v_and_b32_e32 v52, 1, v52
	v_cmp_eq_u32_e64 s[44:45], 1, v52
	v_sub_f32_e32 v52, v181, v64
	v_mul_f32_e32 v52, 0x3fb8aa3b, v52
	v_exp_f32_e32 v52, v52
	v_cvt_pk_bf16_f32 v5, v14, v15
	v_mul_f32_e32 v16, v52, v16
	v_cndmask_b32_e64 v16, 0, v16, s[44:45]
	v_cmp_ge_i32_e64 s[44:45], v203, v187
	v_cndmask_b32_e64 v52, 0, 1, s[46:47]
	v_cmp_le_i32_e64 s[46:47], v211, v187
	v_cndmask_b32_e64 v53, 0, 1, s[44:45]
	v_cndmask_b32_e64 v52, v53, v52, s[40:41]
	v_and_b32_e32 v52, 1, v52
	v_cmp_eq_u32_e64 s[44:45], 1, v52
	v_sub_f32_e32 v52, v181, v65
	v_mul_f32_e32 v52, 0x3fb8aa3b, v52
	v_exp_f32_e32 v52, v52
	s_nop 0
	v_mul_f32_e32 v17, v52, v17
	v_cndmask_b32_e64 v17, 0, v17, s[44:45]
	v_cmp_ge_i32_e64 s[44:45], v211, v187
	v_cndmask_b32_e64 v52, 0, 1, s[46:47]
	v_cmp_le_i32_e64 s[46:47], v212, v187
	v_cndmask_b32_e64 v53, 0, 1, s[44:45]
	v_cndmask_b32_e64 v52, v53, v52, s[40:41]
	v_and_b32_e32 v52, 1, v52
	v_cmp_eq_u32_e64 s[44:45], 1, v52
	v_sub_f32_e32 v52, v181, v66
	v_mul_f32_e32 v52, 0x3fb8aa3b, v52
	v_exp_f32_e32 v52, v52
	v_cvt_pk_bf16_f32 v6, v16, v17
	v_mul_f32_e32 v18, v52, v18
	v_cndmask_b32_e64 v18, 0, v18, s[44:45]
	v_cmp_ge_i32_e64 s[44:45], v212, v187
	v_cndmask_b32_e64 v52, 0, 1, s[46:47]
	s_nop 0
	v_cndmask_b32_e64 v53, 0, 1, s[44:45]
	v_cndmask_b32_e64 v52, v53, v52, s[40:41]
	v_and_b32_e32 v52, 1, v52
	v_cmp_eq_u32_e64 s[44:45], 1, v52
	v_sub_f32_e32 v52, v181, v67
	v_mul_f32_e32 v52, 0x3fb8aa3b, v52
	v_exp_f32_e32 v52, v52
	s_nop 0
	v_mul_f32_e32 v19, v52, v19
	v_cndmask_b32_e64 v19, 0, v19, s[44:45]
	v_add_co_u32_e64 v52, s[44:45], s90, v166
	v_cvt_pk_bf16_f32 v7, v18, v19
	s_nop 0
	v_addc_co_u32_e64 v53, s[44:45], -1, v167, s[44:45]
	global_store_dwordx4 v[52:53], v[4:7], off offset:-3584
	v_cmp_le_i32_e64 s[44:45], v201, v187
	s_nop 0
	v_mfma_f32_32x32x16_bf16 v[4:19], v[96:99], v[48:51], 0
	v_mfma_f32_32x32x16_bf16 v[4:19], v[88:91], v[44:47], v[4:19]
	v_mfma_f32_32x32x16_bf16 v[4:19], v[92:95], v[40:43], v[4:19]
	v_mfma_f32_32x32x16_bf16 v[4:19], v[84:87], v[36:39], v[4:19]
	v_mfma_f32_32x32x16_bf16 v[4:19], v[80:83], v[32:35], v[4:19]
	v_mfma_f32_32x32x16_bf16 v[4:19], v[76:79], v[28:31], v[4:19]
	v_mfma_f32_32x32x16_bf16 v[4:19], v[68:71], v[20:23], v[4:19]
	v_sub_f32_e32 v20, v181, v136
	v_mul_f32_e32 v20, 0x3fb8aa3b, v20
	v_exp_f32_e32 v20, v20
	v_mfma_f32_32x32x16_bf16 v[4:19], v[72:75], v[24:27], v[4:19]
	s_nop 11
	v_mul_f32_e32 v4, v20, v4
	v_cndmask_b32_e64 v4, 0, v4, s[42:43]
	v_cmp_ge_i32_e64 s[42:43], v202, v187
	s_nop 1
	v_cndmask_b32_e64 v20, 0, 1, s[42:43]
	v_cndmask_b32_e64 v20, v20, v165, s[40:41]
	v_and_b32_e32 v20, 1, v20
	v_cmp_eq_u32_e64 s[42:43], 1, v20
	v_sub_f32_e32 v20, v181, v137
	v_mul_f32_e32 v20, 0x3fb8aa3b, v20
	v_exp_f32_e32 v20, v20
	s_nop 0
	v_mul_f32_e32 v5, v20, v5
	v_cndmask_b32_e64 v5, 0, v5, s[42:43]
	v_cmp_ge_i32_e64 s[42:43], v201, v187
	v_cndmask_b32_e64 v20, 0, 1, s[44:45]
	v_cmp_le_i32_e64 s[44:45], v200, v187
	v_cndmask_b32_e64 v21, 0, 1, s[42:43]
	v_cndmask_b32_e64 v20, v21, v20, s[40:41]
	v_and_b32_e32 v20, 1, v20
	v_cmp_eq_u32_e64 s[42:43], 1, v20
	v_sub_f32_e32 v20, v181, v138
	v_mul_f32_e32 v20, 0x3fb8aa3b, v20
	v_exp_f32_e32 v20, v20
	v_cvt_pk_bf16_f32 v4, v4, v5
	v_mul_f32_e32 v6, v20, v6
	v_cndmask_b32_e64 v6, 0, v6, s[42:43]
	v_cmp_ge_i32_e64 s[42:43], v200, v187
	v_cndmask_b32_e64 v20, 0, 1, s[44:45]
	v_cmp_le_i32_e64 s[44:45], v199, v187
	v_cndmask_b32_e64 v21, 0, 1, s[42:43]
	v_cndmask_b32_e64 v20, v21, v20, s[40:41]
	v_and_b32_e32 v20, 1, v20
	v_cmp_eq_u32_e64 s[42:43], 1, v20
	v_sub_f32_e32 v20, v181, v139
	v_mul_f32_e32 v20, 0x3fb8aa3b, v20
	v_exp_f32_e32 v20, v20
	s_nop 0
	v_mul_f32_e32 v7, v20, v7
	v_cndmask_b32_e64 v7, 0, v7, s[42:43]
	v_cmp_ge_i32_e64 s[42:43], v199, v187
	v_cndmask_b32_e64 v20, 0, 1, s[44:45]
	v_cmp_le_i32_e64 s[44:45], v198, v187
	v_cndmask_b32_e64 v21, 0, 1, s[42:43]
	v_cndmask_b32_e64 v20, v21, v20, s[40:41]
	v_and_b32_e32 v20, 1, v20
	v_cmp_eq_u32_e64 s[42:43], 1, v20
	v_sub_f32_e32 v20, v181, v132
	v_mul_f32_e32 v20, 0x3fb8aa3b, v20
	v_exp_f32_e32 v20, v20
	v_cvt_pk_bf16_f32 v5, v6, v7
	v_mul_f32_e32 v8, v20, v8
	v_cndmask_b32_e64 v8, 0, v8, s[42:43]
	v_cmp_ge_i32_e64 s[42:43], v198, v187
	v_cndmask_b32_e64 v20, 0, 1, s[44:45]
	v_cmp_le_i32_e64 s[44:45], v197, v187
	v_cndmask_b32_e64 v21, 0, 1, s[42:43]
	v_cndmask_b32_e64 v20, v21, v20, s[40:41]
	v_and_b32_e32 v20, 1, v20
	v_cmp_eq_u32_e64 s[42:43], 1, v20
	v_sub_f32_e32 v20, v181, v133
	v_mul_f32_e32 v20, 0x3fb8aa3b, v20
	v_exp_f32_e32 v20, v20
	s_nop 0
	v_mul_f32_e32 v9, v20, v9
	v_cndmask_b32_e64 v9, 0, v9, s[42:43]
	v_cmp_ge_i32_e64 s[42:43], v197, v187
	v_cndmask_b32_e64 v20, 0, 1, s[44:45]
	v_cmp_le_i32_e64 s[44:45], v196, v187
	v_cndmask_b32_e64 v21, 0, 1, s[42:43]
	v_cndmask_b32_e64 v20, v21, v20, s[40:41]
	v_and_b32_e32 v20, 1, v20
	v_cmp_eq_u32_e64 s[42:43], 1, v20
	v_sub_f32_e32 v20, v181, v134
	v_mul_f32_e32 v20, 0x3fb8aa3b, v20
	v_exp_f32_e32 v20, v20
	v_cvt_pk_bf16_f32 v6, v8, v9
	v_mul_f32_e32 v10, v20, v10
	v_cndmask_b32_e64 v10, 0, v10, s[42:43]
	v_cmp_ge_i32_e64 s[42:43], v196, v187
	v_cndmask_b32_e64 v20, 0, 1, s[44:45]
	v_cmp_le_i32_e64 s[44:45], v195, v187
	v_cndmask_b32_e64 v21, 0, 1, s[42:43]
	v_cndmask_b32_e64 v20, v21, v20, s[40:41]
	v_and_b32_e32 v20, 1, v20
	v_cmp_eq_u32_e64 s[42:43], 1, v20
	v_sub_f32_e32 v20, v181, v135
	v_mul_f32_e32 v20, 0x3fb8aa3b, v20
	v_exp_f32_e32 v20, v20
	s_nop 0
	v_mul_f32_e32 v11, v20, v11
; #define LAS __attribute__((address_space(3)))
; __device__ __forceinline__ unsigned pk2(float lo, float hi) { const f32x2_cv v = {lo, hi}; const bf16x2_cv b = __builtin_convertvector(v, bf16x2_cv); return __builtin_bit_cast(unsigned, b); }
; __device__ __forceinline__ int crow16(int r, int hi) { return (r & 3) + 8 * (r >> 2) + 4 * hi; }
; __device__ __forceinline__ void dk_phase(const Frame& F, const bf16* QKrm, const unsigned char* KT, const unsigned char* VT, const float* BG, unsigned char* ITEMS) {
;     ...
;                     for (int rg = 0; rg < 16; ++rg) { const int s = 32 * si + crow16(rg, hi); const float gs = gamL[s];
;                         const bool ok = dir ? (s >= r) : (s <= r);
;                         pv[rg] = ok ? p[rg] * __expf(gr - gs) : 0.f; }
; #pragma unroll
;                     for (int st = 0; st < 2; ++st) { v4u wv; wv.x = pk2(pv[8 * st + 0], pv[8 * st + 1]); wv.y = pk2(pv[8 * st + 2], pv[8 * st + 3]); wv.z = pk2(pv[8 * st + 4], pv[8 * st + 5]); wv.w = pk2(pv[8 * st + 6], pv[8 * st + 7]);
;                         *(v4u*)(item + ITEM_AQK + ((ri * 2 + si) * 2 + st) * 1024 + lane * 16) = wv; } } }
;     ...
;         float t[64];
; #pragma unroll
;         for (int r = 0; r < 64; ++r) {
;             float acc = (lane == r) ? 1.f : 0.f;
; #pragma unroll
;             for (int s4 = 0; s4 < (r + 3) / 4; ++s4) { const f32x4 a = *(const LAS f32x4*)(Amat + r * 64 + 4 * s4);
;                 if (4 * s4 + 0 < r) acc -= a.x * t[4 * s4 + 0]; if (4 * s4 + 1 < r) acc -= a.y * t[4 * s4 + 1];
;                 if (4 * s4 + 2 < r) acc -= a.z * t[4 * s4 + 2]; if (4 * s4 + 3 < r) acc -= a.w * t[4 * s4 + 3]; }
;             t[r] = acc;
;         }
	v_cndmask_b32_e64 v11, 0, v11, s[42:43]
	v_cmp_ge_i32_e64 s[42:43], v195, v187
	v_cndmask_b32_e64 v20, 0, 1, s[44:45]
	v_cmp_le_i32_e64 s[44:45], v194, v187
	v_cndmask_b32_e64 v21, 0, 1, s[42:43]
	v_cndmask_b32_e64 v20, v21, v20, s[40:41]
	v_and_b32_e32 v20, 1, v20
	v_cmp_eq_u32_e64 s[42:43], 1, v20
	v_sub_f32_e32 v20, v181, v140
	v_mul_f32_e32 v20, 0x3fb8aa3b, v20
	v_exp_f32_e32 v20, v20
	v_cvt_pk_bf16_f32 v7, v10, v11
	global_store_dwordx4 v[52:53], v[4:7], off offset:-2560
	v_mul_f32_e32 v12, v20, v12
	v_cndmask_b32_e64 v12, 0, v12, s[42:43]
	v_cmp_ge_i32_e64 s[42:43], v194, v187
	v_cndmask_b32_e64 v20, 0, 1, s[44:45]
	v_cmp_le_i32_e64 s[44:45], v193, v187
	v_cndmask_b32_e64 v21, 0, 1, s[42:43]
	v_cndmask_b32_e64 v20, v21, v20, s[40:41]
	v_and_b32_e32 v20, 1, v20
	v_cmp_eq_u32_e64 s[42:43], 1, v20
	v_sub_f32_e32 v20, v181, v141
	v_mul_f32_e32 v20, 0x3fb8aa3b, v20
	v_exp_f32_e32 v20, v20
	s_nop 0
	v_mul_f32_e32 v13, v20, v13
	v_cndmask_b32_e64 v13, 0, v13, s[42:43]
	v_cmp_ge_i32_e64 s[42:43], v193, v187
	v_cndmask_b32_e64 v20, 0, 1, s[44:45]
	v_cmp_le_i32_e64 s[44:45], v192, v187
	v_cndmask_b32_e64 v21, 0, 1, s[42:43]
	v_cndmask_b32_e64 v20, v21, v20, s[40:41]
	v_and_b32_e32 v20, 1, v20
	v_cmp_eq_u32_e64 s[42:43], 1, v20
	v_sub_f32_e32 v20, v181, v142
	v_mul_f32_e32 v20, 0x3fb8aa3b, v20
	v_exp_f32_e32 v20, v20
	v_cvt_pk_bf16_f32 v4, v12, v13
	v_mul_f32_e32 v14, v20, v14
	v_cndmask_b32_e64 v14, 0, v14, s[42:43]
	v_cmp_ge_i32_e64 s[42:43], v192, v187
	v_cndmask_b32_e64 v20, 0, 1, s[44:45]
	v_cmp_le_i32_e64 s[44:45], v191, v187
	v_cndmask_b32_e64 v21, 0, 1, s[42:43]
	v_cndmask_b32_e64 v20, v21, v20, s[40:41]
	v_and_b32_e32 v20, 1, v20
	v_cmp_eq_u32_e64 s[42:43], 1, v20
	v_sub_f32_e32 v20, v181, v143
	v_mul_f32_e32 v20, 0x3fb8aa3b, v20
	v_exp_f32_e32 v20, v20
	s_nop 0
	v_mul_f32_e32 v15, v20, v15
	v_cndmask_b32_e64 v15, 0, v15, s[42:43]
	v_cmp_ge_i32_e64 s[42:43], v191, v187
	v_cndmask_b32_e64 v20, 0, 1, s[44:45]
	v_cmp_le_i32_e64 s[44:45], v190, v187
	v_cndmask_b32_e64 v21, 0, 1, s[42:43]
	v_cndmask_b32_e64 v20, v21, v20, s[40:41]
	v_and_b32_e32 v20, 1, v20
	v_cmp_eq_u32_e64 s[42:43], 1, v20
	v_sub_f32_e32 v20, v181, v144
	v_mul_f32_e32 v20, 0x3fb8aa3b, v20
	v_exp_f32_e32 v20, v20
	v_cvt_pk_bf16_f32 v5, v14, v15
	v_mul_f32_e32 v16, v20, v16
	v_cndmask_b32_e64 v16, 0, v16, s[42:43]
	v_cmp_ge_i32_e64 s[42:43], v190, v187
	v_cndmask_b32_e64 v20, 0, 1, s[44:45]
	v_cmp_le_i32_e64 s[44:45], v189, v187
	v_cndmask_b32_e64 v21, 0, 1, s[42:43]
	v_cndmask_b32_e64 v20, v21, v20, s[40:41]
	v_and_b32_e32 v20, 1, v20
	v_cmp_eq_u32_e64 s[42:43], 1, v20
	v_sub_f32_e32 v20, v181, v145
	v_mul_f32_e32 v20, 0x3fb8aa3b, v20
	v_exp_f32_e32 v20, v20
	s_nop 0
	v_mul_f32_e32 v17, v20, v17
	v_cndmask_b32_e64 v17, 0, v17, s[42:43]
	v_cmp_ge_i32_e64 s[42:43], v189, v187
	v_cndmask_b32_e64 v20, 0, 1, s[44:45]
	v_cmp_le_i32_e64 s[44:45], v188, v187
	v_cndmask_b32_e64 v21, 0, 1, s[42:43]
	v_cndmask_b32_e64 v20, v21, v20, s[40:41]
	v_and_b32_e32 v20, 1, v20
	v_cmp_eq_u32_e64 s[42:43], 1, v20
	v_sub_f32_e32 v20, v181, v146
	v_mul_f32_e32 v20, 0x3fb8aa3b, v20
	v_exp_f32_e32 v20, v20
	v_cvt_pk_bf16_f32 v6, v16, v17
	v_mul_f32_e32 v18, v20, v18
	v_cndmask_b32_e64 v18, 0, v18, s[42:43]
	v_cmp_ge_i32_e64 s[42:43], v188, v187
	v_cndmask_b32_e64 v20, 0, 1, s[44:45]
	s_nop 0
	v_cndmask_b32_e64 v21, 0, 1, s[42:43]
	v_cndmask_b32_e64 v20, v21, v20, s[40:41]
	v_and_b32_e32 v20, 1, v20
	v_cmp_eq_u32_e64 s[42:43], 1, v20
	v_sub_f32_e32 v20, v181, v147
	v_mul_f32_e32 v20, 0x3fb8aa3b, v20
	v_exp_f32_e32 v20, v20
	s_nop 0
	v_mul_f32_e32 v19, v20, v19
	v_cndmask_b32_e64 v19, 0, v19, s[42:43]
	v_cvt_pk_bf16_f32 v7, v18, v19
	global_store_dwordx4 v[52:53], v[4:7], off offset:-1536
	s_waitcnt lgkmcnt(0)
	ds_read2_b64 v[4:7], v2 offset0:32 offset1:64
	ds_read_b128 v[188:191], v2 offset:768
	ds_read_b128 v[212:215], v2 offset:1280
	ds_read_b128 v[216:219], v2 offset:1024
	v_cndmask_b32_e64 v30, 0, 1.0, vcc
	v_cmp_eq_u32_e32 vcc, 1, v185
	s_nop 1
	v_cndmask_b32_e64 v13, 0, 1.0, vcc
	v_cmp_eq_u32_e32 vcc, 2, v185
	s_waitcnt lgkmcnt(3)
	v_mov_b32_e32 v14, v6
	v_mov_b32_e32 v15, v4
	v_cndmask_b32_e64 v12, 0, 1.0, vcc
	v_pk_fma_f32 v[28:29], v[30:31], v[14:15], v[12:13] op_sel_hi:[0,1,1] neg_lo:[1,0,0] neg_hi:[1,0,0]
	v_cmp_eq_u32_e32 vcc, 5, v185
	v_mov_b32_e32 v31, v29
	v_mov_b32_e32 v6, v29
	v_cndmask_b32_e64 v4, 0, 1.0, vcc
	s_waitcnt lgkmcnt(1)
	v_fma_f32 v4, -v30, v212, v4
	v_mov_b32_e32 v16, v213
	v_mov_b32_e32 v17, v29
	v_mov_b32_e32 v5, v28
	v_mov_b32_e32 v21, v190
	s_waitcnt lgkmcnt(0)
	v_pk_mul_f32 v[22:23], v[30:31], v[216:217]
	ds_read_b128 v[10:13], v2 offset:1536
	ds_read2_b64 v[228:231], v2 offset0:162 offset1:194
	ds_read_b128 v[232:235], v2 offset:1792
	v_pk_fma_f32 v[26:27], v[6:7], v[16:17], v[4:5] neg_lo:[1,0,0] neg_hi:[1,0,0]
	v_cmp_eq_u32_e32 vcc, 3, v185
	v_mov_b32_e32 v20, v189
	v_mov_b32_e32 v24, v29
	v_mov_b32_e32 v25, v27
	v_cndmask_b32_e64 v35, 0, 1.0, vcc
	v_cmp_eq_u32_e32 vcc, 6, v185
	v_pk_mul_f32 v[16:17], v[20:21], v[24:25]
	s_waitcnt lgkmcnt(1)
	v_mov_b32_e32 v21, v228
	v_mul_f32_e32 v4, v29, v11
	v_cndmask_b32_e64 v34, 0, 1.0, vcc
	v_mov_b32_e32 v11, v188
	v_pk_fma_f32 v[8:9], v[30:31], v[10:11], v[34:35] op_sel_hi:[0,1,1] neg_lo:[1,0,0] neg_hi:[1,0,0]
	v_mov_b32_e32 v5, v16
	v_pk_add_f32 v[4:5], v[8:9], v[4:5] neg_lo:[0,1] neg_hi:[0,1]
	v_mul_f32_e32 v32, v27, v12
	v_mov_b32_e32 v33, v17
	v_cmp_eq_u32_e32 vcc, 4, v185
	v_pk_add_f32 v[32:33], v[4:5], v[32:33] neg_lo:[0,1] neg_hi:[0,1]
	v_mov_b32_e32 v4, v27
	v_cndmask_b32_e64 v41, 0, 1.0, vcc
	v_cmp_eq_u32_e32 vcc, 7, v185
	v_mov_b32_e32 v5, v33
	s_waitcnt lgkmcnt(0)
; #define LAS __attribute__((address_space(3)))
; __device__ __forceinline__ void dk_phase(const Frame& F, const bf16* QKrm, const unsigned char* KT, const unsigned char* VT, const float* BG, unsigned char* ITEMS) {
;     ...
;         float t[64];
; #pragma unroll
;         for (int r = 0; r < 64; ++r) {
;             float acc = (lane == r) ? 1.f : 0.f;
; #pragma unroll
;             for (int s4 = 0; s4 < (r + 3) / 4; ++s4) { const f32x4 a = *(const LAS f32x4*)(Amat + r * 64 + 4 * s4);
;                 if (4 * s4 + 0 < r) acc -= a.x * t[4 * s4 + 0]; if (4 * s4 + 1 < r) acc -= a.y * t[4 * s4 + 1];
;                 if (4 * s4 + 2 < r) acc -= a.z * t[4 * s4 + 2]; if (4 * s4 + 3 < r) acc -= a.w * t[4 * s4 + 3]; }
;             t[r] = acc;
;         }
	v_mul_f32_e32 v8, v30, v232
	v_mul_f32_e32 v36, v29, v233
	v_cndmask_b32_e64 v40, 0, 1.0, vcc
	v_mov_b32_e32 v9, v22
	v_pk_mul_f32 v[34:35], v[218:219], v[4:5]
	v_pk_add_f32 v[8:9], v[40:41], v[8:9] neg_lo:[0,1] neg_hi:[0,1]
	v_mov_b32_e32 v37, v23
	v_mul_f32_e32 v10, v27, v234
	v_mul_f32_e32 v38, v33, v235
	v_pk_add_f32 v[8:9], v[8:9], v[36:37] neg_lo:[0,1] neg_hi:[0,1]
	v_mov_b32_e32 v11, v34
	v_pk_add_f32 v[8:9], v[8:9], v[10:11] neg_lo:[0,1] neg_hi:[0,1]
	v_mov_b32_e32 v39, v35
	v_pk_add_f32 v[34:35], v[8:9], v[38:39] neg_lo:[0,1] neg_hi:[0,1]
	ds_read_b128 v[8:11], v2 offset:2048
	ds_read_b128 v[236:239], v2 offset:1808
	v_cmp_eq_u32_e32 vcc, 8, v185
	ds_read_b128 v[42:45], v2 offset:2064
	ds_read_b128 v[46:49], v2 offset:2576
	ds_read_b128 v[240:243], v2 offset:2304
	ds_read_b128 v[188:191], v2 offset:2320
	v_cndmask_b32_e64 v12, 0, 1.0, vcc
	s_waitcnt lgkmcnt(5)
	v_pk_mul_f32 v[8:9], v[30:31], v[8:9]
	v_mov_b32_e32 v20, v215
	v_mov_b32_e32 v22, v33
	v_mov_b32_e32 v23, v35
	v_sub_f32_e32 v8, v12, v8
	v_pk_mul_f32 v[20:21], v[20:21], v[22:23]
	s_waitcnt lgkmcnt(4)
	v_mov_b32_e32 v41, v238
	v_sub_f32_e32 v8, v8, v9
	v_mul_f32_e32 v16, v33, v11
	v_pk_mov_b32 v[18:19], v[26:27], v[214:215] op_sel:[1,0]
	v_mov_b32_e32 v11, v27
	v_mov_b32_e32 v9, v26
	v_pk_fma_f32 v[8:9], v[18:19], v[10:11], v[8:9] neg_lo:[1,0,0] neg_hi:[1,0,0]
	v_mov_b32_e32 v17, v20
	s_waitcnt lgkmcnt(3)
	v_mul_f32_e32 v36, v35, v42
	v_pk_add_f32 v[8:9], v[8:9], v[16:17] neg_lo:[0,1] neg_hi:[0,1]
	v_mov_b32_e32 v37, v21
	v_pk_add_f32 v[36:37], v[8:9], v[36:37] neg_lo:[0,1] neg_hi:[0,1]
	v_cmp_eq_u32_e32 vcc, 9, v185
	v_mov_b32_e32 v64, v35
	s_nop 0
	v_cndmask_b32_e64 v12, 0, 1.0, vcc
	s_waitcnt lgkmcnt(1)
	v_fma_f32 v12, -v30, v240, v12
	v_mov_b32_e32 v8, v241
	v_mov_b32_e32 v9, v242
	v_pk_mul_f32 v[8:9], v[24:25], v[8:9]
	v_mov_b32_e32 v65, v37
	v_sub_f32_e32 v8, v12, v8
	v_pk_mul_f32 v[6:7], v[230:231], v[64:65]
	v_sub_f32_e32 v8, v8, v9
	v_mov_b32_e32 v12, v33
	v_mov_b32_e32 v20, v243
	v_mov_b32_e32 v21, v33
	v_mov_b32_e32 v9, v32
	s_waitcnt lgkmcnt(0)
	v_mul_f32_e32 v10, v35, v188
	v_pk_fma_f32 v[8:9], v[12:13], v[20:21], v[8:9] neg_lo:[1,0,0] neg_hi:[1,0,0]
	v_mov_b32_e32 v11, v6
	v_mul_f32_e32 v16, v37, v189
	v_pk_add_f32 v[8:9], v[8:9], v[10:11] neg_lo:[0,1] neg_hi:[0,1]
	v_mov_b32_e32 v17, v7
	v_add_u32_e32 v56, 0x800, v2
	v_pk_add_f32 v[38:39], v[8:9], v[16:17] neg_lo:[0,1] neg_hi:[0,1]
	ds_read2_b64 v[6:9], v56 offset0:36 offset1:68
	ds_read_b128 v[216:219], v2 offset:2560
	ds_read_b128 v[232:235], v2 offset:2816
	ds_read_b128 v[212:215], v2 offset:2832
	ds_read_b128 v[228:231], v2 offset:2848
	ds_read_b128 v[240:243], v2 offset:3072
	v_cmp_eq_u32_e32 vcc, 10, v185
	v_mov_b32_e32 v40, v237
	v_mov_b32_e32 v66, v37
	s_waitcnt lgkmcnt(5)
	v_mov_b32_e32 v21, v6
	v_cndmask_b32_e64 v15, 0, 1.0, vcc
	s_waitcnt lgkmcnt(4)
	v_pk_mul_f32 v[6:7], v[30:31], v[216:217]
	v_mov_b32_e32 v67, v39
	v_sub_f32_e32 v6, v15, v6
	v_sub_f32_e32 v10, v6, v7
	v_pk_mul_f32 v[6:7], v[4:5], v[218:219]
	v_pk_mul_f32 v[16:17], v[40:41], v[66:67]
	v_sub_f32_e32 v6, v10, v6
	v_sub_f32_e32 v6, v6, v7
	v_mul_f32_e32 v10, v37, v47
	v_mov_b32_e32 v47, v236
	v_mov_b32_e32 v7, v34
	v_pk_fma_f32 v[6:7], v[34:35], v[46:47], v[6:7] op_sel:[1,0,0] neg_lo:[1,0,0] neg_hi:[1,0,0]
	v_mov_b32_e32 v11, v16
	v_mul_f32_e32 v12, v39, v48
	v_pk_add_f32 v[6:7], v[6:7], v[10:11] neg_lo:[0,1] neg_hi:[0,1]
	v_mov_b32_e32 v13, v17
	v_pk_add_f32 v[40:41], v[6:7], v[12:13] neg_lo:[0,1] neg_hi:[0,1]
	v_cmp_eq_u32_e32 vcc, 11, v185
	v_mov_b32_e32 v68, v39
	s_nop 0
	v_cndmask_b32_e64 v42, 0, 1.0, vcc
	s_waitcnt lgkmcnt(3)
	v_fma_f32 v42, -v30, v232, v42
	v_mov_b32_e32 v10, v233
	v_mov_b32_e32 v11, v234
	v_pk_mul_f32 v[10:11], v[24:25], v[10:11]
	v_mov_b32_e32 v69, v41
	v_sub_f32_e32 v10, v42, v10
	v_sub_f32_e32 v12, v10, v11
	v_mov_b32_e32 v10, v235
	s_waitcnt lgkmcnt(2)
	v_mov_b32_e32 v11, v212
	v_pk_mul_f32 v[10:11], v[22:23], v[10:11]
	v_pk_mul_f32 v[6:7], v[44:45], v[68:69]
	v_sub_f32_e32 v10, v12, v10
	v_sub_f32_e32 v10, v10, v11
	v_mov_b32_e32 v42, v213
	v_mov_b32_e32 v11, v36
	v_mul_f32_e32 v12, v39, v214
	v_pk_fma_f32 v[10:11], v[36:37], v[42:43], v[10:11] op_sel:[1,0,0] neg_lo:[1,0,0] neg_hi:[1,0,0]
	v_mov_b32_e32 v13, v6
	v_mul_f32_e32 v14, v41, v215
	v_pk_add_f32 v[10:11], v[10:11], v[12:13] neg_lo:[0,1] neg_hi:[0,1]
	v_mov_b32_e32 v15, v7
	v_pk_add_f32 v[42:43], v[10:11], v[14:15] neg_lo:[0,1] neg_hi:[0,1]
	v_mov_b32_e32 v20, v191
	v_mov_b32_e32 v70, v41
	v_mov_b32_e32 v71, v43
	v_cmp_eq_u32_e32 vcc, 12, v185
	v_pk_mul_f32 v[6:7], v[20:21], v[70:71]
	s_waitcnt lgkmcnt(1)
	v_mov_b32_e32 v20, v229
	v_mov_b32_e32 v21, v230
	v_cndmask_b32_e64 v11, 0, 1.0, vcc
	s_waitcnt lgkmcnt(0)
	v_pk_mul_f32 v[12:13], v[30:31], v[240:241]
	v_pk_mul_f32 v[16:17], v[4:5], v[242:243]
	v_sub_f32_e32 v11, v11, v12
	v_sub_f32_e32 v11, v11, v13
	ds_read_b128 v[12:15], v2 offset:3088
	v_sub_f32_e32 v11, v11, v16
	ds_read_b128 v[50:53], v2 offset:3104
	ds_read_b128 v[216:219], v2 offset:4640
	ds_read_b128 v[236:239], v2 offset:3328
	ds_read_b128 v[232:235], v2 offset:3344
	ds_read_b128 v[212:215], v2 offset:3360
	ds_read_b128 v[240:243], v2 offset:3584
	v_sub_f32_e32 v11, v11, v17
	s_waitcnt lgkmcnt(6)
	v_pk_mul_f32 v[12:13], v[64:65], v[12:13]
	v_mul_f32_e32 v16, v41, v15
	v_sub_f32_e32 v11, v11, v12
	v_sub_f32_e32 v12, v11, v13
	v_pk_mov_b32 v[18:19], v[38:39], v[190:191] op_sel:[1,0]
	v_mov_b32_e32 v15, v39
	v_mov_b32_e32 v13, v38
	v_pk_fma_f32 v[12:13], v[18:19], v[14:15], v[12:13] neg_lo:[1,0,0] neg_hi:[1,0,0]
	v_mov_b32_e32 v17, v6
	s_waitcnt lgkmcnt(5)
; #define LAS __attribute__((address_space(3)))
; __device__ __forceinline__ void dk_phase(const Frame& F, const bf16* QKrm, const unsigned char* KT, const unsigned char* VT, const float* BG, unsigned char* ITEMS) {
;     ...
;         float t[64];
; #pragma unroll
;         for (int r = 0; r < 64; ++r) {
;             float acc = (lane == r) ? 1.f : 0.f;
; #pragma unroll
;             for (int s4 = 0; s4 < (r + 3) / 4; ++s4) { const f32x4 a = *(const LAS f32x4*)(Amat + r * 64 + 4 * s4);
;                 if (4 * s4 + 0 < r) acc -= a.x * t[4 * s4 + 0]; if (4 * s4 + 1 < r) acc -= a.y * t[4 * s4 + 1];
;                 if (4 * s4 + 2 < r) acc -= a.z * t[4 * s4 + 2]; if (4 * s4 + 3 < r) acc -= a.w * t[4 * s4 + 3]; }
;             t[r] = acc;
;         }
	v_mul_f32_e32 v44, v43, v50
	v_pk_add_f32 v[12:13], v[12:13], v[16:17] neg_lo:[0,1] neg_hi:[0,1]
	v_mov_b32_e32 v45, v7
	v_pk_add_f32 v[44:45], v[12:13], v[44:45] neg_lo:[0,1] neg_hi:[0,1]
	v_mov_b32_e32 v72, v43
	v_mov_b32_e32 v73, v45
	v_pk_mul_f32 v[46:47], v[8:9], v[72:73]
	v_cmp_eq_u32_e32 vcc, 13, v185
	v_mov_b32_e32 v48, v41
	s_nop 0
	v_cndmask_b32_e64 v11, 0, 1.0, vcc
	s_waitcnt lgkmcnt(3)
	v_fma_f32 v11, -v30, v236, v11
	v_mov_b32_e32 v12, v237
	v_mov_b32_e32 v13, v238
	v_pk_mul_f32 v[12:13], v[24:25], v[12:13]
	s_waitcnt lgkmcnt(2)
	v_mov_b32_e32 v54, v235
	v_sub_f32_e32 v11, v11, v12
	v_sub_f32_e32 v11, v11, v13
	v_mov_b32_e32 v12, v239
	v_mov_b32_e32 v13, v232
	v_pk_mul_f32 v[12:13], v[22:23], v[12:13]
	v_mov_b32_e32 v55, v41
	v_sub_f32_e32 v6, v11, v12
	v_sub_f32_e32 v11, v6, v13
	v_mov_b32_e32 v6, v233
	v_mov_b32_e32 v7, v234
	v_pk_mul_f32 v[6:7], v[66:67], v[6:7]
	v_mov_b32_e32 v9, v46
	v_sub_f32_e32 v6, v11, v6
	v_sub_f32_e32 v6, v6, v7
	v_mov_b32_e32 v7, v40
	s_waitcnt lgkmcnt(1)
	v_mul_f32_e32 v8, v43, v212
	v_pk_fma_f32 v[6:7], v[48:49], v[54:55], v[6:7] neg_lo:[1,0,0] neg_hi:[1,0,0]
	v_mul_f32_e32 v12, v45, v213
	v_pk_add_f32 v[6:7], v[6:7], v[8:9] neg_lo:[0,1] neg_hi:[0,1]
	v_mov_b32_e32 v13, v47
	v_pk_add_f32 v[46:47], v[6:7], v[12:13] neg_lo:[0,1] neg_hi:[0,1]
	ds_read2_b64 v[6:9], v56 offset0:166 offset1:198
	ds_read_b128 v[188:191], v2 offset:3600
	v_mov_b32_e32 v74, v45
	v_mov_b32_e32 v75, v47
	v_cmp_eq_u32_e32 vcc, 14, v185
	v_pk_mul_f32 v[12:13], v[20:21], v[74:75]
	s_waitcnt lgkmcnt(1)
	v_mov_b32_e32 v21, v6
	v_cndmask_b32_e64 v11, 0, 1.0, vcc
	v_pk_mul_f32 v[6:7], v[30:31], v[240:241]
	v_mov_b32_e32 v49, v12
	v_sub_f32_e32 v6, v11, v6
	v_sub_f32_e32 v11, v6, v7
	v_pk_mul_f32 v[6:7], v[4:5], v[242:243]
	ds_read_b128 v[16:19], v2 offset:3616
	ds_read_b128 v[236:239], v2 offset:3840
	ds_read_b128 v[232:235], v2 offset:3856
	ds_read_b128 v[240:243], v2 offset:3888
	v_sub_f32_e32 v6, v11, v6
	v_sub_f32_e32 v11, v6, v7
	s_waitcnt lgkmcnt(4)
	v_pk_mul_f32 v[6:7], v[64:65], v[188:189]
	v_mov_b32_e32 v55, v13
	v_sub_f32_e32 v6, v11, v6
	v_sub_f32_e32 v11, v6, v7
	v_pk_mul_f32 v[6:7], v[68:69], v[190:191]
	ds_read_b128 v[188:191], v2 offset:3872
	s_waitcnt lgkmcnt(4)
	v_mul_f32_e32 v48, v45, v17
	v_sub_f32_e32 v6, v11, v6
	v_sub_f32_e32 v6, v6, v7
	v_mov_b32_e32 v17, v228
	ds_read_b128 v[228:231], v2 offset:4112
	v_mov_b32_e32 v7, v42
	v_pk_fma_f32 v[6:7], v[42:43], v[16:17], v[6:7] op_sel:[1,0,0] neg_lo:[1,0,0] neg_hi:[1,0,0]
	v_mul_f32_e32 v54, v47, v18
	v_pk_add_f32 v[6:7], v[6:7], v[48:49] neg_lo:[0,1] neg_hi:[0,1]
	v_pk_add_f32 v[48:49], v[6:7], v[54:55] neg_lo:[0,1] neg_hi:[0,1]
	v_mov_b32_e32 v76, v47
	v_mov_b32_e32 v77, v49
	v_pk_mul_f32 v[6:7], v[52:53], v[76:77]
	v_cmp_eq_u32_e32 vcc, 15, v185
	s_nop 1
	v_cndmask_b32_e64 v16, 0, 1.0, vcc
	s_waitcnt lgkmcnt(4)
	v_fma_f32 v16, -v30, v236, v16
	v_mov_b32_e32 v10, v237
	v_mov_b32_e32 v11, v238
	v_pk_mul_f32 v[10:11], v[24:25], v[10:11]
	v_cmp_eq_u32_e32 vcc, 16, v185
	v_sub_f32_e32 v10, v16, v10
	v_sub_f32_e32 v12, v10, v11
	v_mov_b32_e32 v10, v239
	ds_read_b128 v[236:239], v2 offset:4096
	s_waitcnt lgkmcnt(4)
	v_mov_b32_e32 v11, v232
	v_pk_mul_f32 v[10:11], v[22:23], v[10:11]
	s_waitcnt lgkmcnt(3)
	v_mov_b32_e32 v63, v242
	v_sub_f32_e32 v10, v12, v10
	v_sub_f32_e32 v18, v10, v11
	v_mov_b32_e32 v10, v233
	v_mov_b32_e32 v11, v234
	v_pk_mul_f32 v[16:17], v[66:67], v[10:11]
	v_sub_f32_e32 v16, v18, v16
	v_sub_f32_e32 v18, v16, v17
	v_mov_b32_e32 v16, v235
	s_waitcnt lgkmcnt(2)
	v_mov_b32_e32 v17, v188
	v_pk_mul_f32 v[16:17], v[70:71], v[16:17]
	v_mov_b32_e32 v50, v189
	v_sub_f32_e32 v10, v18, v16
	v_sub_f32_e32 v10, v10, v17
	v_mov_b32_e32 v11, v44
	v_mul_f32_e32 v12, v47, v190
	v_mul_f32_e32 v16, v49, v191
	v_pk_fma_f32 v[10:11], v[44:45], v[50:51], v[10:11] op_sel:[1,0,0] neg_lo:[1,0,0] neg_hi:[1,0,0]
	v_mov_b32_e32 v13, v6
	v_pk_add_f32 v[10:11], v[10:11], v[12:13] neg_lo:[0,1] neg_hi:[0,1]
	v_mov_b32_e32 v17, v7
	v_pk_add_f32 v[50:51], v[10:11], v[16:17] neg_lo:[0,1] neg_hi:[0,1]
	v_cndmask_b32_e64 v16, 0, 1.0, vcc
	ds_read_b128 v[58:61], v2 offset:4128
	v_mov_b32_e32 v20, v215
	v_mov_b32_e32 v78, v49
	s_waitcnt lgkmcnt(1)
	v_pk_mul_f32 v[10:11], v[30:31], v[236:237]
	v_mov_b32_e32 v79, v51
	v_sub_f32_e32 v10, v16, v10
	v_sub_f32_e32 v16, v10, v11
	v_pk_mul_f32 v[10:11], v[4:5], v[238:239]
	v_pk_mul_f32 v[6:7], v[20:21], v[78:79]
	v_sub_f32_e32 v10, v16, v10
	v_sub_f32_e32 v12, v10, v11
	v_pk_mul_f32 v[10:11], v[64:65], v[228:229]
	s_waitcnt lgkmcnt(0)
	v_pk_mul_f32 v[16:17], v[72:73], v[58:59]
	v_sub_f32_e32 v10, v12, v10
	v_sub_f32_e32 v12, v10, v11
	v_pk_mul_f32 v[10:11], v[68:69], v[230:231]
	v_mul_f32_e32 v20, v49, v61
	v_sub_f32_e32 v10, v12, v10
	v_sub_f32_e32 v18, v10, v11
	ds_read_b128 v[10:13], v2 offset:4144
	ds_read_b128 v[232:235], v2 offset:4352
	ds_read_b128 v[188:191], v2 offset:4368
	ds_read_b128 v[236:239], v2 offset:4384
	ds_read_b128 v[228:231], v2 offset:4400
	v_sub_f32_e32 v16, v18, v16
	v_sub_f32_e32 v16, v16, v17
	v_pk_mov_b32 v[14:15], v[46:47], v[214:215] op_sel:[1,0]
	ds_read_b128 v[212:215], v2 offset:4608
	v_mov_b32_e32 v61, v47
	v_mov_b32_e32 v17, v46
	v_pk_fma_f32 v[14:15], v[14:15], v[60:61], v[16:17] neg_lo:[1,0,0] neg_hi:[1,0,0]
	v_mov_b32_e32 v21, v6
	s_waitcnt lgkmcnt(5)
	v_mul_f32_e32 v52, v51, v10
	v_pk_add_f32 v[14:15], v[14:15], v[20:21] neg_lo:[0,1] neg_hi:[0,1]
	v_mov_b32_e32 v53, v7
	v_pk_add_f32 v[52:53], v[14:15], v[52:53] neg_lo:[0,1] neg_hi:[0,1]
	v_mov_b32_e32 v80, v51
	v_mov_b32_e32 v81, v53
	v_pk_mul_f32 v[20:21], v[8:9], v[80:81]
	v_cmp_eq_u32_e32 vcc, 17, v185
	s_nop 1
	v_cndmask_b32_e64 v10, 0, 1.0, vcc
	s_waitcnt lgkmcnt(4)
; #define LAS __attribute__((address_space(3)))
; __device__ __forceinline__ void dk_phase(const Frame& F, const bf16* QKrm, const unsigned char* KT, const unsigned char* VT, const float* BG, unsigned char* ITEMS) {
;     ...
;         float t[64];
; #pragma unroll
;         for (int r = 0; r < 64; ++r) {
;             float acc = (lane == r) ? 1.f : 0.f;
; #pragma unroll
;             for (int s4 = 0; s4 < (r + 3) / 4; ++s4) { const f32x4 a = *(const LAS f32x4*)(Amat + r * 64 + 4 * s4);
;                 if (4 * s4 + 0 < r) acc -= a.x * t[4 * s4 + 0]; if (4 * s4 + 1 < r) acc -= a.y * t[4 * s4 + 1];
;                 if (4 * s4 + 2 < r) acc -= a.z * t[4 * s4 + 2]; if (4 * s4 + 3 < r) acc -= a.w * t[4 * s4 + 3]; }
;             t[r] = acc;
;         }
	v_fma_f32 v10, -v30, v232, v10
	v_mov_b32_e32 v14, v233
	v_mov_b32_e32 v15, v234
	v_pk_mul_f32 v[14:15], v[24:25], v[14:15]
	v_mov_b32_e32 v18, v49
	v_sub_f32_e32 v10, v10, v14
	v_sub_f32_e32 v10, v10, v15
	v_mov_b32_e32 v14, v235
	ds_read_b128 v[232:235], v2 offset:4624
	s_waitcnt lgkmcnt(4)
	v_mov_b32_e32 v15, v188
	v_pk_mul_f32 v[14:15], v[22:23], v[14:15]
	s_waitcnt lgkmcnt(3)
	v_mov_b32_e32 v54, v239
	v_sub_f32_e32 v6, v10, v14
	v_sub_f32_e32 v10, v6, v15
	v_mov_b32_e32 v6, v189
	v_mov_b32_e32 v7, v190
	v_pk_mul_f32 v[6:7], v[66:67], v[6:7]
	v_sub_f32_e32 v6, v10, v6
	v_sub_f32_e32 v8, v6, v7
	v_mov_b32_e32 v6, v191
	v_mov_b32_e32 v7, v236
	v_pk_mul_f32 v[6:7], v[70:71], v[6:7]
	v_mov_b32_e32 v55, v49
	v_sub_f32_e32 v6, v8, v6
	v_sub_f32_e32 v8, v6, v7
	v_mov_b32_e32 v6, v237
	v_mov_b32_e32 v7, v238
	v_pk_mul_f32 v[6:7], v[74:75], v[6:7]
	v_mov_b32_e32 v9, v20
	v_sub_f32_e32 v6, v8, v6
	v_sub_f32_e32 v6, v6, v7
	v_mov_b32_e32 v7, v48
	s_waitcnt lgkmcnt(2)
	v_mul_f32_e32 v8, v51, v228
	v_pk_fma_f32 v[6:7], v[18:19], v[54:55], v[6:7] neg_lo:[1,0,0] neg_hi:[1,0,0]
	v_mul_f32_e32 v14, v53, v229
	v_pk_add_f32 v[6:7], v[6:7], v[8:9] neg_lo:[0,1] neg_hi:[0,1]
	v_mov_b32_e32 v15, v21
	v_pk_add_f32 v[54:55], v[6:7], v[14:15] neg_lo:[0,1] neg_hi:[0,1]
	v_cmp_eq_u32_e32 vcc, 18, v185
	v_add_u32_e32 v90, 0x1000, v2
	s_nop 0
	v_cndmask_b32_e64 v10, 0, 1.0, vcc
	s_waitcnt lgkmcnt(1)
	v_pk_mul_f32 v[6:7], v[30:31], v[212:213]
	ds_read2_b64 v[18:21], v90 offset0:40 offset1:72
	v_sub_f32_e32 v6, v10, v6
	v_sub_f32_e32 v10, v6, v7
	v_pk_mul_f32 v[6:7], v[4:5], v[214:215]
	v_mov_b32_e32 v62, v241
	v_sub_f32_e32 v6, v10, v6
	v_sub_f32_e32 v8, v6, v7
	s_waitcnt lgkmcnt(1)
	v_pk_mul_f32 v[6:7], v[64:65], v[232:233]
	v_mov_b32_e32 v82, v53
	v_sub_f32_e32 v6, v8, v6
	v_sub_f32_e32 v8, v6, v7
	v_pk_mul_f32 v[6:7], v[68:69], v[234:235]
	v_mov_b32_e32 v83, v55
	v_sub_f32_e32 v6, v8, v6
	v_sub_f32_e32 v10, v6, v7
	ds_read_b128 v[6:9], v2 offset:4656
	ds_read_b128 v[188:191], v2 offset:4864
	ds_read_b128 v[236:239], v2 offset:4880
	ds_read_b128 v[212:215], v2 offset:4896
	ds_read_b128 v[232:235], v2 offset:4912
	v_pk_mul_f32 v[14:15], v[62:63], v[82:83]
	s_waitcnt lgkmcnt(5)
	v_mov_b32_e32 v63, v18
	v_pk_mul_f32 v[18:19], v[72:73], v[216:217]
	v_mov_b32_e32 v59, v14
	v_sub_f32_e32 v10, v10, v18
	v_sub_f32_e32 v10, v10, v19
	v_pk_mul_f32 v[18:19], v[76:77], v[218:219]
	ds_read_b128 v[216:219], v2 offset:4928
	s_waitcnt lgkmcnt(5)
	v_mul_f32_e32 v58, v53, v7
	v_sub_f32_e32 v10, v10, v18
	v_sub_f32_e32 v18, v10, v19
	v_mov_b32_e32 v7, v240
	ds_read_b128 v[240:243], v2 offset:5120
	v_mov_b32_e32 v19, v50
	v_pk_fma_f32 v[6:7], v[50:51], v[6:7], v[18:19] op_sel:[1,0,0] neg_lo:[1,0,0] neg_hi:[1,0,0]
	v_mul_f32_e32 v60, v55, v8
	v_pk_add_f32 v[6:7], v[6:7], v[58:59] neg_lo:[0,1] neg_hi:[0,1]
	v_mov_b32_e32 v61, v15
	v_pk_add_f32 v[56:57], v[6:7], v[60:61] neg_lo:[0,1] neg_hi:[0,1]
	v_mov_b32_e32 v84, v55
	v_mov_b32_e32 v85, v57
	v_pk_mul_f32 v[6:7], v[12:13], v[84:85]
	v_cmp_eq_u32_e32 vcc, 19, v185
	s_waitcnt lgkmcnt(5)
	v_mov_b32_e32 v18, v189
	v_mov_b32_e32 v19, v190
	v_cndmask_b32_e64 v8, 0, 1.0, vcc
	v_fma_f32 v8, -v30, v188, v8
	v_pk_mul_f32 v[18:19], v[24:25], v[18:19]
	v_mov_b32_e32 v62, v231
	v_sub_f32_e32 v8, v8, v18
	v_mov_b32_e32 v18, v191
	ds_read_b128 v[188:191], v2 offset:5136
	v_sub_f32_e32 v8, v8, v19
	s_waitcnt lgkmcnt(5)
	v_mov_b32_e32 v19, v236
	v_pk_mul_f32 v[18:19], v[22:23], v[18:19]
	v_mov_b32_e32 v12, v237
	v_sub_f32_e32 v8, v8, v18
	v_mov_b32_e32 v13, v238
	v_sub_f32_e32 v8, v8, v19
	v_pk_mul_f32 v[12:13], v[66:67], v[12:13]
	v_mov_b32_e32 v18, v239
	ds_read_b128 v[236:239], v2 offset:5152
	v_sub_f32_e32 v8, v8, v12
	s_waitcnt lgkmcnt(5)
	v_mov_b32_e32 v19, v212
	v_sub_f32_e32 v8, v8, v13
	v_pk_mul_f32 v[18:19], v[70:71], v[18:19]
	v_mov_b32_e32 v86, v57
	v_sub_f32_e32 v8, v8, v18
	v_sub_f32_e32 v8, v8, v19
	v_mov_b32_e32 v18, v213
	v_mov_b32_e32 v19, v214
	v_pk_mul_f32 v[18:19], v[74:75], v[18:19]
	s_waitcnt lgkmcnt(4)
	v_mov_b32_e32 v10, v233
	v_sub_f32_e32 v8, v8, v18
	v_sub_f32_e32 v8, v8, v19
	v_mov_b32_e32 v18, v215
	v_mov_b32_e32 v19, v232
	v_pk_mul_f32 v[18:19], v[78:79], v[18:19]
	v_mov_b32_e32 v13, v52
	v_sub_f32_e32 v8, v8, v18
	v_sub_f32_e32 v12, v8, v19
	v_mul_f32_e32 v14, v55, v234
	v_mul_f32_e32 v18, v57, v235
	v_pk_fma_f32 v[10:11], v[52:53], v[10:11], v[12:13] op_sel:[1,0,0] neg_lo:[1,0,0] neg_hi:[1,0,0]
	v_mov_b32_e32 v15, v6
	v_pk_add_f32 v[10:11], v[10:11], v[14:15] neg_lo:[0,1] neg_hi:[0,1]
	v_mov_b32_e32 v19, v7
	v_pk_add_f32 v[58:59], v[10:11], v[18:19] neg_lo:[0,1] neg_hi:[0,1]
	v_mov_b32_e32 v87, v59
	v_pk_mul_f32 v[18:19], v[62:63], v[86:87]
	v_cmp_eq_u32_e32 vcc, 20, v185
	s_waitcnt lgkmcnt(3)
	v_mov_b32_e32 v97, v218
	v_cndmask_b32_e64 v6, 0, 1.0, vcc
	s_waitcnt lgkmcnt(2)
	v_fma_f32 v6, -v30, v240, v6
	v_fma_f32 v6, -v29, v241, v6
	v_pk_mul_f32 v[4:5], v[4:5], v[242:243]
	s_waitcnt lgkmcnt(1)
	v_pk_mul_f32 v[12:13], v[64:65], v[188:189]
	v_sub_f32_e32 v4, v6, v4
	v_sub_f32_e32 v8, v4, v5
	v_sub_f32_e32 v8, v8, v12
	v_sub_f32_e32 v8, v8, v13
	v_pk_mul_f32 v[12:13], v[68:69], v[190:191]
	v_pk_mov_b32 v[16:17], v[54:55], v[230:231] op_sel:[1,0]
	v_sub_f32_e32 v8, v8, v12
	v_sub_f32_e32 v8, v8, v13
	s_waitcnt lgkmcnt(0)
	v_pk_mul_f32 v[4:5], v[72:73], v[236:237]
	ds_read_b128 v[12:15], v2 offset:5168
	v_sub_f32_e32 v4, v8, v4
	v_sub_f32_e32 v8, v4, v5
	v_pk_mul_f32 v[4:5], v[76:77], v[238:239]
	v_mov_b32_e32 v25, v18
	v_sub_f32_e32 v4, v8, v4
	v_sub_f32_e32 v8, v4, v5
	ds_read_b128 v[4:7], v2 offset:5184
	ds_read_b128 v[212:215], v2 offset:5376
	ds_read_b128 v[232:235], v2 offset:5392
	ds_read_b128 v[240:243], v2 offset:5408
	ds_read_b128 v[188:191], v2 offset:5424
	ds_read_b128 v[228:231], v2 offset:5632
	ds_read_b128 v[236:239], v2 offset:7680
	s_waitcnt lgkmcnt(7)
; #define LAS __attribute__((address_space(3)))
; __device__ __forceinline__ void dk_phase(const Frame& F, const bf16* QKrm, const unsigned char* KT, const unsigned char* VT, const float* BG, unsigned char* ITEMS) {
;     ...
;         float t[64];
; #pragma unroll
;         for (int r = 0; r < 64; ++r) {
;             float acc = (lane == r) ? 1.f : 0.f;
; #pragma unroll
;             for (int s4 = 0; s4 < (r + 3) / 4; ++s4) { const f32x4 a = *(const LAS f32x4*)(Amat + r * 64 + 4 * s4);
;                 if (4 * s4 + 0 < r) acc -= a.x * t[4 * s4 + 0]; if (4 * s4 + 1 < r) acc -= a.y * t[4 * s4 + 1];
;                 if (4 * s4 + 2 < r) acc -= a.z * t[4 * s4 + 2]; if (4 * s4 + 3 < r) acc -= a.w * t[4 * s4 + 3]; }
;             t[r] = acc;
;         }
	v_pk_mul_f32 v[12:13], v[80:81], v[12:13]
	v_mul_f32_e32 v24, v57, v15
	v_sub_f32_e32 v8, v8, v12
	v_sub_f32_e32 v12, v8, v13
	v_mov_b32_e32 v15, v55
	v_mov_b32_e32 v13, v54
	v_pk_fma_f32 v[12:13], v[16:17], v[14:15], v[12:13] neg_lo:[1,0,0] neg_hi:[1,0,0]
	s_waitcnt lgkmcnt(6)
	v_mul_f32_e32 v60, v59, v4
	v_pk_add_f32 v[12:13], v[12:13], v[24:25] neg_lo:[0,1] neg_hi:[0,1]
	v_mov_b32_e32 v61, v19
	v_pk_add_f32 v[60:61], v[12:13], v[60:61] neg_lo:[0,1] neg_hi:[0,1]
	v_cmp_eq_u32_e32 vcc, 21, v185
	v_mov_b32_e32 v88, v59
	v_mov_b32_e32 v89, v61
	v_cndmask_b32_e64 v4, 0, 1.0, vcc
	s_waitcnt lgkmcnt(5)
	v_fma_f32 v4, -v30, v212, v4
	v_fma_f32 v4, -v29, v213, v4
	v_mov_b32_e32 v12, v215
	s_waitcnt lgkmcnt(4)
	v_mov_b32_e32 v13, v232
	v_fma_f32 v4, -v27, v214, v4
	ds_read_b128 v[212:215], v2 offset:5440
	v_pk_mul_f32 v[12:13], v[22:23], v[12:13]
	v_mov_b32_e32 v22, v235
	v_sub_f32_e32 v4, v4, v12
	v_sub_f32_e32 v4, v4, v13
	v_mov_b32_e32 v12, v233
	v_mov_b32_e32 v13, v234
	ds_read_b128 v[232:235], v2 offset:5648
	v_pk_mul_f32 v[16:17], v[66:67], v[12:13]
	v_sub_f32_e32 v4, v4, v16
	v_sub_f32_e32 v4, v4, v17
	s_waitcnt lgkmcnt(5)
	v_mov_b32_e32 v23, v240
	v_pk_mul_f32 v[22:23], v[70:71], v[22:23]
	v_mov_b32_e32 v12, v241
	v_sub_f32_e32 v4, v4, v22
	v_mov_b32_e32 v13, v242
	v_sub_f32_e32 v4, v4, v23
	v_pk_mul_f32 v[12:13], v[74:75], v[12:13]
	v_pk_mul_f32 v[20:21], v[20:21], v[88:89]
	v_sub_f32_e32 v4, v4, v12
	v_sub_f32_e32 v4, v4, v13
	v_mov_b32_e32 v12, v243
	ds_read_b128 v[240:243], v2 offset:5664
	s_waitcnt lgkmcnt(5)
	v_mov_b32_e32 v13, v188
	v_pk_mul_f32 v[12:13], v[78:79], v[12:13]
	v_mov_b32_e32 v8, v57
	v_sub_f32_e32 v4, v4, v12
	v_mov_b32_e32 v12, v189
	v_sub_f32_e32 v4, v4, v13
	v_mov_b32_e32 v13, v190
	v_pk_mul_f32 v[12:13], v[82:83], v[12:13]
	v_mov_b32_e32 v22, v191
	ds_read_b128 v[188:191], v2 offset:5680
	v_sub_f32_e32 v4, v4, v12
	v_sub_f32_e32 v12, v4, v13
	v_mov_b32_e32 v23, v57
	v_mov_b32_e32 v13, v56
	s_waitcnt lgkmcnt(3)
	v_mul_f32_e32 v14, v59, v212
	v_mul_f32_e32 v18, v61, v213
	v_pk_fma_f32 v[8:9], v[8:9], v[22:23], v[12:13] neg_lo:[1,0,0] neg_hi:[1,0,0]
	v_mov_b32_e32 v15, v20
	v_pk_add_f32 v[8:9], v[8:9], v[14:15] neg_lo:[0,1] neg_hi:[0,1]
	v_cmp_eq_u32_e32 vcc, 22, v185
	v_mov_b32_e32 v19, v21
	s_nop 0
	v_cndmask_b32_e64 v4, 0, 1.0, vcc
	v_fma_f32 v4, -v30, v228, v4
	v_fma_f32 v4, -v29, v229, v4
	v_pk_add_f32 v[62:63], v[8:9], v[18:19] neg_lo:[0,1] neg_hi:[0,1]
	v_fma_f32 v4, -v27, v230, v4
	v_fma_f32 v4, -v33, v231, v4
	s_waitcnt lgkmcnt(2)
	v_pk_mul_f32 v[12:13], v[64:65], v[232:233]
	v_sub_f32_e32 v4, v4, v12
	v_sub_f32_e32 v4, v4, v13
	v_pk_mul_f32 v[12:13], v[68:69], v[234:235]
	ds_read2_b64 v[22:25], v90 offset0:170 offset1:202
	v_sub_f32_e32 v4, v4, v12
	v_sub_f32_e32 v4, v4, v13
	s_waitcnt lgkmcnt(2)
	v_pk_mul_f32 v[12:13], v[72:73], v[240:241]
	s_waitcnt lgkmcnt(1)
	v_pk_mul_f32 v[18:19], v[80:81], v[188:189]
	v_sub_f32_e32 v4, v4, v12
	v_sub_f32_e32 v4, v4, v13
	v_pk_mul_f32 v[12:13], v[76:77], v[242:243]
	v_mov_b32_e32 v96, v217
	v_sub_f32_e32 v4, v4, v12
	v_sub_f32_e32 v4, v4, v13
	ds_read_b128 v[12:15], v2 offset:5696
	ds_read_b128 v[228:231], v2 offset:5888
	ds_read_b128 v[232:235], v2 offset:5904
	ds_read_b128 v[240:243], v2 offset:5920
	v_sub_f32_e32 v4, v4, v18
	v_sub_f32_e32 v4, v4, v19
	v_pk_mul_f32 v[18:19], v[84:85], v[190:191]
	ds_read_b128 v[188:191], v2 offset:5936
	v_mov_b32_e32 v90, v61
	v_mov_b32_e32 v91, v63
	v_sub_f32_e32 v4, v4, v18
	v_pk_mul_f32 v[8:9], v[96:97], v[90:91]
	v_sub_f32_e32 v18, v4, v19
	s_waitcnt lgkmcnt(4)
	v_mul_f32_e32 v20, v61, v13
	v_mov_b32_e32 v13, v216
	ds_read_b128 v[216:219], v2 offset:5968
	v_mov_b32_e32 v19, v58
	v_pk_fma_f32 v[10:11], v[58:59], v[12:13], v[18:19] op_sel:[1,0,0] neg_lo:[1,0,0] neg_hi:[1,0,0]
	v_mov_b32_e32 v21, v8
	v_mov_b32_e32 v97, v22
	v_mul_f32_e32 v22, v63, v14
	v_pk_add_f32 v[10:11], v[10:11], v[20:21] neg_lo:[0,1] neg_hi:[0,1]
	v_mov_b32_e32 v23, v9
	v_pk_add_f32 v[64:65], v[10:11], v[22:23] neg_lo:[0,1] neg_hi:[0,1]
	v_cmp_eq_u32_e32 vcc, 23, v185
	v_mov_b32_e32 v92, v63
	v_mov_b32_e32 v93, v65
	v_cndmask_b32_e64 v4, 0, 1.0, vcc
	s_waitcnt lgkmcnt(4)
	v_fma_f32 v4, -v30, v228, v4
	v_fma_f32 v4, -v29, v229, v4
	v_pk_mul_f32 v[94:95], v[6:7], v[92:93]
	v_fma_f32 v4, -v27, v230, v4
	s_waitcnt lgkmcnt(3)
	v_mov_b32_e32 v6, v233
	v_mov_b32_e32 v7, v234
	v_fma_f32 v4, -v33, v231, v4
	ds_read_b128 v[228:231], v2 offset:5952
	v_pk_mul_f32 v[10:11], v[66:67], v[6:7]
	v_fma_f32 v4, -v35, v232, v4
	v_sub_f32_e32 v4, v4, v10
	v_sub_f32_e32 v4, v4, v11
	v_mov_b32_e32 v18, v235
	ds_read_b128 v[232:235], v2 offset:6144
	s_waitcnt lgkmcnt(4)
	v_mov_b32_e32 v19, v240
	v_pk_mul_f32 v[18:19], v[70:71], v[18:19]
	v_mov_b32_e32 v6, v241
	v_sub_f32_e32 v4, v4, v18
	v_mov_b32_e32 v7, v242
	v_sub_f32_e32 v4, v4, v19
	v_pk_mul_f32 v[6:7], v[74:75], v[6:7]
	v_cmp_eq_u32_e32 vcc, 24, v185
	v_sub_f32_e32 v4, v4, v6
	v_sub_f32_e32 v4, v4, v7
	v_mov_b32_e32 v6, v243
	ds_read_b128 v[240:243], v2 offset:6160
	s_waitcnt lgkmcnt(4)
	v_mov_b32_e32 v7, v188
	v_pk_mul_f32 v[6:7], v[78:79], v[6:7]
	v_sub_f32_e32 v4, v4, v6
	v_sub_f32_e32 v4, v4, v7
	v_mov_b32_e32 v6, v189
	v_mov_b32_e32 v7, v190
	v_pk_mul_f32 v[10:11], v[82:83], v[6:7]
	v_sub_f32_e32 v4, v4, v10
	v_sub_f32_e32 v4, v4, v11
	v_mov_b32_e32 v10, v191
	ds_read_b128 v[188:191], v2 offset:6176
	v_cndmask_b32_e64 v12, 0, 1.0, vcc
	s_waitcnt lgkmcnt(3)
; #define LAS __attribute__((address_space(3)))
; __device__ __forceinline__ void dk_phase(const Frame& F, const bf16* QKrm, const unsigned char* KT, const unsigned char* VT, const float* BG, unsigned char* ITEMS) {
;     ...
;         float t[64];
; #pragma unroll
;         for (int r = 0; r < 64; ++r) {
;             float acc = (lane == r) ? 1.f : 0.f;
; #pragma unroll
;             for (int s4 = 0; s4 < (r + 3) / 4; ++s4) { const f32x4 a = *(const LAS f32x4*)(Amat + r * 64 + 4 * s4);
;                 if (4 * s4 + 0 < r) acc -= a.x * t[4 * s4 + 0]; if (4 * s4 + 1 < r) acc -= a.y * t[4 * s4 + 1];
;                 if (4 * s4 + 2 < r) acc -= a.z * t[4 * s4 + 2]; if (4 * s4 + 3 < r) acc -= a.w * t[4 * s4 + 3]; }
;             t[r] = acc;
;         }
	v_mov_b32_e32 v11, v228
	v_pk_mul_f32 v[10:11], v[86:87], v[10:11]
	v_mul_f32_e32 v8, v63, v230
	v_sub_f32_e32 v4, v4, v10
	v_sub_f32_e32 v6, v4, v11
	v_mov_b32_e32 v4, v229
	v_mov_b32_e32 v7, v60
	v_mul_f32_e32 v10, v65, v231
	ds_read_b128 v[228:231], v2 offset:6192
	v_pk_fma_f32 v[4:5], v[60:61], v[4:5], v[6:7] op_sel:[1,0,0] neg_lo:[1,0,0] neg_hi:[1,0,0]
	v_mov_b32_e32 v9, v94
	v_pk_add_f32 v[4:5], v[4:5], v[8:9] neg_lo:[0,1] neg_hi:[0,1]
	v_mov_b32_e32 v11, v95
	v_pk_add_f32 v[66:67], v[4:5], v[10:11] neg_lo:[0,1] neg_hi:[0,1]
	v_mov_b32_e32 v96, v215
	v_mov_b32_e32 v94, v65
	v_mov_b32_e32 v95, v67
	s_waitcnt lgkmcnt(3)
	v_fma_f32 v4, -v30, v232, v12
	v_fma_f32 v4, -v29, v233, v4
	v_fma_f32 v4, -v27, v234, v4
	v_fma_f32 v4, -v33, v235, v4
	s_waitcnt lgkmcnt(2)
	v_fma_f32 v4, -v35, v240, v4
	v_fma_f32 v12, -v37, v241, v4
	v_pk_mul_f32 v[8:9], v[68:69], v[242:243]
	v_pk_mul_f32 v[18:19], v[96:97], v[94:95]
	v_sub_f32_e32 v8, v12, v8
	v_sub_f32_e32 v12, v8, v9
	s_waitcnt lgkmcnt(1)
	v_pk_mul_f32 v[4:5], v[72:73], v[188:189]
	v_pk_mov_b32 v[16:17], v[62:63], v[214:215] op_sel:[1,0]
	v_sub_f32_e32 v4, v12, v4
	v_sub_f32_e32 v12, v4, v5
	v_pk_mul_f32 v[4:5], v[76:77], v[190:191]
	v_mov_b32_e32 v101, v218
	v_sub_f32_e32 v4, v12, v4
	v_sub_f32_e32 v6, v4, v5
	s_waitcnt lgkmcnt(0)
	v_pk_mul_f32 v[4:5], v[80:81], v[228:229]
	v_pk_mul_f32 v[8:9], v[84:85], v[230:231]
	v_sub_f32_e32 v4, v6, v4
	v_sub_f32_e32 v12, v4, v5
	ds_read_b128 v[4:7], v2 offset:6208
	v_sub_f32_e32 v8, v12, v8
	ds_read_b128 v[10:13], v2 offset:6224
	ds_read_b128 v[232:235], v2 offset:6400
	ds_read_b128 v[240:243], v2 offset:6416
	ds_read_b128 v[212:215], v2 offset:6432
	ds_read_b128 v[188:191], v2 offset:6448
	ds_read_b128 v[228:231], v2 offset:6464
	v_sub_f32_e32 v8, v8, v9
	v_mov_b32_e32 v9, v18
	s_waitcnt lgkmcnt(6)
	v_pk_mul_f32 v[4:5], v[88:89], v[4:5]
	v_mov_b32_e32 v23, v19
	v_sub_f32_e32 v4, v8, v4
	v_sub_f32_e32 v4, v4, v5
	v_mul_f32_e32 v8, v65, v7
	v_mov_b32_e32 v7, v63
	v_mov_b32_e32 v5, v62
	v_pk_fma_f32 v[4:5], v[16:17], v[6:7], v[4:5] neg_lo:[1,0,0] neg_hi:[1,0,0]
	s_waitcnt lgkmcnt(5)
	v_mul_f32_e32 v22, v67, v10
	v_pk_add_f32 v[4:5], v[4:5], v[8:9] neg_lo:[0,1] neg_hi:[0,1]
	v_cmp_eq_u32_e32 vcc, 25, v185
	v_pk_add_f32 v[68:69], v[4:5], v[22:23] neg_lo:[0,1] neg_hi:[0,1]
	s_nop 0
	v_cndmask_b32_e64 v10, 0, 1.0, vcc
	v_mov_b32_e32 v96, v67
	v_mov_b32_e32 v97, v69
	s_waitcnt lgkmcnt(4)
	v_fma_f32 v4, -v30, v232, v10
	v_fma_f32 v4, -v29, v233, v4
	v_fma_f32 v4, -v27, v234, v4
	v_fma_f32 v4, -v33, v235, v4
	ds_read_b128 v[232:235], v2 offset:6480
	s_waitcnt lgkmcnt(4)
	v_fma_f32 v10, -v35, v240, v4
	v_fma_f32 v10, -v37, v241, v10
	v_mov_b32_e32 v22, v243
	v_fma_f32 v10, -v39, v242, v10
	ds_read_b128 v[240:243], v2 offset:6656
	s_waitcnt lgkmcnt(4)
	v_mov_b32_e32 v23, v212
	v_pk_mul_f32 v[22:23], v[70:71], v[22:23]
	v_pk_mul_f32 v[8:9], v[24:25], v[96:97]
	v_sub_f32_e32 v4, v10, v22
	v_sub_f32_e32 v10, v4, v23
	v_mov_b32_e32 v4, v213
	v_mov_b32_e32 v5, v214
	v_pk_mul_f32 v[4:5], v[74:75], v[4:5]
	s_waitcnt lgkmcnt(3)
	v_mov_b32_e32 v22, v191
	v_sub_f32_e32 v4, v10, v4
	v_sub_f32_e32 v6, v4, v5
	v_mov_b32_e32 v4, v215
	ds_read_b128 v[212:215], v2 offset:6672
	v_mov_b32_e32 v5, v188
	v_pk_mul_f32 v[4:5], v[78:79], v[4:5]
	v_mov_b32_e32 v14, v65
	v_sub_f32_e32 v4, v6, v4
	v_sub_f32_e32 v10, v4, v5
	v_mov_b32_e32 v4, v189
	v_mov_b32_e32 v5, v190
	ds_read_b128 v[188:191], v2 offset:6688
	v_pk_mul_f32 v[16:17], v[82:83], v[4:5]
	v_sub_f32_e32 v10, v10, v16
	v_sub_f32_e32 v10, v10, v17
	v_cmp_eq_u32_e32 vcc, 26, v185
	s_waitcnt lgkmcnt(4)
	v_mov_b32_e32 v23, v228
	v_pk_mul_f32 v[22:23], v[86:87], v[22:23]
	v_mov_b32_e32 v100, v217
	v_sub_f32_e32 v4, v10, v22
	v_sub_f32_e32 v10, v4, v23
	v_mov_b32_e32 v4, v229
	v_mov_b32_e32 v5, v230
	v_pk_mul_f32 v[4:5], v[90:91], v[4:5]
	v_mov_b32_e32 v22, v231
	ds_read_b128 v[228:231], v2 offset:6704
	v_sub_f32_e32 v4, v10, v4
	v_sub_f32_e32 v4, v4, v5
	v_mov_b32_e32 v23, v65
	v_mov_b32_e32 v5, v64
	s_waitcnt lgkmcnt(4)
	v_mul_f32_e32 v6, v67, v232
	v_pk_fma_f32 v[4:5], v[14:15], v[22:23], v[4:5] neg_lo:[1,0,0] neg_hi:[1,0,0]
	v_mov_b32_e32 v7, v8
	v_mul_f32_e32 v16, v69, v233
	v_pk_add_f32 v[4:5], v[4:5], v[6:7] neg_lo:[0,1] neg_hi:[0,1]
	v_mov_b32_e32 v17, v9
	v_pk_add_f32 v[70:71], v[4:5], v[16:17] neg_lo:[0,1] neg_hi:[0,1]
	v_cndmask_b32_e64 v8, 0, 1.0, vcc
	v_mov_b32_e32 v98, v69
	v_mov_b32_e32 v99, v71
	s_waitcnt lgkmcnt(3)
	v_fma_f32 v4, -v30, v240, v8
	v_fma_f32 v4, -v29, v241, v4
	v_fma_f32 v4, -v27, v242, v4
	v_fma_f32 v4, -v33, v243, v4
	ds_read_b128 v[240:243], v2 offset:6720
	s_waitcnt lgkmcnt(3)
	v_fma_f32 v8, -v35, v212, v4
	v_fma_f32 v8, -v37, v213, v8
	v_fma_f32 v8, -v39, v214, v8
	v_fma_f32 v8, -v41, v215, v8
	s_waitcnt lgkmcnt(2)
	v_pk_mul_f32 v[4:5], v[72:73], v[188:189]
	v_pk_mul_f32 v[104:105], v[100:101], v[98:99]
	v_sub_f32_e32 v4, v8, v4
	v_sub_f32_e32 v8, v4, v5
	v_pk_mul_f32 v[4:5], v[76:77], v[190:191]
	v_sub_f32_e32 v4, v8, v4
	v_sub_f32_e32 v6, v4, v5
	s_waitcnt lgkmcnt(1)
	v_pk_mul_f32 v[4:5], v[80:81], v[228:229]
	v_add_u32_e32 v31, 0x1800, v2
	v_sub_f32_e32 v4, v6, v4
	v_sub_f32_e32 v6, v4, v5
	v_pk_mul_f32 v[4:5], v[84:85], v[230:231]
	ds_read2_b64 v[14:17], v31 offset0:44 offset1:76
	v_sub_f32_e32 v4, v6, v4
	ds_read_b128 v[6:9], v2 offset:6736
	ds_read_b128 v[212:215], v2 offset:6912
	ds_read_b128 v[188:191], v2 offset:6928
	ds_read_b128 v[228:231], v2 offset:6944
	v_sub_f32_e32 v10, v4, v5
	s_waitcnt lgkmcnt(5)
	v_pk_mul_f32 v[4:5], v[88:89], v[240:241]
	s_waitcnt lgkmcnt(4)
	v_mov_b32_e32 v107, v14
	v_sub_f32_e32 v4, v10, v4
	v_sub_f32_e32 v10, v4, v5
	v_pk_mul_f32 v[4:5], v[92:93], v[242:243]
	ds_read_b128 v[240:243], v2 offset:6960
	s_waitcnt lgkmcnt(4)
; #define LAS __attribute__((address_space(3)))
; __device__ __forceinline__ void dk_phase(const Frame& F, const bf16* QKrm, const unsigned char* KT, const unsigned char* VT, const float* BG, unsigned char* ITEMS) {
;     ...
;         float t[64];
; #pragma unroll
;         for (int r = 0; r < 64; ++r) {
;             float acc = (lane == r) ? 1.f : 0.f;
; #pragma unroll
;             for (int s4 = 0; s4 < (r + 3) / 4; ++s4) { const f32x4 a = *(const LAS f32x4*)(Amat + r * 64 + 4 * s4);
;                 if (4 * s4 + 0 < r) acc -= a.x * t[4 * s4 + 0]; if (4 * s4 + 1 < r) acc -= a.y * t[4 * s4 + 1];
;                 if (4 * s4 + 2 < r) acc -= a.z * t[4 * s4 + 2]; if (4 * s4 + 3 < r) acc -= a.w * t[4 * s4 + 3]; }
;             t[r] = acc;
;         }
	v_mul_f32_e32 v14, v69, v7
	v_sub_f32_e32 v4, v10, v4
	v_sub_f32_e32 v4, v4, v5
	v_mov_b32_e32 v7, v216
	ds_read_b128 v[216:219], v2 offset:6976
	v_mov_b32_e32 v5, v66
	v_pk_fma_f32 v[4:5], v[66:67], v[6:7], v[4:5] op_sel:[1,0,0] neg_lo:[1,0,0] neg_hi:[1,0,0]
	v_mov_b32_e32 v15, v104
	v_mul_f32_e32 v22, v71, v8
	v_pk_add_f32 v[4:5], v[4:5], v[14:15] neg_lo:[0,1] neg_hi:[0,1]
	v_mov_b32_e32 v23, v105
	v_pk_add_f32 v[72:73], v[4:5], v[22:23] neg_lo:[0,1] neg_hi:[0,1]
	v_mov_b32_e32 v100, v71
	v_mov_b32_e32 v101, v73
	v_cmp_eq_u32_e32 vcc, 27, v185
	v_pk_mul_f32 v[20:21], v[12:13], v[100:101]
	s_nop 0
	v_cndmask_b32_e64 v8, 0, 1.0, vcc
	s_waitcnt lgkmcnt(4)
	v_fma_f32 v4, -v30, v212, v8
	v_fma_f32 v4, -v29, v213, v4
	v_fma_f32 v4, -v27, v214, v4
	v_fma_f32 v4, -v33, v215, v4
	ds_read_b128 v[212:215], v2 offset:6992
	s_waitcnt lgkmcnt(4)
	v_fma_f32 v8, -v35, v188, v4
	v_fma_f32 v8, -v37, v189, v8
	v_fma_f32 v8, -v39, v190, v8
	v_fma_f32 v8, -v41, v191, v8
	ds_read_b128 v[188:191], v2 offset:7008
	s_waitcnt lgkmcnt(4)
	v_fma_f32 v8, -v43, v228, v8
	v_mov_b32_e32 v4, v229
	v_mov_b32_e32 v5, v230
	v_pk_mul_f32 v[4:5], v[74:75], v[4:5]
	s_waitcnt lgkmcnt(3)
	v_mov_b32_e32 v22, v243
	v_sub_f32_e32 v4, v8, v4
	v_sub_f32_e32 v6, v4, v5
	v_mov_b32_e32 v4, v231
	ds_read_b128 v[228:231], v2 offset:7168
	v_mov_b32_e32 v5, v240
	v_pk_mul_f32 v[4:5], v[78:79], v[4:5]
	v_cmp_eq_u32_e32 vcc, 28, v185
	v_sub_f32_e32 v4, v6, v4
	v_sub_f32_e32 v8, v4, v5
	v_mov_b32_e32 v4, v241
	v_mov_b32_e32 v5, v242
	ds_read_b128 v[240:243], v2 offset:7184
	v_pk_mul_f32 v[12:13], v[82:83], v[4:5]
	v_sub_f32_e32 v8, v8, v12
	v_sub_f32_e32 v8, v8, v13
	v_mov_b32_e32 v106, v235
	s_waitcnt lgkmcnt(4)
	v_mov_b32_e32 v23, v216
	v_pk_mul_f32 v[22:23], v[86:87], v[22:23]
	v_mov_b32_e32 v102, v73
	v_sub_f32_e32 v4, v8, v22
	v_sub_f32_e32 v8, v4, v23
	v_mov_b32_e32 v4, v217
	v_mov_b32_e32 v5, v218
	v_pk_mul_f32 v[4:5], v[90:91], v[4:5]
	s_waitcnt lgkmcnt(3)
	v_mov_b32_e32 v10, v213
	v_sub_f32_e32 v4, v8, v4
	v_sub_f32_e32 v6, v4, v5
	v_mov_b32_e32 v4, v219
	ds_read_b128 v[216:219], v2 offset:7200
	v_mov_b32_e32 v5, v212
	v_pk_mul_f32 v[4:5], v[94:95], v[4:5]
	v_mov_b32_e32 v7, v20
	v_sub_f32_e32 v4, v6, v4
	v_sub_f32_e32 v4, v4, v5
	v_mov_b32_e32 v5, v68
	v_mul_f32_e32 v6, v71, v214
	v_pk_fma_f32 v[4:5], v[68:69], v[10:11], v[4:5] op_sel:[1,0,0] neg_lo:[1,0,0] neg_hi:[1,0,0]
	v_mul_f32_e32 v12, v73, v215
	ds_read_b128 v[212:215], v2 offset:7216
	v_pk_add_f32 v[4:5], v[4:5], v[6:7] neg_lo:[0,1] neg_hi:[0,1]
	v_mov_b32_e32 v13, v21
	v_pk_add_f32 v[74:75], v[4:5], v[12:13] neg_lo:[0,1] neg_hi:[0,1]
	v_cndmask_b32_e64 v8, 0, 1.0, vcc
	v_mov_b32_e32 v103, v75
	v_pk_mul_f32 v[20:21], v[106:107], v[102:103]
	s_waitcnt lgkmcnt(4)
	v_mov_b32_e32 v113, v190
	s_waitcnt lgkmcnt(3)
	v_fma_f32 v4, -v30, v228, v8
	v_fma_f32 v4, -v29, v229, v4
	v_fma_f32 v4, -v27, v230, v4
	v_fma_f32 v8, -v33, v231, v4
	ds_read_b128 v[228:231], v2 offset:7232
	s_waitcnt lgkmcnt(3)
	v_fma_f32 v8, -v35, v240, v8
	v_fma_f32 v8, -v37, v241, v8
	v_fma_f32 v8, -v39, v242, v8
	v_fma_f32 v8, -v41, v243, v8
	s_waitcnt lgkmcnt(2)
	v_fma_f32 v4, -v43, v216, v8
	v_fma_f32 v8, -v45, v217, v4
	v_pk_mul_f32 v[4:5], v[76:77], v[218:219]
	v_pk_mov_b32 v[18:19], v[70:71], v[234:235] op_sel:[1,0]
	v_sub_f32_e32 v4, v8, v4
	v_sub_f32_e32 v8, v4, v5
	s_waitcnt lgkmcnt(1)
	v_pk_mul_f32 v[12:13], v[80:81], v[212:213]
	v_mov_b32_e32 v23, v20
	v_sub_f32_e32 v8, v8, v12
	v_sub_f32_e32 v8, v8, v13
	v_pk_mul_f32 v[12:13], v[84:85], v[214:215]
	s_waitcnt lgkmcnt(0)
	v_pk_mul_f32 v[4:5], v[88:89], v[228:229]
	v_sub_f32_e32 v8, v8, v12
	v_sub_f32_e32 v8, v8, v13
	ds_read_b128 v[12:15], v2 offset:7248
	v_sub_f32_e32 v4, v8, v4
	v_sub_f32_e32 v8, v4, v5
	v_pk_mul_f32 v[4:5], v[92:93], v[230:231]
	v_mov_b32_e32 v25, v21
	v_sub_f32_e32 v4, v8, v4
	v_sub_f32_e32 v8, v4, v5
	ds_read_b128 v[4:7], v2 offset:7264
	ds_read_b128 v[240:243], v2 offset:7424
	ds_read_b128 v[216:219], v2 offset:7440
	ds_read_b128 v[232:235], v2 offset:7456
	ds_read_b128 v[212:215], v2 offset:7472
	ds_read_b128 v[228:231], v2 offset:7488
	s_waitcnt lgkmcnt(6)
	v_pk_mul_f32 v[12:13], v[96:97], v[12:13]
	v_mul_f32_e32 v22, v73, v15
	v_sub_f32_e32 v8, v8, v12
	v_sub_f32_e32 v12, v8, v13
	v_mov_b32_e32 v15, v71
	v_mov_b32_e32 v13, v70
	v_pk_fma_f32 v[12:13], v[18:19], v[14:15], v[12:13] neg_lo:[1,0,0] neg_hi:[1,0,0]
	s_waitcnt lgkmcnt(5)
	v_mul_f32_e32 v24, v75, v4
	v_pk_add_f32 v[12:13], v[12:13], v[22:23] neg_lo:[0,1] neg_hi:[0,1]
	v_mov_b32_e32 v104, v75
	v_pk_add_f32 v[76:77], v[12:13], v[24:25] neg_lo:[0,1] neg_hi:[0,1]
	v_mov_b32_e32 v105, v77
	v_cmp_eq_u32_e32 vcc, 29, v185
	v_pk_mul_f32 v[20:21], v[16:17], v[104:105]
	s_nop 0
	v_cndmask_b32_e64 v4, 0, 1.0, vcc
	s_waitcnt lgkmcnt(4)
	v_fma_f32 v4, -v30, v240, v4
	v_fma_f32 v4, -v29, v241, v4
	v_fma_f32 v4, -v27, v242, v4
	v_fma_f32 v4, -v33, v243, v4
	ds_read_b128 v[240:243], v2 offset:7504
	s_waitcnt lgkmcnt(4)
	v_fma_f32 v4, -v35, v216, v4
	v_fma_f32 v4, -v37, v217, v4
	v_fma_f32 v4, -v39, v218, v4
	v_fma_f32 v4, -v41, v219, v4
	ds_read_b128 v[216:219], v2 offset:7520
	v_mov_b32_e32 v8, v73
	s_waitcnt lgkmcnt(4)
	v_fma_f32 v4, -v43, v232, v4
	v_fma_f32 v4, -v45, v233, v4
	v_mov_b32_e32 v12, v235
	s_waitcnt lgkmcnt(3)
	v_mov_b32_e32 v13, v212
	v_fma_f32 v4, -v47, v234, v4
	ds_read_b128 v[232:235], v2 offset:7696
	v_pk_mul_f32 v[12:13], v[78:79], v[12:13]
	v_mov_b32_e32 v22, v215
	v_sub_f32_e32 v4, v4, v12
	v_sub_f32_e32 v4, v4, v13
	v_mov_b32_e32 v12, v213
	v_mov_b32_e32 v13, v214
	ds_read_b128 v[212:215], v2 offset:7712
	v_pk_mul_f32 v[16:17], v[82:83], v[12:13]
	v_sub_f32_e32 v4, v4, v16
	v_sub_f32_e32 v4, v4, v17
	v_cmp_eq_u32_e32 vcc, 30, v185
	s_waitcnt lgkmcnt(4)
; #define LAS __attribute__((address_space(3)))
; __device__ __forceinline__ void dk_phase(const Frame& F, const bf16* QKrm, const unsigned char* KT, const unsigned char* VT, const float* BG, unsigned char* ITEMS) {
;     ...
;         float t[64];
; #pragma unroll
;         for (int r = 0; r < 64; ++r) {
;             float acc = (lane == r) ? 1.f : 0.f;
; #pragma unroll
;             for (int s4 = 0; s4 < (r + 3) / 4; ++s4) { const f32x4 a = *(const LAS f32x4*)(Amat + r * 64 + 4 * s4);
;                 if (4 * s4 + 0 < r) acc -= a.x * t[4 * s4 + 0]; if (4 * s4 + 1 < r) acc -= a.y * t[4 * s4 + 1];
;                 if (4 * s4 + 2 < r) acc -= a.z * t[4 * s4 + 2]; if (4 * s4 + 3 < r) acc -= a.w * t[4 * s4 + 3]; }
;             t[r] = acc;
;         }
	v_mov_b32_e32 v23, v228
	v_pk_mul_f32 v[22:23], v[86:87], v[22:23]
	v_mov_b32_e32 v12, v229
	v_sub_f32_e32 v4, v4, v22
	v_mov_b32_e32 v13, v230
	v_sub_f32_e32 v4, v4, v23
	v_pk_mul_f32 v[12:13], v[90:91], v[12:13]
	s_waitcnt lgkmcnt(3)
	v_mov_b32_e32 v22, v243
	v_sub_f32_e32 v4, v4, v12
	v_sub_f32_e32 v4, v4, v13
	v_mov_b32_e32 v12, v231
	ds_read_b128 v[228:231], v2 offset:7728
	v_mov_b32_e32 v13, v240
	v_pk_mul_f32 v[12:13], v[94:95], v[12:13]
	v_mov_b32_e32 v23, v73
	v_sub_f32_e32 v4, v4, v12
	v_mov_b32_e32 v12, v241
	v_sub_f32_e32 v4, v4, v13
	v_mov_b32_e32 v13, v242
	ds_read_b128 v[240:243], v2 offset:7744
	v_pk_mul_f32 v[12:13], v[98:99], v[12:13]
	v_mov_b32_e32 v19, v21
	v_sub_f32_e32 v4, v4, v12
	v_sub_f32_e32 v12, v4, v13
	v_mov_b32_e32 v13, v72
	s_waitcnt lgkmcnt(4)
	v_mul_f32_e32 v14, v75, v216
	v_mul_f32_e32 v18, v77, v217
	v_pk_fma_f32 v[8:9], v[8:9], v[22:23], v[12:13] neg_lo:[1,0,0] neg_hi:[1,0,0]
	v_mov_b32_e32 v15, v20
	v_pk_add_f32 v[8:9], v[8:9], v[14:15] neg_lo:[0,1] neg_hi:[0,1]
	v_cndmask_b32_e64 v4, 0, 1.0, vcc
	v_fma_f32 v4, -v30, v236, v4
	v_fma_f32 v4, -v29, v237, v4
	v_fma_f32 v4, -v27, v238, v4
	v_pk_add_f32 v[78:79], v[8:9], v[18:19] neg_lo:[0,1] neg_hi:[0,1]
	v_fma_f32 v4, -v33, v239, v4
	ds_read_b128 v[236:239], v2 offset:7760
	s_waitcnt lgkmcnt(4)
	v_fma_f32 v4, -v35, v232, v4
	v_fma_f32 v4, -v37, v233, v4
	v_fma_f32 v4, -v39, v234, v4
	v_fma_f32 v4, -v41, v235, v4
	s_waitcnt lgkmcnt(3)
	v_fma_f32 v4, -v43, v212, v4
	v_fma_f32 v4, -v45, v213, v4
	v_fma_f32 v4, -v47, v214, v4
	v_fma_f32 v4, -v49, v215, v4
	s_waitcnt lgkmcnt(2)
	v_pk_mul_f32 v[12:13], v[80:81], v[228:229]
	v_sub_f32_e32 v4, v4, v12
	v_sub_f32_e32 v4, v4, v13
	v_pk_mul_f32 v[12:13], v[84:85], v[230:231]
	ds_read2_b64 v[22:25], v31 offset0:174 offset1:206
	v_sub_f32_e32 v4, v4, v12
	v_sub_f32_e32 v4, v4, v13
	s_waitcnt lgkmcnt(2)
	v_pk_mul_f32 v[12:13], v[88:89], v[240:241]
	s_waitcnt lgkmcnt(1)
	v_pk_mul_f32 v[18:19], v[96:97], v[236:237]
	v_sub_f32_e32 v4, v4, v12
	v_sub_f32_e32 v4, v4, v13
	v_pk_mul_f32 v[12:13], v[92:93], v[242:243]
	v_mov_b32_e32 v112, v189
	v_sub_f32_e32 v4, v4, v12
	v_sub_f32_e32 v4, v4, v13
	ds_read_b128 v[12:15], v2 offset:7776
	ds_read_b128 v[232:235], v2 offset:7936
	ds_read_b128 v[212:215], v2 offset:7952
	ds_read_b128 v[228:231], v2 offset:7968
	ds_read_b128 v[240:243], v2 offset:7984
	v_sub_f32_e32 v4, v4, v18
	v_sub_f32_e32 v4, v4, v19
	v_pk_mul_f32 v[18:19], v[100:101], v[238:239]
	ds_read_b128 v[236:239], v2 offset:8000
	v_mov_b32_e32 v106, v77
	v_mov_b32_e32 v107, v79
	v_sub_f32_e32 v4, v4, v18
	v_pk_mul_f32 v[8:9], v[112:113], v[106:107]
	v_sub_f32_e32 v18, v4, v19
	s_waitcnt lgkmcnt(5)
	v_mul_f32_e32 v20, v77, v13
	v_mov_b32_e32 v13, v188
	ds_read_b128 v[188:191], v2 offset:8016
	v_mov_b32_e32 v19, v74
	v_pk_fma_f32 v[10:11], v[74:75], v[12:13], v[18:19] op_sel:[1,0,0] neg_lo:[1,0,0] neg_hi:[1,0,0]
	v_mov_b32_e32 v21, v8
	v_mov_b32_e32 v113, v22
	v_mul_f32_e32 v22, v79, v14
	v_pk_add_f32 v[10:11], v[10:11], v[20:21] neg_lo:[0,1] neg_hi:[0,1]
	v_mov_b32_e32 v23, v9
	v_pk_add_f32 v[80:81], v[10:11], v[22:23] neg_lo:[0,1] neg_hi:[0,1]
	v_cmp_eq_u32_e32 vcc, 31, v185
	v_mov_b32_e32 v108, v79
	s_nop 0
	v_cndmask_b32_e64 v4, 0, 1.0, vcc
	s_waitcnt lgkmcnt(5)
	v_fma_f32 v4, -v30, v232, v4
	v_fma_f32 v4, -v29, v233, v4
	v_mov_b32_e32 v109, v81
	v_fma_f32 v4, -v27, v234, v4
	v_pk_mul_f32 v[110:111], v[6:7], v[108:109]
	v_fma_f32 v4, -v33, v235, v4
	ds_read_b128 v[232:235], v2 offset:8048
	s_waitcnt lgkmcnt(5)
	v_fma_f32 v4, -v35, v212, v4
	v_fma_f32 v4, -v37, v213, v4
	v_fma_f32 v4, -v39, v214, v4
	v_fma_f32 v4, -v41, v215, v4
	ds_read_b128 v[212:215], v2 offset:8032
	s_waitcnt lgkmcnt(5)
	v_fma_f32 v4, -v43, v228, v4
	v_fma_f32 v4, -v45, v229, v4
	v_fma_f32 v4, -v47, v230, v4
	v_fma_f32 v4, -v49, v231, v4
	ds_read_b128 v[228:231], v2 offset:8192
	s_waitcnt lgkmcnt(5)
	v_mov_b32_e32 v6, v241
	v_mov_b32_e32 v7, v242
	v_fma_f32 v4, -v51, v240, v4
	v_pk_mul_f32 v[10:11], v[82:83], v[6:7]
	v_sub_f32_e32 v4, v4, v10
	v_sub_f32_e32 v4, v4, v11
	v_mov_b32_e32 v18, v243
	ds_read_b128 v[240:243], v2 offset:8208
	s_waitcnt lgkmcnt(5)
	v_mov_b32_e32 v19, v236
	v_pk_mul_f32 v[18:19], v[86:87], v[18:19]
	v_mov_b32_e32 v6, v237
	v_sub_f32_e32 v4, v4, v18
	v_mov_b32_e32 v7, v238
	v_sub_f32_e32 v4, v4, v19
	v_pk_mul_f32 v[6:7], v[90:91], v[6:7]
	v_cmp_eq_u32_e32 vcc, 32, v185
	v_sub_f32_e32 v4, v4, v6
	v_sub_f32_e32 v4, v4, v7
	v_mov_b32_e32 v6, v239
	ds_read_b128 v[236:239], v2 offset:8224
	s_waitcnt lgkmcnt(5)
	v_mov_b32_e32 v7, v188
	v_pk_mul_f32 v[6:7], v[94:95], v[6:7]
	v_sub_f32_e32 v4, v4, v6
	v_sub_f32_e32 v4, v4, v7
	v_mov_b32_e32 v6, v189
	v_mov_b32_e32 v7, v190
	v_pk_mul_f32 v[10:11], v[98:99], v[6:7]
	v_sub_f32_e32 v4, v4, v10
	v_sub_f32_e32 v4, v4, v11
	v_mov_b32_e32 v10, v191
	ds_read_b128 v[188:191], v2 offset:8240
	v_cndmask_b32_e64 v12, 0, 1.0, vcc
	s_waitcnt lgkmcnt(4)
	v_mov_b32_e32 v11, v212
	v_pk_mul_f32 v[10:11], v[102:103], v[10:11]
	v_mul_f32_e32 v8, v79, v214
	v_sub_f32_e32 v4, v4, v10
	v_sub_f32_e32 v6, v4, v11
	v_mov_b32_e32 v4, v213
	v_mov_b32_e32 v7, v76
	v_mul_f32_e32 v10, v81, v215
	ds_read_b128 v[212:215], v2 offset:8256
	v_pk_fma_f32 v[4:5], v[76:77], v[4:5], v[6:7] op_sel:[1,0,0] neg_lo:[1,0,0] neg_hi:[1,0,0]
	v_mov_b32_e32 v9, v110
	v_pk_add_f32 v[4:5], v[4:5], v[8:9] neg_lo:[0,1] neg_hi:[0,1]
	v_mov_b32_e32 v11, v111
	v_pk_add_f32 v[82:83], v[4:5], v[10:11] neg_lo:[0,1] neg_hi:[0,1]
	v_mov_b32_e32 v112, v219
	v_mov_b32_e32 v110, v81
	v_mov_b32_e32 v111, v83
	s_waitcnt lgkmcnt(4)
	v_fma_f32 v4, -v30, v228, v12
	v_fma_f32 v4, -v29, v229, v4
	v_fma_f32 v4, -v27, v230, v4
	v_fma_f32 v4, -v33, v231, v4
	ds_read_b128 v[228:231], v2 offset:8272
	s_waitcnt lgkmcnt(4)
; #define LAS __attribute__((address_space(3)))
; __device__ __forceinline__ void dk_phase(const Frame& F, const bf16* QKrm, const unsigned char* KT, const unsigned char* VT, const float* BG, unsigned char* ITEMS) {
;     ...
;         float t[64];
; #pragma unroll
;         for (int r = 0; r < 64; ++r) {
;             float acc = (lane == r) ? 1.f : 0.f;
; #pragma unroll
;             for (int s4 = 0; s4 < (r + 3) / 4; ++s4) { const f32x4 a = *(const LAS f32x4*)(Amat + r * 64 + 4 * s4);
;                 if (4 * s4 + 0 < r) acc -= a.x * t[4 * s4 + 0]; if (4 * s4 + 1 < r) acc -= a.y * t[4 * s4 + 1];
;                 if (4 * s4 + 2 < r) acc -= a.z * t[4 * s4 + 2]; if (4 * s4 + 3 < r) acc -= a.w * t[4 * s4 + 3]; }
;             t[r] = acc;
;         }
	v_fma_f32 v8, -v35, v240, v4
	v_fma_f32 v8, -v37, v241, v8
	v_fma_f32 v8, -v39, v242, v8
	v_fma_f32 v12, -v41, v243, v8
	s_waitcnt lgkmcnt(3)
	v_fma_f32 v4, -v43, v236, v12
	v_fma_f32 v4, -v45, v237, v4
	v_fma_f32 v4, -v47, v238, v4
	v_fma_f32 v4, -v49, v239, v4
	s_waitcnt lgkmcnt(2)
	v_fma_f32 v4, -v51, v188, v4
	v_fma_f32 v12, -v53, v189, v4
	v_pk_mul_f32 v[8:9], v[84:85], v[190:191]
	v_pk_mul_f32 v[18:19], v[112:113], v[110:111]
	v_sub_f32_e32 v8, v12, v8
	v_sub_f32_e32 v12, v8, v9
	s_waitcnt lgkmcnt(1)
	v_pk_mul_f32 v[4:5], v[88:89], v[212:213]
	v_pk_mov_b32 v[16:17], v[78:79], v[218:219] op_sel:[1,0]
	v_sub_f32_e32 v4, v12, v4
	v_sub_f32_e32 v12, v4, v5
	v_pk_mul_f32 v[4:5], v[92:93], v[214:215]
	v_mov_b32_e32 v117, v234
	v_sub_f32_e32 v4, v12, v4
	v_sub_f32_e32 v6, v4, v5
	s_waitcnt lgkmcnt(0)
	v_pk_mul_f32 v[4:5], v[96:97], v[228:229]
	v_pk_mul_f32 v[8:9], v[100:101], v[230:231]
	v_sub_f32_e32 v4, v6, v4
	v_sub_f32_e32 v12, v4, v5
	ds_read_b128 v[4:7], v2 offset:8288
	v_sub_f32_e32 v8, v12, v8
	ds_read_b128 v[10:13], v2 offset:8304
	ds_read_b128 v[240:243], v2 offset:8448
	ds_read_b128 v[236:239], v2 offset:8464
	ds_read_b128 v[188:191], v2 offset:8480
	ds_read_b128 v[216:219], v2 offset:8496
	ds_read_b128 v[212:215], v2 offset:8512
	ds_read_b128 v[228:231], v2 offset:8528
	v_sub_f32_e32 v8, v8, v9
	v_mov_b32_e32 v9, v18
	s_waitcnt lgkmcnt(7)
	v_pk_mul_f32 v[4:5], v[104:105], v[4:5]
	v_mov_b32_e32 v23, v19
	v_sub_f32_e32 v4, v8, v4
	v_sub_f32_e32 v4, v4, v5
	v_mul_f32_e32 v8, v81, v7
	v_mov_b32_e32 v7, v79
	v_mov_b32_e32 v5, v78
	v_pk_fma_f32 v[4:5], v[16:17], v[6:7], v[4:5] neg_lo:[1,0,0] neg_hi:[1,0,0]
	s_waitcnt lgkmcnt(6)
	v_mul_f32_e32 v22, v83, v10
	v_pk_add_f32 v[4:5], v[4:5], v[8:9] neg_lo:[0,1] neg_hi:[0,1]
	v_cmp_eq_u32_e32 vcc, 33, v185
	v_pk_add_f32 v[84:85], v[4:5], v[22:23] neg_lo:[0,1] neg_hi:[0,1]
	s_nop 0
	v_cndmask_b32_e64 v10, 0, 1.0, vcc
	v_mov_b32_e32 v112, v83
	v_mov_b32_e32 v113, v85
	s_waitcnt lgkmcnt(5)
	v_fma_f32 v4, -v30, v240, v10
	v_fma_f32 v4, -v29, v241, v4
	v_fma_f32 v4, -v27, v242, v4
	v_fma_f32 v4, -v33, v243, v4
	ds_read_b128 v[240:243], v2 offset:8544
	s_waitcnt lgkmcnt(5)
	v_fma_f32 v10, -v35, v236, v4
	v_fma_f32 v10, -v37, v237, v10
	v_fma_f32 v10, -v39, v238, v10
	v_fma_f32 v10, -v41, v239, v10
	ds_read_b128 v[236:239], v2 offset:8560
	s_waitcnt lgkmcnt(5)
	v_fma_f32 v4, -v43, v188, v10
	v_fma_f32 v4, -v45, v189, v4
	v_fma_f32 v4, -v47, v190, v4
	v_fma_f32 v4, -v49, v191, v4
	ds_read_b128 v[188:191], v2 offset:8704
	s_waitcnt lgkmcnt(5)
	v_fma_f32 v10, -v51, v216, v4
	v_fma_f32 v10, -v53, v217, v10
	v_mov_b32_e32 v22, v219
	v_fma_f32 v10, -v55, v218, v10
	ds_read_b128 v[216:219], v2 offset:8720
	s_waitcnt lgkmcnt(5)
	v_mov_b32_e32 v23, v212
	v_pk_mul_f32 v[22:23], v[86:87], v[22:23]
	v_pk_mul_f32 v[8:9], v[24:25], v[112:113]
	v_sub_f32_e32 v4, v10, v22
	v_sub_f32_e32 v10, v4, v23
	v_mov_b32_e32 v4, v213
	v_mov_b32_e32 v5, v214
	v_pk_mul_f32 v[4:5], v[90:91], v[4:5]
	s_waitcnt lgkmcnt(4)
	v_mov_b32_e32 v22, v231
	v_sub_f32_e32 v4, v10, v4
	v_sub_f32_e32 v6, v4, v5
	v_mov_b32_e32 v4, v215
	ds_read_b128 v[212:215], v2 offset:8736
	v_mov_b32_e32 v5, v228
	v_pk_mul_f32 v[4:5], v[94:95], v[4:5]
	v_mov_b32_e32 v14, v81
	v_sub_f32_e32 v4, v6, v4
	v_sub_f32_e32 v10, v4, v5
	v_mov_b32_e32 v4, v229
	v_mov_b32_e32 v5, v230
	ds_read_b128 v[228:231], v2 offset:8752
	v_pk_mul_f32 v[16:17], v[98:99], v[4:5]
	v_sub_f32_e32 v10, v10, v16
	v_sub_f32_e32 v10, v10, v17
	v_cmp_eq_u32_e32 vcc, 34, v185
	s_waitcnt lgkmcnt(5)
	v_mov_b32_e32 v23, v240
	v_pk_mul_f32 v[22:23], v[102:103], v[22:23]
	v_mov_b32_e32 v116, v233
	v_sub_f32_e32 v4, v10, v22
	v_sub_f32_e32 v10, v4, v23
	v_mov_b32_e32 v4, v241
	v_mov_b32_e32 v5, v242
	v_pk_mul_f32 v[4:5], v[106:107], v[4:5]
	v_mov_b32_e32 v22, v243
	ds_read_b128 v[240:243], v2 offset:8768
	v_sub_f32_e32 v4, v10, v4
	v_sub_f32_e32 v4, v4, v5
	v_mov_b32_e32 v23, v81
	v_mov_b32_e32 v5, v80
	s_waitcnt lgkmcnt(5)
	v_mul_f32_e32 v6, v83, v236
	v_pk_fma_f32 v[4:5], v[14:15], v[22:23], v[4:5] neg_lo:[1,0,0] neg_hi:[1,0,0]
	v_mov_b32_e32 v7, v8
	v_mul_f32_e32 v16, v85, v237
	v_pk_add_f32 v[4:5], v[4:5], v[6:7] neg_lo:[0,1] neg_hi:[0,1]
	v_mov_b32_e32 v17, v9
	v_pk_add_f32 v[86:87], v[4:5], v[16:17] neg_lo:[0,1] neg_hi:[0,1]
	v_cndmask_b32_e64 v8, 0, 1.0, vcc
	v_mov_b32_e32 v114, v85
	v_mov_b32_e32 v115, v87
	s_waitcnt lgkmcnt(4)
	v_fma_f32 v4, -v30, v188, v8
	v_fma_f32 v4, -v29, v189, v4
	v_fma_f32 v4, -v27, v190, v4
	v_fma_f32 v4, -v33, v191, v4
	ds_read_b128 v[188:191], v2 offset:8784
	s_waitcnt lgkmcnt(4)
	v_fma_f32 v8, -v35, v216, v4
	v_fma_f32 v8, -v37, v217, v8
	v_fma_f32 v8, -v39, v218, v8
	v_fma_f32 v8, -v41, v219, v8
	ds_read_b128 v[216:219], v2 offset:8800
	s_waitcnt lgkmcnt(4)
	v_fma_f32 v4, -v43, v212, v8
	v_fma_f32 v4, -v45, v213, v4
	v_fma_f32 v4, -v47, v214, v4
	v_fma_f32 v4, -v49, v215, v4
	s_waitcnt lgkmcnt(3)
	v_fma_f32 v8, -v51, v228, v4
	v_fma_f32 v8, -v53, v229, v8
	v_fma_f32 v8, -v55, v230, v8
	v_fma_f32 v8, -v57, v231, v8
	s_waitcnt lgkmcnt(2)
	v_pk_mul_f32 v[4:5], v[88:89], v[240:241]
	v_pk_mul_f32 v[120:121], v[116:117], v[114:115]
	v_sub_f32_e32 v4, v8, v4
	v_sub_f32_e32 v8, v4, v5
	v_pk_mul_f32 v[4:5], v[92:93], v[242:243]
	v_sub_f32_e32 v4, v8, v4
	v_sub_f32_e32 v6, v4, v5
	s_waitcnt lgkmcnt(1)
	v_pk_mul_f32 v[4:5], v[96:97], v[188:189]
	v_add_u32_e32 v31, 0x2000, v2
	v_sub_f32_e32 v4, v6, v4
	v_sub_f32_e32 v6, v4, v5
	v_pk_mul_f32 v[4:5], v[100:101], v[190:191]
	ds_read2_b64 v[14:17], v31 offset0:48 offset1:80
	v_sub_f32_e32 v4, v6, v4
	ds_read_b128 v[6:9], v2 offset:8816
	ds_read_b128 v[212:215], v2 offset:8960
	ds_read_b128 v[228:231], v2 offset:8976
	ds_read_b128 v[240:243], v2 offset:8992
	ds_read_b128 v[188:191], v2 offset:9008
	v_sub_f32_e32 v10, v4, v5
	s_waitcnt lgkmcnt(6)
; #define LAS __attribute__((address_space(3)))
; __device__ __forceinline__ void dk_phase(const Frame& F, const bf16* QKrm, const unsigned char* KT, const unsigned char* VT, const float* BG, unsigned char* ITEMS) {
;     ...
;         float t[64];
; #pragma unroll
;         for (int r = 0; r < 64; ++r) {
;             float acc = (lane == r) ? 1.f : 0.f;
; #pragma unroll
;             for (int s4 = 0; s4 < (r + 3) / 4; ++s4) { const f32x4 a = *(const LAS f32x4*)(Amat + r * 64 + 4 * s4);
;                 if (4 * s4 + 0 < r) acc -= a.x * t[4 * s4 + 0]; if (4 * s4 + 1 < r) acc -= a.y * t[4 * s4 + 1];
;                 if (4 * s4 + 2 < r) acc -= a.z * t[4 * s4 + 2]; if (4 * s4 + 3 < r) acc -= a.w * t[4 * s4 + 3]; }
;             t[r] = acc;
;         }
	v_pk_mul_f32 v[4:5], v[104:105], v[216:217]
	s_waitcnt lgkmcnt(5)
	v_mov_b32_e32 v123, v14
	v_sub_f32_e32 v4, v10, v4
	v_sub_f32_e32 v10, v4, v5
	v_pk_mul_f32 v[4:5], v[108:109], v[218:219]
	ds_read_b128 v[216:219], v2 offset:9024
	s_waitcnt lgkmcnt(5)
	v_mul_f32_e32 v14, v85, v7
	v_sub_f32_e32 v4, v10, v4
	v_sub_f32_e32 v4, v4, v5
	v_mov_b32_e32 v7, v232
	ds_read_b128 v[232:235], v2 offset:9040
	v_mov_b32_e32 v5, v82
	v_pk_fma_f32 v[4:5], v[82:83], v[6:7], v[4:5] op_sel:[1,0,0] neg_lo:[1,0,0] neg_hi:[1,0,0]
	v_mov_b32_e32 v15, v120
	v_mul_f32_e32 v22, v87, v8
	v_pk_add_f32 v[4:5], v[4:5], v[14:15] neg_lo:[0,1] neg_hi:[0,1]
	v_mov_b32_e32 v23, v121
	v_pk_add_f32 v[88:89], v[4:5], v[22:23] neg_lo:[0,1] neg_hi:[0,1]
	v_mov_b32_e32 v116, v87
	v_mov_b32_e32 v117, v89
	v_cmp_eq_u32_e32 vcc, 35, v185
	v_pk_mul_f32 v[20:21], v[12:13], v[116:117]
	s_nop 0
	v_cndmask_b32_e64 v8, 0, 1.0, vcc
	s_waitcnt lgkmcnt(5)
	v_fma_f32 v4, -v30, v212, v8
	v_fma_f32 v4, -v29, v213, v4
	v_fma_f32 v4, -v27, v214, v4
	v_fma_f32 v4, -v33, v215, v4
	ds_read_b128 v[212:215], v2 offset:9056
	s_waitcnt lgkmcnt(5)
	v_fma_f32 v8, -v35, v228, v4
	v_fma_f32 v8, -v37, v229, v8
	v_fma_f32 v8, -v39, v230, v8
	v_fma_f32 v8, -v41, v231, v8
	ds_read_b128 v[228:231], v2 offset:9072
	s_waitcnt lgkmcnt(5)
	v_fma_f32 v4, -v43, v240, v8
	v_fma_f32 v4, -v45, v241, v4
	v_fma_f32 v4, -v47, v242, v4
	v_fma_f32 v4, -v49, v243, v4
	ds_read_b128 v[240:243], v2 offset:9088
	s_waitcnt lgkmcnt(5)
	v_fma_f32 v8, -v51, v188, v4
	v_fma_f32 v8, -v53, v189, v8
	v_fma_f32 v8, -v55, v190, v8
	v_fma_f32 v8, -v57, v191, v8
	ds_read_b128 v[188:191], v2 offset:9216
	s_waitcnt lgkmcnt(5)
	v_fma_f32 v8, -v59, v216, v8
	v_mov_b32_e32 v4, v217
	v_mov_b32_e32 v5, v218
	v_pk_mul_f32 v[4:5], v[90:91], v[4:5]
	s_waitcnt lgkmcnt(4)
	v_mov_b32_e32 v22, v235
	v_sub_f32_e32 v4, v8, v4
	v_sub_f32_e32 v6, v4, v5
	v_mov_b32_e32 v4, v219
	ds_read_b128 v[216:219], v2 offset:9232
	v_mov_b32_e32 v5, v232
	v_pk_mul_f32 v[4:5], v[94:95], v[4:5]
	v_cmp_eq_u32_e32 vcc, 36, v185
	v_sub_f32_e32 v4, v6, v4
	v_sub_f32_e32 v8, v4, v5
	v_mov_b32_e32 v4, v233
	v_mov_b32_e32 v5, v234
	ds_read_b128 v[232:235], v2 offset:9248
	v_pk_mul_f32 v[12:13], v[98:99], v[4:5]
	v_sub_f32_e32 v8, v8, v12
	v_sub_f32_e32 v8, v8, v13
	v_mov_b32_e32 v122, v239
	s_waitcnt lgkmcnt(5)
	v_mov_b32_e32 v23, v212
	v_pk_mul_f32 v[22:23], v[102:103], v[22:23]
	v_mov_b32_e32 v118, v89
	v_sub_f32_e32 v4, v8, v22
	v_sub_f32_e32 v8, v4, v23
	v_mov_b32_e32 v4, v213
	v_mov_b32_e32 v5, v214
	v_pk_mul_f32 v[4:5], v[106:107], v[4:5]
	s_waitcnt lgkmcnt(4)
	v_mov_b32_e32 v10, v229
	v_sub_f32_e32 v4, v8, v4
	v_sub_f32_e32 v6, v4, v5
	v_mov_b32_e32 v4, v215
	ds_read_b128 v[212:215], v2 offset:9264
	v_mov_b32_e32 v5, v228
	v_pk_mul_f32 v[4:5], v[110:111], v[4:5]
	v_mov_b32_e32 v7, v20
	v_sub_f32_e32 v4, v6, v4
	v_sub_f32_e32 v4, v4, v5
	v_mov_b32_e32 v5, v84
	v_mul_f32_e32 v6, v87, v230
	v_pk_fma_f32 v[4:5], v[84:85], v[10:11], v[4:5] op_sel:[1,0,0] neg_lo:[1,0,0] neg_hi:[1,0,0]
	v_mul_f32_e32 v12, v89, v231
	ds_read_b128 v[228:231], v2 offset:9280
	v_pk_add_f32 v[4:5], v[4:5], v[6:7] neg_lo:[0,1] neg_hi:[0,1]
	v_mov_b32_e32 v13, v21
	v_pk_add_f32 v[90:91], v[4:5], v[12:13] neg_lo:[0,1] neg_hi:[0,1]
	v_cndmask_b32_e64 v8, 0, 1.0, vcc
	v_mov_b32_e32 v119, v91
	v_pk_mul_f32 v[22:23], v[122:123], v[118:119]
	s_waitcnt lgkmcnt(5)
	v_mov_b32_e32 v21, v242
	s_waitcnt lgkmcnt(4)
	v_fma_f32 v4, -v30, v188, v8
	v_fma_f32 v4, -v29, v189, v4
	v_fma_f32 v4, -v27, v190, v4
	v_fma_f32 v8, -v33, v191, v4
	ds_read_b128 v[188:191], v2 offset:9296
	s_waitcnt lgkmcnt(4)
	v_fma_f32 v8, -v35, v216, v8
	v_fma_f32 v8, -v37, v217, v8
	v_fma_f32 v8, -v39, v218, v8
	v_fma_f32 v8, -v41, v219, v8
	ds_read_b128 v[216:219], v2 offset:9312
	s_waitcnt lgkmcnt(4)
	v_fma_f32 v4, -v43, v232, v8
	v_fma_f32 v4, -v45, v233, v4
	v_fma_f32 v4, -v47, v234, v4
	v_fma_f32 v8, -v49, v235, v4
	s_waitcnt lgkmcnt(3)
	v_fma_f32 v8, -v51, v212, v8
	v_fma_f32 v8, -v53, v213, v8
	v_fma_f32 v8, -v55, v214, v8
	v_fma_f32 v8, -v57, v215, v8
	s_waitcnt lgkmcnt(2)
	v_fma_f32 v4, -v59, v228, v8
	v_fma_f32 v8, -v61, v229, v4
	v_pk_mul_f32 v[4:5], v[92:93], v[230:231]
	v_pk_mov_b32 v[18:19], v[86:87], v[238:239] op_sel:[1,0]
	v_sub_f32_e32 v4, v8, v4
	v_sub_f32_e32 v8, v4, v5
	s_waitcnt lgkmcnt(1)
	v_pk_mul_f32 v[12:13], v[96:97], v[188:189]
	v_mov_b32_e32 v25, v22
	v_sub_f32_e32 v8, v8, v12
	v_sub_f32_e32 v8, v8, v13
	v_pk_mul_f32 v[12:13], v[100:101], v[190:191]
	s_waitcnt lgkmcnt(0)
	v_pk_mul_f32 v[4:5], v[104:105], v[216:217]
	v_sub_f32_e32 v8, v8, v12
	v_sub_f32_e32 v8, v8, v13
	ds_read_b128 v[12:15], v2 offset:9328
	v_sub_f32_e32 v4, v8, v4
	v_sub_f32_e32 v8, v4, v5
	v_pk_mul_f32 v[4:5], v[108:109], v[218:219]
	v_mov_b32_e32 v93, v23
	v_sub_f32_e32 v4, v8, v4
	v_sub_f32_e32 v8, v4, v5
	ds_read_b128 v[4:7], v2 offset:9344
	ds_read_b128 v[232:235], v2 offset:9472
	ds_read_b128 v[212:215], v2 offset:9488
	ds_read_b128 v[228:231], v2 offset:9504
	ds_read_b128 v[236:239], v2 offset:9520
	ds_read_b128 v[188:191], v2 offset:9536
	ds_read_b128 v[216:219], v2 offset:9552
	s_waitcnt lgkmcnt(7)
	v_pk_mul_f32 v[12:13], v[112:113], v[12:13]
	v_mul_f32_e32 v24, v89, v15
	v_sub_f32_e32 v8, v8, v12
	v_sub_f32_e32 v12, v8, v13
	v_mov_b32_e32 v15, v87
	v_mov_b32_e32 v13, v86
	v_pk_fma_f32 v[12:13], v[18:19], v[14:15], v[12:13] neg_lo:[1,0,0] neg_hi:[1,0,0]
	s_waitcnt lgkmcnt(6)
	v_mul_f32_e32 v92, v91, v4
	v_pk_add_f32 v[12:13], v[12:13], v[24:25] neg_lo:[0,1] neg_hi:[0,1]
	v_mov_b32_e32 v120, v91
	v_pk_add_f32 v[92:93], v[12:13], v[92:93] neg_lo:[0,1] neg_hi:[0,1]
	v_mov_b32_e32 v121, v93
	v_cmp_eq_u32_e32 vcc, 37, v185
	v_pk_mul_f32 v[22:23], v[16:17], v[120:121]
	s_nop 0
	v_cndmask_b32_e64 v4, 0, 1.0, vcc
	s_waitcnt lgkmcnt(5)
; #define LAS __attribute__((address_space(3)))
; __device__ __forceinline__ void dk_phase(const Frame& F, const bf16* QKrm, const unsigned char* KT, const unsigned char* VT, const float* BG, unsigned char* ITEMS) {
;     ...
;         float t[64];
; #pragma unroll
;         for (int r = 0; r < 64; ++r) {
;             float acc = (lane == r) ? 1.f : 0.f;
; #pragma unroll
;             for (int s4 = 0; s4 < (r + 3) / 4; ++s4) { const f32x4 a = *(const LAS f32x4*)(Amat + r * 64 + 4 * s4);
;                 if (4 * s4 + 0 < r) acc -= a.x * t[4 * s4 + 0]; if (4 * s4 + 1 < r) acc -= a.y * t[4 * s4 + 1];
;                 if (4 * s4 + 2 < r) acc -= a.z * t[4 * s4 + 2]; if (4 * s4 + 3 < r) acc -= a.w * t[4 * s4 + 3]; }
;             t[r] = acc;
;         }
	v_fma_f32 v4, -v30, v232, v4
	v_fma_f32 v4, -v29, v233, v4
	v_fma_f32 v4, -v27, v234, v4
	v_fma_f32 v4, -v33, v235, v4
	ds_read_b128 v[232:235], v2 offset:9728
	s_waitcnt lgkmcnt(5)
	v_fma_f32 v4, -v35, v212, v4
	v_fma_f32 v4, -v37, v213, v4
	v_fma_f32 v4, -v39, v214, v4
	v_fma_f32 v4, -v41, v215, v4
	ds_read_b128 v[212:215], v2 offset:10880
	s_waitcnt lgkmcnt(5)
	v_fma_f32 v4, -v43, v228, v4
	v_fma_f32 v4, -v45, v229, v4
	v_fma_f32 v4, -v47, v230, v4
	v_fma_f32 v4, -v49, v231, v4
	ds_read_b128 v[228:231], v2 offset:9568
	s_waitcnt lgkmcnt(5)
	v_fma_f32 v4, -v51, v236, v4
	v_fma_f32 v4, -v53, v237, v4
	v_fma_f32 v4, -v55, v238, v4
	v_fma_f32 v4, -v57, v239, v4
	ds_read_b128 v[236:239], v2 offset:9584
	s_waitcnt lgkmcnt(5)
	v_fma_f32 v4, -v59, v188, v4
	v_fma_f32 v4, -v61, v189, v4
	v_mov_b32_e32 v12, v191
	s_waitcnt lgkmcnt(4)
	v_mov_b32_e32 v13, v216
	v_fma_f32 v4, -v63, v190, v4
	ds_read_b128 v[188:191], v2 offset:9600
	v_pk_mul_f32 v[12:13], v[94:95], v[12:13]
	v_mov_b32_e32 v24, v219
	v_sub_f32_e32 v4, v4, v12
	v_sub_f32_e32 v4, v4, v13
	v_mov_b32_e32 v12, v217
	v_mov_b32_e32 v13, v218
	ds_read_b128 v[216:219], v2 offset:9744
	v_pk_mul_f32 v[16:17], v[98:99], v[12:13]
	v_sub_f32_e32 v4, v4, v16
	v_sub_f32_e32 v4, v4, v17
	v_mov_b32_e32 v8, v89
	s_waitcnt lgkmcnt(3)
	v_mov_b32_e32 v25, v228
	v_pk_mul_f32 v[24:25], v[102:103], v[24:25]
	v_mov_b32_e32 v12, v229
	v_sub_f32_e32 v4, v4, v24
	v_mov_b32_e32 v13, v230
	v_sub_f32_e32 v4, v4, v25
	v_pk_mul_f32 v[12:13], v[106:107], v[12:13]
	s_waitcnt lgkmcnt(2)
	v_mov_b32_e32 v24, v239
	v_sub_f32_e32 v4, v4, v12
	v_sub_f32_e32 v4, v4, v13
	v_mov_b32_e32 v12, v231
	ds_read_b128 v[228:231], v2 offset:9760
	v_mov_b32_e32 v13, v236
	v_pk_mul_f32 v[12:13], v[110:111], v[12:13]
	v_mov_b32_e32 v25, v89
	v_sub_f32_e32 v4, v4, v12
	v_mov_b32_e32 v12, v237
	v_sub_f32_e32 v4, v4, v13
	v_mov_b32_e32 v13, v238
	ds_read_b128 v[236:239], v2 offset:9776
	v_pk_mul_f32 v[12:13], v[114:115], v[12:13]
	v_cmp_eq_u32_e32 vcc, 38, v185
	v_sub_f32_e32 v4, v4, v12
	v_sub_f32_e32 v12, v4, v13
	v_mov_b32_e32 v13, v88
	s_waitcnt lgkmcnt(3)
	v_mul_f32_e32 v14, v91, v188
	v_mul_f32_e32 v18, v93, v189
	v_pk_fma_f32 v[8:9], v[8:9], v[24:25], v[12:13] neg_lo:[1,0,0] neg_hi:[1,0,0]
	v_mov_b32_e32 v15, v22
	v_pk_add_f32 v[8:9], v[8:9], v[14:15] neg_lo:[0,1] neg_hi:[0,1]
	v_cndmask_b32_e64 v4, 0, 1.0, vcc
	v_mov_b32_e32 v19, v23
	v_fma_f32 v4, -v30, v232, v4
	v_pk_add_f32 v[94:95], v[8:9], v[18:19] neg_lo:[0,1] neg_hi:[0,1]
	v_fma_f32 v4, -v29, v233, v4
	v_mov_b32_e32 v20, v241
	v_mov_b32_e32 v122, v93
	v_mov_b32_e32 v123, v95
	v_fma_f32 v4, -v27, v234, v4
	v_pk_mul_f32 v[128:129], v[20:21], v[122:123]
	v_fma_f32 v4, -v33, v235, v4
	ds_read_b128 v[232:235], v2 offset:9792
	s_waitcnt lgkmcnt(3)
	v_fma_f32 v4, -v35, v216, v4
	v_fma_f32 v4, -v37, v217, v4
	v_fma_f32 v4, -v39, v218, v4
	v_fma_f32 v4, -v41, v219, v4
	ds_read_b128 v[216:219], v2 offset:9808
	s_waitcnt lgkmcnt(3)
	v_fma_f32 v4, -v43, v228, v4
	v_fma_f32 v4, -v45, v229, v4
	v_fma_f32 v4, -v47, v230, v4
	v_fma_f32 v4, -v49, v231, v4
	ds_read_b128 v[228:231], v2 offset:9824
	s_waitcnt lgkmcnt(3)
	v_fma_f32 v4, -v51, v236, v4
	v_fma_f32 v4, -v53, v237, v4
	v_fma_f32 v4, -v55, v238, v4
	v_fma_f32 v4, -v57, v239, v4
	ds_read_b128 v[236:239], v2 offset:9840
	s_waitcnt lgkmcnt(3)
	v_fma_f32 v4, -v59, v232, v4
	v_fma_f32 v4, -v61, v233, v4
	v_fma_f32 v4, -v63, v234, v4
	v_fma_f32 v4, -v65, v235, v4
	s_waitcnt lgkmcnt(2)
	v_pk_mul_f32 v[12:13], v[96:97], v[216:217]
	v_sub_f32_e32 v4, v4, v12
	v_sub_f32_e32 v4, v4, v13
	v_pk_mul_f32 v[12:13], v[100:101], v[218:219]
	ds_read2_b64 v[22:25], v31 offset0:178 offset1:210
	v_sub_f32_e32 v4, v4, v12
	v_sub_f32_e32 v4, v4, v13
	s_waitcnt lgkmcnt(2)
	v_pk_mul_f32 v[12:13], v[104:105], v[228:229]
	s_waitcnt lgkmcnt(1)
	v_pk_mul_f32 v[18:19], v[112:113], v[236:237]
	v_sub_f32_e32 v4, v4, v12
	v_sub_f32_e32 v4, v4, v13
	v_pk_mul_f32 v[12:13], v[108:109], v[230:231]
	v_mov_b32_e32 v21, v128
	v_sub_f32_e32 v4, v4, v12
	v_sub_f32_e32 v4, v4, v13
	ds_read_b128 v[12:15], v2 offset:9856
	ds_read_b128 v[232:235], v2 offset:9984
	ds_read_b128 v[216:219], v2 offset:10000
	ds_read_b128 v[228:231], v2 offset:10016
	v_sub_f32_e32 v4, v4, v18
	v_sub_f32_e32 v4, v4, v19
	v_pk_mul_f32 v[18:19], v[116:117], v[238:239]
	ds_read_b128 v[236:239], v2 offset:10032
	s_waitcnt lgkmcnt(5)
	v_mov_b32_e32 v9, v22
	v_sub_f32_e32 v4, v4, v18
	v_sub_f32_e32 v18, v4, v19
	s_waitcnt lgkmcnt(4)
	v_mul_f32_e32 v20, v93, v13
	v_mov_b32_e32 v13, v240
	ds_read_b128 v[240:243], v2 offset:10048
	v_mov_b32_e32 v19, v90
	v_pk_fma_f32 v[10:11], v[90:91], v[12:13], v[18:19] op_sel:[1,0,0] neg_lo:[1,0,0] neg_hi:[1,0,0]
	v_mul_f32_e32 v22, v95, v14
	v_pk_add_f32 v[10:11], v[10:11], v[20:21] neg_lo:[0,1] neg_hi:[0,1]
	v_mov_b32_e32 v23, v129
	v_pk_add_f32 v[96:97], v[10:11], v[22:23] neg_lo:[0,1] neg_hi:[0,1]
	v_cmp_eq_u32_e32 vcc, 39, v185
	v_mov_b32_e32 v124, v95
	s_nop 0
	v_cndmask_b32_e64 v4, 0, 1.0, vcc
	s_waitcnt lgkmcnt(4)
	v_fma_f32 v4, -v30, v232, v4
	v_fma_f32 v4, -v29, v233, v4
	v_fma_f32 v4, -v27, v234, v4
	v_fma_f32 v4, -v33, v235, v4
	ds_read_b128 v[232:235], v2 offset:10064
	s_waitcnt lgkmcnt(4)
	v_fma_f32 v4, -v35, v216, v4
	v_fma_f32 v4, -v37, v217, v4
	v_fma_f32 v4, -v39, v218, v4
	v_fma_f32 v4, -v41, v219, v4
	ds_read_b128 v[216:219], v2 offset:10080
	s_waitcnt lgkmcnt(4)
	v_fma_f32 v4, -v43, v228, v4
	v_fma_f32 v4, -v45, v229, v4
	v_fma_f32 v4, -v47, v230, v4
	v_fma_f32 v4, -v49, v231, v4
	ds_read_b128 v[228:231], v2 offset:10096
	s_waitcnt lgkmcnt(4)
	v_fma_f32 v4, -v51, v236, v4
	v_fma_f32 v4, -v53, v237, v4
	v_fma_f32 v4, -v55, v238, v4
	v_fma_f32 v4, -v57, v239, v4
	ds_read_b128 v[236:239], v2 offset:10112
	s_waitcnt lgkmcnt(4)
; #define LAS __attribute__((address_space(3)))
; __device__ __forceinline__ void dk_phase(const Frame& F, const bf16* QKrm, const unsigned char* KT, const unsigned char* VT, const float* BG, unsigned char* ITEMS) {
;     ...
; #pragma unroll
;         for (int r = 0; r < 64; ++r) {
;             float acc = (lane == r) ? 1.f : 0.f;
; #pragma unroll
;             for (int s4 = 0; s4 < (r + 3) / 4; ++s4) { const f32x4 a = *(const LAS f32x4*)(Amat + r * 64 + 4 * s4);
;                 if (4 * s4 + 0 < r) acc -= a.x * t[4 * s4 + 0]; if (4 * s4 + 1 < r) acc -= a.y * t[4 * s4 + 1];
;                 if (4 * s4 + 2 < r) acc -= a.z * t[4 * s4 + 2]; if (4 * s4 + 3 < r) acc -= a.w * t[4 * s4 + 3]; }
;             t[r] = acc;
;         }
	v_fma_f32 v4, -v59, v240, v4
	v_fma_f32 v4, -v61, v241, v4
	v_fma_f32 v4, -v63, v242, v4
	v_fma_f32 v4, -v65, v243, v4
	ds_read_b128 v[240:243], v2 offset:10240
	s_waitcnt lgkmcnt(4)
	v_mov_b32_e32 v10, v233
	v_mov_b32_e32 v11, v234
	v_fma_f32 v4, -v67, v232, v4
	v_pk_mul_f32 v[18:19], v[98:99], v[10:11]
	v_sub_f32_e32 v4, v4, v18
	v_sub_f32_e32 v4, v4, v19
	v_mov_b32_e32 v22, v235
	ds_read_b128 v[232:235], v2 offset:10256
	s_waitcnt lgkmcnt(4)
	v_mov_b32_e32 v23, v216
	v_pk_mul_f32 v[22:23], v[102:103], v[22:23]
	v_mov_b32_e32 v10, v217
	v_sub_f32_e32 v4, v4, v22
	v_mov_b32_e32 v11, v218
	v_sub_f32_e32 v4, v4, v23
	v_pk_mul_f32 v[10:11], v[106:107], v[10:11]
	v_mov_b32_e32 v125, v97
	v_sub_f32_e32 v4, v4, v10
	v_sub_f32_e32 v4, v4, v11
	v_mov_b32_e32 v10, v219
	ds_read_b128 v[216:219], v2 offset:10128
	s_waitcnt lgkmcnt(4)
	v_mov_b32_e32 v11, v228
	v_pk_mul_f32 v[10:11], v[110:111], v[10:11]
	v_pk_mul_f32 v[6:7], v[6:7], v[124:125]
	v_sub_f32_e32 v4, v4, v10
	v_sub_f32_e32 v4, v4, v11
	v_mov_b32_e32 v10, v229
	v_mov_b32_e32 v11, v230
	v_pk_mul_f32 v[18:19], v[114:115], v[10:11]
	v_sub_f32_e32 v4, v4, v18
	v_sub_f32_e32 v4, v4, v19
	v_mov_b32_e32 v18, v231
	ds_read_b128 v[228:231], v2 offset:10272
	v_mov_b32_e32 v8, v191
	s_waitcnt lgkmcnt(4)
	v_mov_b32_e32 v19, v236
	v_pk_mul_f32 v[18:19], v[118:119], v[18:19]
	v_mul_f32_e32 v12, v95, v238
	v_sub_f32_e32 v4, v4, v18
	v_sub_f32_e32 v10, v4, v19
	v_mov_b32_e32 v4, v237
	v_mov_b32_e32 v11, v92
	v_mul_f32_e32 v18, v97, v239
	ds_read_b128 v[236:239], v2 offset:10288
	v_pk_fma_f32 v[4:5], v[92:93], v[4:5], v[10:11] op_sel:[1,0,0] neg_lo:[1,0,0] neg_hi:[1,0,0]
	v_mov_b32_e32 v13, v6
	v_pk_add_f32 v[4:5], v[4:5], v[12:13] neg_lo:[0,1] neg_hi:[0,1]
	v_mov_b32_e32 v19, v7
	v_pk_add_f32 v[98:99], v[4:5], v[18:19] neg_lo:[0,1] neg_hi:[0,1]
	v_mov_b32_e32 v140, v97
	v_mov_b32_e32 v141, v99
	v_pk_mul_f32 v[18:19], v[8:9], v[140:141]
	v_cmp_eq_u32_e32 vcc, 40, v185
	s_nop 1
	v_cndmask_b32_e64 v14, 0, 1.0, vcc
	s_waitcnt lgkmcnt(4)
	v_fma_f32 v6, -v30, v240, v14
	v_fma_f32 v6, -v29, v241, v6
	v_fma_f32 v6, -v27, v242, v6
	v_fma_f32 v6, -v33, v243, v6
	ds_read_b128 v[240:243], v2 offset:10304
	s_waitcnt lgkmcnt(4)
	v_fma_f32 v10, -v35, v232, v6
	v_fma_f32 v10, -v37, v233, v10
	v_fma_f32 v10, -v39, v234, v10
	v_fma_f32 v14, -v41, v235, v10
	ds_read_b128 v[232:235], v2 offset:10320
	s_waitcnt lgkmcnt(3)
	v_fma_f32 v6, -v43, v228, v14
	v_fma_f32 v6, -v45, v229, v6
	v_fma_f32 v6, -v47, v230, v6
	v_fma_f32 v6, -v49, v231, v6
	ds_read_b128 v[228:231], v2 offset:10336
	s_waitcnt lgkmcnt(3)
	v_fma_f32 v10, -v51, v236, v6
	v_fma_f32 v10, -v53, v237, v10
	v_fma_f32 v10, -v55, v238, v10
	v_fma_f32 v14, -v57, v239, v10
	ds_read_b128 v[236:239], v2 offset:10352
	s_waitcnt lgkmcnt(3)
	v_fma_f32 v6, -v59, v240, v14
	v_fma_f32 v6, -v61, v241, v6
	v_fma_f32 v6, -v63, v242, v6
	v_fma_f32 v6, -v65, v243, v6
	s_waitcnt lgkmcnt(2)
	v_fma_f32 v6, -v67, v232, v6
	v_fma_f32 v14, -v69, v233, v6
	v_pk_mul_f32 v[10:11], v[100:101], v[234:235]
	v_mov_b32_e32 v5, v218
	v_sub_f32_e32 v10, v14, v10
	v_sub_f32_e32 v14, v10, v11
	s_waitcnt lgkmcnt(1)
	v_pk_mul_f32 v[6:7], v[104:105], v[228:229]
	v_pk_mov_b32 v[16:17], v[94:95], v[190:191] op_sel:[1,0]
	v_sub_f32_e32 v6, v14, v6
	v_sub_f32_e32 v14, v6, v7
	v_pk_mul_f32 v[6:7], v[108:109], v[230:231]
	v_mov_b32_e32 v23, v18
	v_sub_f32_e32 v6, v14, v6
	v_sub_f32_e32 v8, v6, v7
	s_waitcnt lgkmcnt(0)
	v_pk_mul_f32 v[6:7], v[112:113], v[236:237]
	v_pk_mul_f32 v[10:11], v[116:117], v[238:239]
	v_sub_f32_e32 v6, v8, v6
	v_sub_f32_e32 v14, v6, v7
	ds_read_b128 v[6:9], v2 offset:10368
	v_sub_f32_e32 v10, v14, v10
	v_sub_f32_e32 v14, v10, v11
	ds_read_b128 v[10:13], v2 offset:10384
	ds_read_b128 v[240:243], v2 offset:10496
	ds_read_b128 v[232:235], v2 offset:10512
	ds_read_b128 v[188:191], v2 offset:10528
	ds_read_b128 v[228:231], v2 offset:10544
	ds_read_b128 v[236:239], v2 offset:10560
	v_mov_b32_e32 v101, v19
	s_waitcnt lgkmcnt(6)
	v_pk_mul_f32 v[6:7], v[120:121], v[6:7]
	v_mul_f32_e32 v22, v97, v9
	v_sub_f32_e32 v6, v14, v6
	v_sub_f32_e32 v6, v6, v7
	v_mov_b32_e32 v9, v95
	v_mov_b32_e32 v7, v94
	v_pk_fma_f32 v[6:7], v[16:17], v[8:9], v[6:7] neg_lo:[1,0,0] neg_hi:[1,0,0]
	s_waitcnt lgkmcnt(5)
	v_mul_f32_e32 v100, v99, v10
	v_pk_add_f32 v[6:7], v[6:7], v[22:23] neg_lo:[0,1] neg_hi:[0,1]
	v_cmp_eq_u32_e32 vcc, 41, v185
	v_pk_add_f32 v[100:101], v[6:7], v[100:101] neg_lo:[0,1] neg_hi:[0,1]
	s_nop 0
	v_cndmask_b32_e64 v10, 0, 1.0, vcc
	v_mov_b32_e32 v144, v99
	v_mov_b32_e32 v145, v101
	s_waitcnt lgkmcnt(4)
	v_fma_f32 v6, -v30, v240, v10
	v_fma_f32 v6, -v29, v241, v6
	v_fma_f32 v6, -v27, v242, v6
	v_fma_f32 v6, -v33, v243, v6
	ds_read_b128 v[240:243], v2 offset:10576
	s_waitcnt lgkmcnt(4)
	v_fma_f32 v10, -v35, v232, v6
	v_fma_f32 v10, -v37, v233, v10
	v_fma_f32 v10, -v39, v234, v10
	v_fma_f32 v10, -v41, v235, v10
	ds_read_b128 v[232:235], v2 offset:10592
	s_waitcnt lgkmcnt(4)
	v_fma_f32 v6, -v43, v188, v10
	v_fma_f32 v6, -v45, v189, v6
	v_fma_f32 v6, -v47, v190, v6
	v_fma_f32 v6, -v49, v191, v6
	ds_read_b128 v[188:191], v2 offset:10608
	s_waitcnt lgkmcnt(4)
	v_fma_f32 v10, -v51, v228, v6
	v_fma_f32 v10, -v53, v229, v10
	v_fma_f32 v10, -v55, v230, v10
	v_fma_f32 v10, -v57, v231, v10
	ds_read_b128 v[228:231], v2 offset:10624
	s_waitcnt lgkmcnt(4)
	v_fma_f32 v6, -v59, v236, v10
	v_fma_f32 v6, -v61, v237, v6
	v_fma_f32 v6, -v63, v238, v6
	v_fma_f32 v6, -v65, v239, v6
	ds_read_b128 v[236:239], v2 offset:10640
	s_waitcnt lgkmcnt(4)
	v_fma_f32 v10, -v67, v240, v6
	v_pk_mul_f32 v[22:23], v[24:25], v[144:145]
	v_fma_f32 v10, -v69, v241, v10
	v_mov_b32_e32 v24, v243
	v_fma_f32 v10, -v71, v242, v10
	ds_read_b128 v[240:243], v2 offset:10768
	s_waitcnt lgkmcnt(4)
; #define LAS __attribute__((address_space(3)))
; __device__ __forceinline__ void dk_phase(const Frame& F, const bf16* QKrm, const unsigned char* KT, const unsigned char* VT, const float* BG, unsigned char* ITEMS) {
;     ...
; #pragma unroll
;         for (int r = 0; r < 64; ++r) {
;             float acc = (lane == r) ? 1.f : 0.f;
; #pragma unroll
;             for (int s4 = 0; s4 < (r + 3) / 4; ++s4) { const f32x4 a = *(const LAS f32x4*)(Amat + r * 64 + 4 * s4);
;                 if (4 * s4 + 0 < r) acc -= a.x * t[4 * s4 + 0]; if (4 * s4 + 1 < r) acc -= a.y * t[4 * s4 + 1];
;                 if (4 * s4 + 2 < r) acc -= a.z * t[4 * s4 + 2]; if (4 * s4 + 3 < r) acc -= a.w * t[4 * s4 + 3]; }
;             t[r] = acc;
;         }
	v_mov_b32_e32 v25, v232
	v_pk_mul_f32 v[24:25], v[102:103], v[24:25]
	v_mov_b32_e32 v14, v97
	v_sub_f32_e32 v6, v10, v24
	v_sub_f32_e32 v10, v6, v25
	v_mov_b32_e32 v6, v233
	v_mov_b32_e32 v7, v234
	v_pk_mul_f32 v[6:7], v[106:107], v[6:7]
	s_waitcnt lgkmcnt(3)
	v_mov_b32_e32 v24, v191
	v_sub_f32_e32 v6, v10, v6
	v_sub_f32_e32 v8, v6, v7
	v_mov_b32_e32 v6, v235
	ds_read_b128 v[232:235], v2 offset:10752
	v_mov_b32_e32 v7, v188
	v_pk_mul_f32 v[6:7], v[110:111], v[6:7]
	v_cmp_eq_u32_e32 vcc, 42, v185
	v_sub_f32_e32 v6, v8, v6
	v_sub_f32_e32 v10, v6, v7
	v_mov_b32_e32 v6, v189
	v_mov_b32_e32 v7, v190
	v_pk_mul_f32 v[16:17], v[114:115], v[6:7]
	v_sub_f32_e32 v10, v10, v16
	v_sub_f32_e32 v10, v10, v17
	s_waitcnt lgkmcnt(3)
	v_mov_b32_e32 v25, v228
	v_pk_mul_f32 v[24:25], v[118:119], v[24:25]
	v_mov_b32_e32 v4, v217
	v_sub_f32_e32 v6, v10, v24
	v_sub_f32_e32 v10, v6, v25
	v_mov_b32_e32 v6, v229
	v_mov_b32_e32 v7, v230
	v_pk_mul_f32 v[6:7], v[122:123], v[6:7]
	v_mov_b32_e32 v24, v231
	v_sub_f32_e32 v6, v10, v6
	v_sub_f32_e32 v6, v6, v7
	v_mov_b32_e32 v25, v97
	v_mov_b32_e32 v7, v96
	s_waitcnt lgkmcnt(2)
	v_mul_f32_e32 v8, v99, v236
	v_pk_fma_f32 v[6:7], v[14:15], v[24:25], v[6:7] neg_lo:[1,0,0] neg_hi:[1,0,0]
	v_mov_b32_e32 v9, v22
	v_mul_f32_e32 v16, v101, v237
	v_pk_add_f32 v[6:7], v[6:7], v[8:9] neg_lo:[0,1] neg_hi:[0,1]
	v_mov_b32_e32 v17, v23
	v_pk_add_f32 v[102:103], v[6:7], v[16:17] neg_lo:[0,1] neg_hi:[0,1]
	v_cndmask_b32_e64 v10, 0, 1.0, vcc
	v_add_u32_e32 v22, 0x2800, v2
	ds_read2_b64 v[14:17], v22 offset0:52 offset1:84
	ds_read_b128 v[188:191], v2 offset:10784
	ds_read_b128 v[228:231], v2 offset:10800
	v_mov_b32_e32 v146, v101
	s_waitcnt lgkmcnt(3)
	v_fma_f32 v6, -v30, v232, v10
	v_fma_f32 v6, -v29, v233, v6
	v_fma_f32 v6, -v27, v234, v6
	v_fma_f32 v6, -v33, v235, v6
	ds_read_b128 v[232:235], v2 offset:10816
	v_fma_f32 v10, -v35, v240, v6
	v_fma_f32 v10, -v37, v241, v10
	v_fma_f32 v10, -v39, v242, v10
	v_fma_f32 v10, -v41, v243, v10
	ds_read_b128 v[240:243], v2 offset:10832
	s_waitcnt lgkmcnt(3)
	v_fma_f32 v6, -v43, v188, v10
	v_fma_f32 v6, -v45, v189, v6
	v_fma_f32 v6, -v47, v190, v6
	v_fma_f32 v6, -v49, v191, v6
	ds_read_b128 v[188:191], v2 offset:10848
	s_waitcnt lgkmcnt(3)
	v_fma_f32 v10, -v51, v228, v6
	v_fma_f32 v10, -v53, v229, v10
	v_fma_f32 v10, -v55, v230, v10
	v_fma_f32 v10, -v57, v231, v10
	ds_read_b128 v[228:231], v2 offset:10864
	s_waitcnt lgkmcnt(3)
	v_fma_f32 v6, -v59, v232, v10
	v_fma_f32 v6, -v61, v233, v6
	v_fma_f32 v6, -v63, v234, v6
	v_fma_f32 v6, -v65, v235, v6
	s_waitcnt lgkmcnt(2)
	v_fma_f32 v10, -v67, v240, v6
	v_fma_f32 v10, -v69, v241, v10
	v_fma_f32 v10, -v71, v242, v10
	v_fma_f32 v10, -v73, v243, v10
	s_waitcnt lgkmcnt(1)
	v_pk_mul_f32 v[6:7], v[104:105], v[188:189]
	v_mov_b32_e32 v147, v103
	v_sub_f32_e32 v6, v10, v6
	v_sub_f32_e32 v10, v6, v7
	v_pk_mul_f32 v[6:7], v[108:109], v[190:191]
	v_pk_mul_f32 v[24:25], v[4:5], v[146:147]
	v_sub_f32_e32 v6, v10, v6
	v_sub_f32_e32 v8, v6, v7
	s_waitcnt lgkmcnt(0)
	v_pk_mul_f32 v[6:7], v[112:113], v[228:229]
	v_mov_b32_e32 v5, v14
	v_sub_f32_e32 v6, v8, v6
	v_sub_f32_e32 v8, v6, v7
	v_pk_mul_f32 v[6:7], v[116:117], v[230:231]
	v_pk_mul_f32 v[14:15], v[120:121], v[212:213]
	v_sub_f32_e32 v6, v8, v6
	v_sub_f32_e32 v10, v6, v7
	ds_read_b128 v[6:9], v2 offset:10896
	ds_read_b128 v[232:235], v2 offset:11008
	ds_read_b128 v[240:243], v2 offset:11024
	ds_read_b128 v[188:191], v2 offset:11040
	ds_read_b128 v[228:231], v2 offset:11056
	v_sub_f32_e32 v10, v10, v14
	v_sub_f32_e32 v10, v10, v15
	v_pk_mul_f32 v[14:15], v[124:125], v[214:215]
	ds_read_b128 v[212:215], v2 offset:11072
	v_mov_b32_e32 v105, v24
	v_sub_f32_e32 v10, v10, v14
	v_sub_f32_e32 v14, v10, v15
	s_waitcnt lgkmcnt(5)
	v_mul_f32_e32 v104, v101, v7
	v_mov_b32_e32 v7, v216
	ds_read_b128 v[216:219], v2 offset:11088
	v_mov_b32_e32 v15, v98
	v_pk_fma_f32 v[6:7], v[98:99], v[6:7], v[14:15] op_sel:[1,0,0] neg_lo:[1,0,0] neg_hi:[1,0,0]
	v_mul_f32_e32 v126, v103, v8
	v_pk_add_f32 v[6:7], v[6:7], v[104:105] neg_lo:[0,1] neg_hi:[0,1]
	v_mov_b32_e32 v127, v25
	v_pk_add_f32 v[104:105], v[6:7], v[126:127] neg_lo:[0,1] neg_hi:[0,1]
	v_mov_b32_e32 v142, v103
	v_mov_b32_e32 v143, v105
	v_cmp_eq_u32_e32 vcc, 43, v185
	v_pk_mul_f32 v[6:7], v[12:13], v[142:143]
	s_nop 0
	v_cndmask_b32_e64 v8, 0, 1.0, vcc
	s_waitcnt lgkmcnt(5)
	v_fma_f32 v8, -v30, v232, v8
	v_fma_f32 v8, -v29, v233, v8
	v_fma_f32 v8, -v27, v234, v8
	v_fma_f32 v8, -v33, v235, v8
	ds_read_b128 v[232:235], v2 offset:11104
	s_waitcnt lgkmcnt(5)
	v_fma_f32 v8, -v35, v240, v8
	v_fma_f32 v8, -v37, v241, v8
	v_fma_f32 v8, -v39, v242, v8
	v_fma_f32 v8, -v41, v243, v8
	ds_read_b128 v[240:243], v2 offset:11120
	s_waitcnt lgkmcnt(5)
	v_fma_f32 v8, -v43, v188, v8
	v_fma_f32 v8, -v45, v189, v8
	v_fma_f32 v8, -v47, v190, v8
	v_fma_f32 v8, -v49, v191, v8
	ds_read_b128 v[188:191], v2 offset:11136
	s_waitcnt lgkmcnt(5)
	v_fma_f32 v8, -v51, v228, v8
	v_fma_f32 v8, -v53, v229, v8
	v_fma_f32 v8, -v55, v230, v8
	v_fma_f32 v8, -v57, v231, v8
	ds_read_b128 v[228:231], v2 offset:11152
	s_waitcnt lgkmcnt(5)
	v_fma_f32 v8, -v59, v212, v8
	v_fma_f32 v8, -v61, v213, v8
	v_fma_f32 v8, -v63, v214, v8
	v_fma_f32 v8, -v65, v215, v8
	ds_read_b128 v[212:215], v2 offset:11168
	s_waitcnt lgkmcnt(5)
	v_fma_f32 v8, -v67, v216, v8
	v_fma_f32 v8, -v69, v217, v8
	v_fma_f32 v8, -v71, v218, v8
	v_fma_f32 v8, -v73, v219, v8
	ds_read_b128 v[216:219], v2 offset:11264
	s_waitcnt lgkmcnt(5)
	v_mov_b32_e32 v20, v233
	v_mov_b32_e32 v21, v234
	v_fma_f32 v8, -v75, v232, v8
	v_pk_mul_f32 v[20:21], v[106:107], v[20:21]
	v_mov_b32_e32 v4, v239
	v_sub_f32_e32 v8, v8, v20
	v_mov_b32_e32 v20, v235
	ds_read_b128 v[232:235], v2 offset:11280
	v_sub_f32_e32 v8, v8, v21
	s_waitcnt lgkmcnt(5)
; #define LAS __attribute__((address_space(3)))
; __device__ __forceinline__ void dk_phase(const Frame& F, const bf16* QKrm, const unsigned char* KT, const unsigned char* VT, const float* BG, unsigned char* ITEMS) {
;     ...
; #pragma unroll
;         for (int r = 0; r < 64; ++r) {
;             float acc = (lane == r) ? 1.f : 0.f;
; #pragma unroll
;             for (int s4 = 0; s4 < (r + 3) / 4; ++s4) { const f32x4 a = *(const LAS f32x4*)(Amat + r * 64 + 4 * s4);
;                 if (4 * s4 + 0 < r) acc -= a.x * t[4 * s4 + 0]; if (4 * s4 + 1 < r) acc -= a.y * t[4 * s4 + 1];
;                 if (4 * s4 + 2 < r) acc -= a.z * t[4 * s4 + 2]; if (4 * s4 + 3 < r) acc -= a.w * t[4 * s4 + 3]; }
;             t[r] = acc;
;         }
	v_mov_b32_e32 v21, v240
	v_pk_mul_f32 v[20:21], v[110:111], v[20:21]
	v_mov_b32_e32 v12, v241
	v_sub_f32_e32 v8, v8, v20
	v_mov_b32_e32 v13, v242
	v_sub_f32_e32 v8, v8, v21
	v_pk_mul_f32 v[12:13], v[114:115], v[12:13]
	v_mov_b32_e32 v20, v243
	ds_read_b128 v[240:243], v2 offset:11296
	v_sub_f32_e32 v8, v8, v12
	s_waitcnt lgkmcnt(5)
	v_mov_b32_e32 v21, v188
	v_sub_f32_e32 v8, v8, v13
	v_pk_mul_f32 v[20:21], v[118:119], v[20:21]
	v_mov_b32_e32 v138, v105
	v_sub_f32_e32 v8, v8, v20
	v_sub_f32_e32 v8, v8, v21
	v_mov_b32_e32 v20, v189
	v_mov_b32_e32 v21, v190
	v_pk_mul_f32 v[20:21], v[122:123], v[20:21]
	s_waitcnt lgkmcnt(4)
	v_mov_b32_e32 v10, v229
	v_sub_f32_e32 v8, v8, v20
	v_sub_f32_e32 v8, v8, v21
	v_mov_b32_e32 v20, v191
	ds_read_b128 v[188:191], v2 offset:11312
	v_mov_b32_e32 v21, v228
	v_pk_mul_f32 v[20:21], v[140:141], v[20:21]
	v_mov_b32_e32 v13, v100
	v_sub_f32_e32 v8, v8, v20
	v_sub_f32_e32 v12, v8, v21
	v_mul_f32_e32 v14, v103, v230
	v_mul_f32_e32 v20, v105, v231
	ds_read_b128 v[228:231], v2 offset:11328
	v_pk_fma_f32 v[10:11], v[100:101], v[10:11], v[12:13] op_sel:[1,0,0] neg_lo:[1,0,0] neg_hi:[1,0,0]
	v_mov_b32_e32 v15, v6
	v_pk_add_f32 v[10:11], v[10:11], v[14:15] neg_lo:[0,1] neg_hi:[0,1]
	v_mov_b32_e32 v21, v7
	v_pk_add_f32 v[106:107], v[10:11], v[20:21] neg_lo:[0,1] neg_hi:[0,1]
	v_mov_b32_e32 v139, v107
	v_pk_mul_f32 v[24:25], v[4:5], v[138:139]
	v_cmp_eq_u32_e32 vcc, 44, v185
	s_waitcnt lgkmcnt(5)
	v_mov_b32_e32 v21, v214
	v_cndmask_b32_e64 v8, 0, 1.0, vcc
	s_waitcnt lgkmcnt(4)
	v_fma_f32 v4, -v30, v216, v8
	v_fma_f32 v4, -v29, v217, v4
	v_fma_f32 v4, -v27, v218, v4
	v_fma_f32 v8, -v33, v219, v4
	ds_read_b128 v[216:219], v2 offset:11344
	s_waitcnt lgkmcnt(4)
	v_fma_f32 v8, -v35, v232, v8
	v_fma_f32 v8, -v37, v233, v8
	v_fma_f32 v8, -v39, v234, v8
	v_fma_f32 v8, -v41, v235, v8
	ds_read_b128 v[232:235], v2 offset:11360
	s_waitcnt lgkmcnt(4)
	v_fma_f32 v4, -v43, v240, v8
	v_fma_f32 v4, -v45, v241, v4
	v_fma_f32 v4, -v47, v242, v4
	v_fma_f32 v8, -v49, v243, v4
	ds_read_b128 v[240:243], v2 offset:11376
	s_waitcnt lgkmcnt(4)
	v_fma_f32 v8, -v51, v188, v8
	v_fma_f32 v8, -v53, v189, v8
	v_fma_f32 v8, -v55, v190, v8
	v_fma_f32 v8, -v57, v191, v8
	ds_read_b128 v[188:191], v2 offset:11392
	s_waitcnt lgkmcnt(4)
	v_fma_f32 v4, -v59, v228, v8
	v_fma_f32 v4, -v61, v229, v4
	v_fma_f32 v4, -v63, v230, v4
	v_fma_f32 v8, -v65, v231, v4
	s_waitcnt lgkmcnt(3)
	v_fma_f32 v8, -v67, v216, v8
	v_fma_f32 v8, -v69, v217, v8
	v_fma_f32 v8, -v71, v218, v8
	v_fma_f32 v8, -v73, v219, v8
	s_waitcnt lgkmcnt(2)
	v_fma_f32 v4, -v75, v232, v8
	v_fma_f32 v8, -v77, v233, v4
	v_pk_mul_f32 v[4:5], v[108:109], v[234:235]
	v_pk_mov_b32 v[18:19], v[102:103], v[238:239] op_sel:[1,0]
	v_sub_f32_e32 v4, v8, v4
	v_sub_f32_e32 v8, v4, v5
	s_waitcnt lgkmcnt(1)
	v_pk_mul_f32 v[12:13], v[112:113], v[240:241]
	v_mov_b32_e32 v109, v24
	v_sub_f32_e32 v8, v8, v12
	v_sub_f32_e32 v8, v8, v13
	v_pk_mul_f32 v[12:13], v[116:117], v[242:243]
	s_waitcnt lgkmcnt(0)
	v_pk_mul_f32 v[4:5], v[120:121], v[188:189]
	v_sub_f32_e32 v8, v8, v12
	v_sub_f32_e32 v8, v8, v13
	ds_read_b128 v[12:15], v2 offset:11408
	v_sub_f32_e32 v4, v8, v4
	v_sub_f32_e32 v8, v4, v5
	v_pk_mul_f32 v[4:5], v[124:125], v[190:191]
	v_mov_b32_e32 v127, v25
	v_sub_f32_e32 v4, v8, v4
	v_sub_f32_e32 v8, v4, v5
	ds_read_b128 v[4:7], v2 offset:11424
	ds_read_b128 v[228:231], v2 offset:11520
	ds_read_b128 v[216:219], v2 offset:11776
	ds_read_b128 v[232:235], v2 offset:11536
	ds_read_b128 v[236:239], v2 offset:11552
	ds_read_b128 v[240:243], v2 offset:11568
	ds_read_b128 v[188:191], v2 offset:11584
	s_waitcnt lgkmcnt(7)
	v_pk_mul_f32 v[12:13], v[144:145], v[12:13]
	v_mul_f32_e32 v108, v105, v15
	v_sub_f32_e32 v8, v8, v12
	v_sub_f32_e32 v12, v8, v13
	v_mov_b32_e32 v15, v103
	v_mov_b32_e32 v13, v102
	v_pk_fma_f32 v[12:13], v[18:19], v[14:15], v[12:13] neg_lo:[1,0,0] neg_hi:[1,0,0]
	s_waitcnt lgkmcnt(6)
	v_mul_f32_e32 v126, v107, v4
	v_pk_add_f32 v[12:13], v[12:13], v[108:109] neg_lo:[0,1] neg_hi:[0,1]
	v_mov_b32_e32 v134, v107
	v_pk_add_f32 v[108:109], v[12:13], v[126:127] neg_lo:[0,1] neg_hi:[0,1]
	v_mov_b32_e32 v135, v109
	v_cmp_eq_u32_e32 vcc, 45, v185
	v_pk_mul_f32 v[24:25], v[16:17], v[134:135]
	s_nop 0
	v_cndmask_b32_e64 v4, 0, 1.0, vcc
	s_waitcnt lgkmcnt(5)
	v_fma_f32 v4, -v30, v228, v4
	v_fma_f32 v4, -v29, v229, v4
	v_fma_f32 v4, -v27, v230, v4
	v_fma_f32 v4, -v33, v231, v4
	ds_read_b128 v[228:231], v2 offset:11600
	s_waitcnt lgkmcnt(4)
	v_fma_f32 v4, -v35, v232, v4
	v_fma_f32 v4, -v37, v233, v4
	v_fma_f32 v4, -v39, v234, v4
	v_fma_f32 v4, -v41, v235, v4
	ds_read_b128 v[232:235], v2 offset:11616
	s_waitcnt lgkmcnt(4)
	v_fma_f32 v4, -v43, v236, v4
	v_fma_f32 v4, -v45, v237, v4
	v_fma_f32 v4, -v47, v238, v4
	v_fma_f32 v4, -v49, v239, v4
	ds_read_b128 v[236:239], v2 offset:11632
	s_waitcnt lgkmcnt(4)
	v_fma_f32 v4, -v51, v240, v4
	v_fma_f32 v4, -v53, v241, v4
	v_fma_f32 v4, -v55, v242, v4
	v_fma_f32 v4, -v57, v243, v4
	ds_read_b128 v[240:243], v2 offset:11648
	s_waitcnt lgkmcnt(4)
	v_fma_f32 v4, -v59, v188, v4
	v_fma_f32 v4, -v61, v189, v4
	v_fma_f32 v4, -v63, v190, v4
	v_fma_f32 v4, -v65, v191, v4
	ds_read_b128 v[188:191], v2 offset:11664
	s_waitcnt lgkmcnt(4)
	v_fma_f32 v4, -v67, v228, v4
	v_fma_f32 v4, -v69, v229, v4
	v_fma_f32 v4, -v71, v230, v4
	v_fma_f32 v4, -v73, v231, v4
	ds_read_b128 v[228:231], v2 offset:11680
	v_mov_b32_e32 v8, v105
	s_waitcnt lgkmcnt(4)
	v_fma_f32 v4, -v75, v232, v4
	v_fma_f32 v4, -v77, v233, v4
	v_mov_b32_e32 v12, v235
	s_waitcnt lgkmcnt(3)
; #define LAS __attribute__((address_space(3)))
; __device__ __forceinline__ void dk_phase(const Frame& F, const bf16* QKrm, const unsigned char* KT, const unsigned char* VT, const float* BG, unsigned char* ITEMS) {
;     ...
; #pragma unroll
;         for (int r = 0; r < 64; ++r) {
;             float acc = (lane == r) ? 1.f : 0.f;
; #pragma unroll
;             for (int s4 = 0; s4 < (r + 3) / 4; ++s4) { const f32x4 a = *(const LAS f32x4*)(Amat + r * 64 + 4 * s4);
;                 if (4 * s4 + 0 < r) acc -= a.x * t[4 * s4 + 0]; if (4 * s4 + 1 < r) acc -= a.y * t[4 * s4 + 1];
;                 if (4 * s4 + 2 < r) acc -= a.z * t[4 * s4 + 2]; if (4 * s4 + 3 < r) acc -= a.w * t[4 * s4 + 3]; }
;             t[r] = acc;
;         }
	v_mov_b32_e32 v13, v236
	v_fma_f32 v4, -v79, v234, v4
	ds_read_b128 v[232:235], v2 offset:11792
	v_pk_mul_f32 v[12:13], v[110:111], v[12:13]
	v_mov_b32_e32 v110, v239
	v_sub_f32_e32 v4, v4, v12
	v_sub_f32_e32 v4, v4, v13
	v_mov_b32_e32 v12, v237
	v_mov_b32_e32 v13, v238
	ds_read_b128 v[236:239], v2 offset:11808
	v_pk_mul_f32 v[16:17], v[114:115], v[12:13]
	v_sub_f32_e32 v4, v4, v16
	v_sub_f32_e32 v4, v4, v17
	v_cmp_eq_u32_e32 vcc, 46, v185
	s_waitcnt lgkmcnt(4)
	v_mov_b32_e32 v111, v240
	v_pk_mul_f32 v[110:111], v[118:119], v[110:111]
	v_mov_b32_e32 v12, v241
	v_sub_f32_e32 v4, v4, v110
	v_mov_b32_e32 v13, v242
	v_sub_f32_e32 v4, v4, v111
	v_pk_mul_f32 v[12:13], v[122:123], v[12:13]
	s_waitcnt lgkmcnt(3)
	v_mov_b32_e32 v110, v191
	v_sub_f32_e32 v4, v4, v12
	v_sub_f32_e32 v4, v4, v13
	v_mov_b32_e32 v12, v243
	ds_read_b128 v[240:243], v2 offset:11824
	v_mov_b32_e32 v13, v188
	v_pk_mul_f32 v[12:13], v[140:141], v[12:13]
	v_mov_b32_e32 v111, v105
	v_sub_f32_e32 v4, v4, v12
	v_mov_b32_e32 v12, v189
	v_sub_f32_e32 v4, v4, v13
	v_mov_b32_e32 v13, v190
	ds_read_b128 v[188:191], v2 offset:11840
	v_pk_mul_f32 v[12:13], v[146:147], v[12:13]
	v_mov_b32_e32 v19, v25
	v_sub_f32_e32 v4, v4, v12
	v_sub_f32_e32 v12, v4, v13
	v_mov_b32_e32 v13, v104
	s_waitcnt lgkmcnt(4)
	v_mul_f32_e32 v14, v107, v228
	v_mul_f32_e32 v18, v109, v229
	v_pk_fma_f32 v[8:9], v[8:9], v[110:111], v[12:13] neg_lo:[1,0,0] neg_hi:[1,0,0]
	v_mov_b32_e32 v15, v24
	v_pk_add_f32 v[8:9], v[8:9], v[14:15] neg_lo:[0,1] neg_hi:[0,1]
	v_cndmask_b32_e64 v4, 0, 1.0, vcc
	v_fma_f32 v4, -v30, v216, v4
	v_pk_add_f32 v[110:111], v[8:9], v[18:19] neg_lo:[0,1] neg_hi:[0,1]
	v_fma_f32 v4, -v29, v217, v4
	v_mov_b32_e32 v20, v213
	v_mov_b32_e32 v136, v109
	v_mov_b32_e32 v137, v111
	v_fma_f32 v4, -v27, v218, v4
	v_pk_mul_f32 v[130:131], v[20:21], v[136:137]
	v_fma_f32 v4, -v33, v219, v4
	ds_read_b128 v[216:219], v2 offset:11856
	s_waitcnt lgkmcnt(4)
	v_fma_f32 v4, -v35, v232, v4
	v_fma_f32 v4, -v37, v233, v4
	v_fma_f32 v4, -v39, v234, v4
	v_fma_f32 v4, -v41, v235, v4
	ds_read_b128 v[232:235], v2 offset:11872
	s_waitcnt lgkmcnt(4)
	v_fma_f32 v4, -v43, v236, v4
	v_fma_f32 v4, -v45, v237, v4
	v_fma_f32 v4, -v47, v238, v4
	v_fma_f32 v4, -v49, v239, v4
	ds_read_b128 v[236:239], v2 offset:11888
	s_waitcnt lgkmcnt(4)
	v_fma_f32 v4, -v51, v240, v4
	v_fma_f32 v4, -v53, v241, v4
	v_fma_f32 v4, -v55, v242, v4
	v_fma_f32 v4, -v57, v243, v4
	ds_read_b128 v[240:243], v2 offset:11904
	s_waitcnt lgkmcnt(4)
	v_fma_f32 v4, -v59, v188, v4
	v_fma_f32 v4, -v61, v189, v4
	v_fma_f32 v4, -v63, v190, v4
	v_fma_f32 v4, -v65, v191, v4
	ds_read_b128 v[188:191], v2 offset:11920
	s_waitcnt lgkmcnt(4)
	v_fma_f32 v4, -v67, v216, v4
	v_fma_f32 v4, -v69, v217, v4
	v_fma_f32 v4, -v71, v218, v4
	v_fma_f32 v4, -v73, v219, v4
	s_waitcnt lgkmcnt(3)
	v_fma_f32 v4, -v75, v232, v4
	v_fma_f32 v4, -v77, v233, v4
	v_fma_f32 v4, -v79, v234, v4
	v_fma_f32 v4, -v81, v235, v4
	s_waitcnt lgkmcnt(2)
	v_pk_mul_f32 v[12:13], v[112:113], v[236:237]
	v_sub_f32_e32 v4, v4, v12
	v_sub_f32_e32 v4, v4, v13
	v_pk_mul_f32 v[12:13], v[116:117], v[238:239]
	ds_read2_b64 v[22:25], v22 offset0:182 offset1:214
	v_sub_f32_e32 v4, v4, v12
	v_sub_f32_e32 v4, v4, v13
	s_waitcnt lgkmcnt(2)
	v_pk_mul_f32 v[12:13], v[120:121], v[240:241]
	s_waitcnt lgkmcnt(1)
	v_pk_mul_f32 v[18:19], v[144:145], v[188:189]
	v_sub_f32_e32 v4, v4, v12
	v_sub_f32_e32 v4, v4, v13
	v_pk_mul_f32 v[12:13], v[124:125], v[242:243]
	v_mov_b32_e32 v21, v130
	v_sub_f32_e32 v4, v4, v12
	v_sub_f32_e32 v4, v4, v13
	ds_read_b128 v[12:15], v2 offset:11936
	ds_read_b128 v[216:219], v2 offset:12032
	ds_read_b128 v[232:235], v2 offset:12048
	ds_read_b128 v[236:239], v2 offset:12064
	ds_read_b128 v[240:243], v2 offset:12080
	v_sub_f32_e32 v4, v4, v18
	v_sub_f32_e32 v4, v4, v19
	v_pk_mul_f32 v[18:19], v[142:143], v[190:191]
	ds_read_b128 v[188:191], v2 offset:12096
	s_waitcnt lgkmcnt(6)
	v_mov_b32_e32 v9, v22
	v_sub_f32_e32 v4, v4, v18
	v_sub_f32_e32 v18, v4, v19
	s_waitcnt lgkmcnt(5)
	v_mul_f32_e32 v20, v109, v13
	v_mov_b32_e32 v13, v212
	ds_read_b128 v[212:215], v2 offset:12112
	v_mov_b32_e32 v19, v106
	v_pk_fma_f32 v[10:11], v[106:107], v[12:13], v[18:19] op_sel:[1,0,0] neg_lo:[1,0,0] neg_hi:[1,0,0]
	v_mul_f32_e32 v22, v111, v14
	v_pk_add_f32 v[10:11], v[10:11], v[20:21] neg_lo:[0,1] neg_hi:[0,1]
	v_mov_b32_e32 v23, v131
	v_pk_add_f32 v[112:113], v[10:11], v[22:23] neg_lo:[0,1] neg_hi:[0,1]
	v_cmp_eq_u32_e32 vcc, 47, v185
	v_mov_b32_e32 v132, v111
	s_nop 0
	v_cndmask_b32_e64 v4, 0, 1.0, vcc
	s_waitcnt lgkmcnt(5)
	v_fma_f32 v4, -v30, v216, v4
	v_fma_f32 v4, -v29, v217, v4
	v_fma_f32 v4, -v27, v218, v4
	v_fma_f32 v4, -v33, v219, v4
	ds_read_b128 v[216:219], v2 offset:12128
	s_waitcnt lgkmcnt(5)
	v_fma_f32 v4, -v35, v232, v4
	v_fma_f32 v4, -v37, v233, v4
	v_fma_f32 v4, -v39, v234, v4
	v_fma_f32 v4, -v41, v235, v4
	ds_read_b128 v[232:235], v2 offset:12144
	s_waitcnt lgkmcnt(5)
	v_fma_f32 v4, -v43, v236, v4
	v_fma_f32 v4, -v45, v237, v4
	v_fma_f32 v4, -v47, v238, v4
	v_fma_f32 v4, -v49, v239, v4
	ds_read_b128 v[236:239], v2 offset:12160
	s_waitcnt lgkmcnt(5)
	v_fma_f32 v4, -v51, v240, v4
	v_fma_f32 v4, -v53, v241, v4
	v_fma_f32 v4, -v55, v242, v4
	v_fma_f32 v4, -v57, v243, v4
	ds_read_b128 v[240:243], v2 offset:12176
	s_waitcnt lgkmcnt(5)
	v_fma_f32 v4, -v59, v188, v4
	v_fma_f32 v4, -v61, v189, v4
	v_fma_f32 v4, -v63, v190, v4
	v_fma_f32 v4, -v65, v191, v4
	ds_read_b128 v[188:191], v2 offset:12192
	s_waitcnt lgkmcnt(5)
	v_fma_f32 v4, -v67, v212, v4
	v_fma_f32 v4, -v69, v213, v4
	v_fma_f32 v4, -v71, v214, v4
	v_fma_f32 v4, -v73, v215, v4
	ds_read_b128 v[212:215], v2 offset:12288
	s_waitcnt lgkmcnt(5)
; #define LAS __attribute__((address_space(3)))
; __device__ __forceinline__ void dk_phase(const Frame& F, const bf16* QKrm, const unsigned char* KT, const unsigned char* VT, const float* BG, unsigned char* ITEMS) {
;     ...
; #pragma unroll
;         for (int r = 0; r < 64; ++r) {
;             float acc = (lane == r) ? 1.f : 0.f;
; #pragma unroll
;             for (int s4 = 0; s4 < (r + 3) / 4; ++s4) { const f32x4 a = *(const LAS f32x4*)(Amat + r * 64 + 4 * s4);
;                 if (4 * s4 + 0 < r) acc -= a.x * t[4 * s4 + 0]; if (4 * s4 + 1 < r) acc -= a.y * t[4 * s4 + 1];
;                 if (4 * s4 + 2 < r) acc -= a.z * t[4 * s4 + 2]; if (4 * s4 + 3 < r) acc -= a.w * t[4 * s4 + 3]; }
;             t[r] = acc;
;         }
	v_fma_f32 v4, -v75, v216, v4
	v_fma_f32 v4, -v77, v217, v4
	v_fma_f32 v4, -v79, v218, v4
	v_fma_f32 v4, -v81, v219, v4
	ds_read_b128 v[216:219], v2 offset:12304
	s_waitcnt lgkmcnt(5)
	v_mov_b32_e32 v10, v233
	v_mov_b32_e32 v11, v234
	v_fma_f32 v4, -v83, v232, v4
	v_pk_mul_f32 v[18:19], v[114:115], v[10:11]
	v_sub_f32_e32 v4, v4, v18
	v_sub_f32_e32 v4, v4, v19
	v_mov_b32_e32 v22, v235
	ds_read_b128 v[232:235], v2 offset:12208
	s_waitcnt lgkmcnt(5)
	v_mov_b32_e32 v23, v236
	v_pk_mul_f32 v[22:23], v[118:119], v[22:23]
	v_mov_b32_e32 v10, v237
	v_sub_f32_e32 v4, v4, v22
	v_mov_b32_e32 v11, v238
	v_sub_f32_e32 v4, v4, v23
	v_pk_mul_f32 v[10:11], v[122:123], v[10:11]
	v_mov_b32_e32 v133, v113
	v_sub_f32_e32 v4, v4, v10
	v_sub_f32_e32 v4, v4, v11
	v_mov_b32_e32 v10, v239
	ds_read_b128 v[236:239], v2 offset:12320
	s_waitcnt lgkmcnt(5)
	v_mov_b32_e32 v11, v240
	v_pk_mul_f32 v[10:11], v[140:141], v[10:11]
	v_pk_mul_f32 v[6:7], v[6:7], v[132:133]
	v_sub_f32_e32 v4, v4, v10
	v_sub_f32_e32 v4, v4, v11
	v_mov_b32_e32 v10, v241
	v_mov_b32_e32 v11, v242
	v_pk_mul_f32 v[18:19], v[146:147], v[10:11]
	v_sub_f32_e32 v4, v4, v18
	v_sub_f32_e32 v4, v4, v19
	v_mov_b32_e32 v18, v243
	ds_read_b128 v[240:243], v2 offset:12336
	v_mov_b32_e32 v8, v231
	s_waitcnt lgkmcnt(5)
	v_mov_b32_e32 v19, v188
	v_pk_mul_f32 v[18:19], v[138:139], v[18:19]
	v_mul_f32_e32 v12, v111, v190
	v_sub_f32_e32 v4, v4, v18
	v_sub_f32_e32 v10, v4, v19
	v_mov_b32_e32 v4, v189
	v_mov_b32_e32 v11, v108
	v_mul_f32_e32 v18, v113, v191
	ds_read_b128 v[188:191], v2 offset:12352
	v_pk_fma_f32 v[4:5], v[108:109], v[4:5], v[10:11] op_sel:[1,0,0] neg_lo:[1,0,0] neg_hi:[1,0,0]
	v_mov_b32_e32 v13, v6
	v_pk_add_f32 v[4:5], v[4:5], v[12:13] neg_lo:[0,1] neg_hi:[0,1]
	v_mov_b32_e32 v19, v7
	v_pk_add_f32 v[114:115], v[4:5], v[18:19] neg_lo:[0,1] neg_hi:[0,1]
	v_mov_b32_e32 v130, v113
	v_mov_b32_e32 v131, v115
	v_pk_mul_f32 v[18:19], v[8:9], v[130:131]
	v_cmp_eq_u32_e32 vcc, 48, v185
	s_nop 1
	v_cndmask_b32_e64 v14, 0, 1.0, vcc
	s_waitcnt lgkmcnt(5)
	v_fma_f32 v6, -v30, v212, v14
	v_fma_f32 v6, -v29, v213, v6
	v_fma_f32 v6, -v27, v214, v6
	v_fma_f32 v6, -v33, v215, v6
	ds_read_b128 v[212:215], v2 offset:12368
	s_waitcnt lgkmcnt(5)
	v_fma_f32 v10, -v35, v216, v6
	v_fma_f32 v10, -v37, v217, v10
	v_fma_f32 v10, -v39, v218, v10
	v_fma_f32 v14, -v41, v219, v10
	ds_read_b128 v[216:219], v2 offset:12384
	s_waitcnt lgkmcnt(4)
	v_fma_f32 v6, -v43, v236, v14
	v_fma_f32 v6, -v45, v237, v6
	v_fma_f32 v6, -v47, v238, v6
	v_fma_f32 v6, -v49, v239, v6
	ds_read_b128 v[236:239], v2 offset:12400
	s_waitcnt lgkmcnt(4)
	v_fma_f32 v10, -v51, v240, v6
	v_fma_f32 v10, -v53, v241, v10
	v_fma_f32 v10, -v55, v242, v10
	v_fma_f32 v14, -v57, v243, v10
	ds_read_b128 v[240:243], v2 offset:12416
	s_waitcnt lgkmcnt(4)
	v_fma_f32 v6, -v59, v188, v14
	v_fma_f32 v6, -v61, v189, v6
	v_fma_f32 v6, -v63, v190, v6
	v_fma_f32 v6, -v65, v191, v6
	ds_read_b128 v[188:191], v2 offset:12432
	s_waitcnt lgkmcnt(4)
	v_fma_f32 v10, -v67, v212, v6
	v_fma_f32 v10, -v69, v213, v10
	v_fma_f32 v10, -v71, v214, v10
	v_fma_f32 v14, -v73, v215, v10
	s_waitcnt lgkmcnt(3)
	v_fma_f32 v6, -v75, v216, v14
	v_fma_f32 v6, -v77, v217, v6
	v_fma_f32 v6, -v79, v218, v6
	v_fma_f32 v6, -v81, v219, v6
	s_waitcnt lgkmcnt(2)
	v_fma_f32 v6, -v83, v236, v6
	v_fma_f32 v14, -v85, v237, v6
	v_pk_mul_f32 v[10:11], v[116:117], v[238:239]
	v_mov_b32_e32 v5, v234
	v_sub_f32_e32 v10, v14, v10
	v_sub_f32_e32 v14, v10, v11
	s_waitcnt lgkmcnt(1)
	v_pk_mul_f32 v[6:7], v[120:121], v[240:241]
	v_pk_mov_b32 v[16:17], v[110:111], v[230:231] op_sel:[1,0]
	v_sub_f32_e32 v6, v14, v6
	v_sub_f32_e32 v14, v6, v7
	v_pk_mul_f32 v[6:7], v[124:125], v[242:243]
	v_mov_b32_e32 v23, v18
	v_sub_f32_e32 v6, v14, v6
	v_sub_f32_e32 v8, v6, v7
	s_waitcnt lgkmcnt(0)
	v_pk_mul_f32 v[6:7], v[144:145], v[188:189]
	v_pk_mul_f32 v[10:11], v[142:143], v[190:191]
	v_sub_f32_e32 v6, v8, v6
	v_sub_f32_e32 v14, v6, v7
	ds_read_b128 v[6:9], v2 offset:12448
	v_sub_f32_e32 v10, v14, v10
	v_sub_f32_e32 v14, v10, v11
	ds_read_b128 v[10:13], v2 offset:12464
	ds_read_b128 v[212:215], v2 offset:12544
	ds_read_b128 v[216:219], v2 offset:12560
	ds_read_b128 v[236:239], v2 offset:12576
	ds_read_b128 v[228:231], v2 offset:12592
	ds_read_b128 v[240:243], v2 offset:12608
	ds_read_b128 v[188:191], v2 offset:12624
	v_mov_b32_e32 v117, v19
	s_waitcnt lgkmcnt(7)
	v_pk_mul_f32 v[6:7], v[134:135], v[6:7]
	v_mul_f32_e32 v22, v113, v9
	v_sub_f32_e32 v6, v14, v6
	v_sub_f32_e32 v6, v6, v7
	v_mov_b32_e32 v9, v111
	v_mov_b32_e32 v7, v110
	v_pk_fma_f32 v[6:7], v[16:17], v[8:9], v[6:7] neg_lo:[1,0,0] neg_hi:[1,0,0]
	s_waitcnt lgkmcnt(6)
	v_mul_f32_e32 v116, v115, v10
	v_pk_add_f32 v[6:7], v[6:7], v[22:23] neg_lo:[0,1] neg_hi:[0,1]
	v_cmp_eq_u32_e32 vcc, 49, v185
	v_pk_add_f32 v[116:117], v[6:7], v[116:117] neg_lo:[0,1] neg_hi:[0,1]
	s_nop 0
	v_cndmask_b32_e64 v10, 0, 1.0, vcc
	v_mov_b32_e32 v126, v115
	v_mov_b32_e32 v127, v117
	s_waitcnt lgkmcnt(5)
	v_fma_f32 v6, -v30, v212, v10
	v_fma_f32 v6, -v29, v213, v6
	v_fma_f32 v6, -v27, v214, v6
	v_fma_f32 v6, -v33, v215, v6
	ds_read_b128 v[212:215], v2 offset:12640
	s_waitcnt lgkmcnt(5)
	v_fma_f32 v10, -v35, v216, v6
	v_fma_f32 v10, -v37, v217, v10
	v_fma_f32 v10, -v39, v218, v10
	v_fma_f32 v10, -v41, v219, v10
	ds_read_b128 v[216:219], v2 offset:12656
	s_waitcnt lgkmcnt(5)
	v_fma_f32 v6, -v43, v236, v10
	v_fma_f32 v6, -v45, v237, v6
	v_fma_f32 v6, -v47, v238, v6
	v_fma_f32 v6, -v49, v239, v6
	ds_read_b128 v[236:239], v2 offset:12672
	s_waitcnt lgkmcnt(5)
	v_fma_f32 v10, -v51, v228, v6
	v_fma_f32 v10, -v53, v229, v10
	v_fma_f32 v10, -v55, v230, v10
	v_fma_f32 v10, -v57, v231, v10
	ds_read_b128 v[228:231], v2 offset:12688
	s_waitcnt lgkmcnt(5)
; #define LAS __attribute__((address_space(3)))
; __device__ __forceinline__ void dk_phase(const Frame& F, const bf16* QKrm, const unsigned char* KT, const unsigned char* VT, const float* BG, unsigned char* ITEMS) {
;     ...
; #pragma unroll
;         for (int r = 0; r < 64; ++r) {
;             float acc = (lane == r) ? 1.f : 0.f;
; #pragma unroll
;             for (int s4 = 0; s4 < (r + 3) / 4; ++s4) { const f32x4 a = *(const LAS f32x4*)(Amat + r * 64 + 4 * s4);
;                 if (4 * s4 + 0 < r) acc -= a.x * t[4 * s4 + 0]; if (4 * s4 + 1 < r) acc -= a.y * t[4 * s4 + 1];
;                 if (4 * s4 + 2 < r) acc -= a.z * t[4 * s4 + 2]; if (4 * s4 + 3 < r) acc -= a.w * t[4 * s4 + 3]; }
;             t[r] = acc;
;         }
	v_fma_f32 v6, -v59, v240, v10
	v_fma_f32 v6, -v61, v241, v6
	v_fma_f32 v6, -v63, v242, v6
	v_fma_f32 v6, -v65, v243, v6
	ds_read_b128 v[240:243], v2 offset:12704
	s_waitcnt lgkmcnt(5)
	v_fma_f32 v10, -v67, v188, v6
	v_fma_f32 v10, -v69, v189, v10
	v_fma_f32 v10, -v71, v190, v10
	v_fma_f32 v10, -v73, v191, v10
	ds_read_b128 v[188:191], v2 offset:12720
	s_waitcnt lgkmcnt(5)
	v_fma_f32 v6, -v75, v212, v10
	v_fma_f32 v6, -v77, v213, v6
	v_fma_f32 v6, -v79, v214, v6
	v_fma_f32 v6, -v81, v215, v6
	ds_read_b128 v[212:215], v2 offset:12816
	s_waitcnt lgkmcnt(5)
	v_fma_f32 v10, -v83, v216, v6
	v_pk_mul_f32 v[22:23], v[24:25], v[126:127]
	v_fma_f32 v10, -v85, v217, v10
	v_mov_b32_e32 v24, v219
	v_fma_f32 v10, -v87, v218, v10
	ds_read_b128 v[216:219], v2 offset:12960
	s_waitcnt lgkmcnt(5)
	v_mov_b32_e32 v25, v236
	v_pk_mul_f32 v[24:25], v[118:119], v[24:25]
	v_mov_b32_e32 v14, v113
	v_sub_f32_e32 v6, v10, v24
	v_sub_f32_e32 v10, v6, v25
	v_mov_b32_e32 v6, v237
	v_mov_b32_e32 v7, v238
	v_pk_mul_f32 v[6:7], v[122:123], v[6:7]
	s_waitcnt lgkmcnt(4)
	v_mov_b32_e32 v24, v231
	v_sub_f32_e32 v6, v10, v6
	v_sub_f32_e32 v8, v6, v7
	v_mov_b32_e32 v6, v239
	ds_read_b128 v[236:239], v2 offset:12800
	v_mov_b32_e32 v7, v228
	v_pk_mul_f32 v[6:7], v[140:141], v[6:7]
	v_cmp_eq_u32_e32 vcc, 50, v185
	v_sub_f32_e32 v6, v8, v6
	v_sub_f32_e32 v10, v6, v7
	v_mov_b32_e32 v6, v229
	v_mov_b32_e32 v7, v230
	v_pk_mul_f32 v[16:17], v[146:147], v[6:7]
	v_sub_f32_e32 v10, v10, v16
	v_sub_f32_e32 v10, v10, v17
	s_waitcnt lgkmcnt(4)
	v_mov_b32_e32 v25, v240
	v_pk_mul_f32 v[24:25], v[138:139], v[24:25]
	v_mov_b32_e32 v4, v233
	v_sub_f32_e32 v6, v10, v24
	v_sub_f32_e32 v10, v6, v25
	v_mov_b32_e32 v6, v241
	v_mov_b32_e32 v7, v242
	v_pk_mul_f32 v[6:7], v[136:137], v[6:7]
	v_mov_b32_e32 v24, v243
	v_sub_f32_e32 v6, v10, v6
	v_sub_f32_e32 v6, v6, v7
	v_mov_b32_e32 v25, v113
	v_mov_b32_e32 v7, v112
	s_waitcnt lgkmcnt(3)
	v_mul_f32_e32 v8, v115, v188
	v_pk_fma_f32 v[6:7], v[14:15], v[24:25], v[6:7] neg_lo:[1,0,0] neg_hi:[1,0,0]
	v_mov_b32_e32 v9, v22
	v_mul_f32_e32 v16, v117, v189
	v_pk_add_f32 v[6:7], v[6:7], v[8:9] neg_lo:[0,1] neg_hi:[0,1]
	v_mov_b32_e32 v17, v23
	v_pk_add_f32 v[118:119], v[6:7], v[16:17] neg_lo:[0,1] neg_hi:[0,1]
	v_cndmask_b32_e64 v10, 0, 1.0, vcc
	v_add_u32_e32 v22, 0x3000, v2
	ds_read2_b64 v[14:17], v22 offset0:56 offset1:88
	ds_read_b128 v[228:231], v2 offset:12832
	ds_read_b128 v[240:243], v2 offset:12848
	v_mov_b32_e32 v128, v117
	s_waitcnt lgkmcnt(3)
	v_fma_f32 v6, -v30, v236, v10
	v_fma_f32 v6, -v29, v237, v6
	v_fma_f32 v6, -v27, v238, v6
	v_fma_f32 v6, -v33, v239, v6
	ds_read_b128 v[236:239], v2 offset:12864
	v_fma_f32 v10, -v35, v212, v6
	v_fma_f32 v10, -v37, v213, v10
	v_fma_f32 v10, -v39, v214, v10
	v_fma_f32 v10, -v41, v215, v10
	ds_read_b128 v[212:215], v2 offset:12880
	s_waitcnt lgkmcnt(3)
	v_fma_f32 v6, -v43, v228, v10
	v_fma_f32 v6, -v45, v229, v6
	v_fma_f32 v6, -v47, v230, v6
	v_fma_f32 v6, -v49, v231, v6
	ds_read_b128 v[228:231], v2 offset:12896
	s_waitcnt lgkmcnt(3)
	v_fma_f32 v10, -v51, v240, v6
	v_fma_f32 v10, -v53, v241, v10
	v_fma_f32 v10, -v55, v242, v10
	v_fma_f32 v10, -v57, v243, v10
	ds_read_b128 v[240:243], v2 offset:12912
	s_waitcnt lgkmcnt(3)
	v_fma_f32 v6, -v59, v236, v10
	v_fma_f32 v6, -v61, v237, v6
	v_fma_f32 v6, -v63, v238, v6
	v_fma_f32 v6, -v65, v239, v6
	ds_read_b128 v[236:239], v2 offset:12928
	s_waitcnt lgkmcnt(3)
	v_fma_f32 v10, -v67, v212, v6
	v_fma_f32 v10, -v69, v213, v10
	v_fma_f32 v10, -v71, v214, v10
	v_fma_f32 v10, -v73, v215, v10
	ds_read_b128 v[212:215], v2 offset:12944
	s_waitcnt lgkmcnt(3)
	v_fma_f32 v6, -v75, v228, v10
	v_fma_f32 v6, -v77, v229, v6
	v_fma_f32 v6, -v79, v230, v6
	v_fma_f32 v6, -v81, v231, v6
	s_waitcnt lgkmcnt(2)
	v_fma_f32 v10, -v83, v240, v6
	v_fma_f32 v10, -v85, v241, v10
	v_fma_f32 v10, -v87, v242, v10
	v_fma_f32 v10, -v89, v243, v10
	s_waitcnt lgkmcnt(1)
	v_pk_mul_f32 v[6:7], v[120:121], v[236:237]
	v_mov_b32_e32 v129, v119
	v_sub_f32_e32 v6, v10, v6
	v_sub_f32_e32 v10, v6, v7
	v_pk_mul_f32 v[6:7], v[124:125], v[238:239]
	v_pk_mul_f32 v[24:25], v[4:5], v[128:129]
	v_sub_f32_e32 v6, v10, v6
	v_sub_f32_e32 v8, v6, v7
	s_waitcnt lgkmcnt(0)
	v_pk_mul_f32 v[6:7], v[144:145], v[212:213]
	v_mov_b32_e32 v5, v14
	v_sub_f32_e32 v6, v8, v6
	v_sub_f32_e32 v8, v6, v7
	v_pk_mul_f32 v[6:7], v[142:143], v[214:215]
	v_pk_mul_f32 v[14:15], v[134:135], v[216:217]
	v_sub_f32_e32 v6, v8, v6
	v_sub_f32_e32 v10, v6, v7
	ds_read_b128 v[6:9], v2 offset:12976
	ds_read_b128 v[228:231], v2 offset:13056
	ds_read_b128 v[240:243], v2 offset:13072
	ds_read_b128 v[236:239], v2 offset:13088
	ds_read_b128 v[212:215], v2 offset:13104
	v_sub_f32_e32 v10, v10, v14
	v_sub_f32_e32 v10, v10, v15
	v_pk_mul_f32 v[14:15], v[132:133], v[218:219]
	ds_read_b128 v[216:219], v2 offset:13120
	v_mov_b32_e32 v121, v24
	v_sub_f32_e32 v10, v10, v14
	v_sub_f32_e32 v14, v10, v15
	s_waitcnt lgkmcnt(5)
	v_mul_f32_e32 v120, v117, v7
	v_mov_b32_e32 v7, v232
	ds_read_b128 v[232:235], v2 offset:13136
	v_mov_b32_e32 v15, v114
	v_pk_fma_f32 v[6:7], v[114:115], v[6:7], v[14:15] op_sel:[1,0,0] neg_lo:[1,0,0] neg_hi:[1,0,0]
	v_mul_f32_e32 v148, v119, v8
	v_pk_add_f32 v[6:7], v[6:7], v[120:121] neg_lo:[0,1] neg_hi:[0,1]
	v_mov_b32_e32 v149, v25
	v_pk_add_f32 v[120:121], v[6:7], v[148:149] neg_lo:[0,1] neg_hi:[0,1]
	v_mov_b32_e32 v150, v119
	v_mov_b32_e32 v151, v121
	v_cmp_eq_u32_e32 vcc, 51, v185
	v_pk_mul_f32 v[6:7], v[12:13], v[150:151]
	s_nop 0
	v_cndmask_b32_e64 v8, 0, 1.0, vcc
	s_waitcnt lgkmcnt(5)
	v_fma_f32 v8, -v30, v228, v8
	v_fma_f32 v8, -v29, v229, v8
	v_fma_f32 v8, -v27, v230, v8
	v_fma_f32 v8, -v33, v231, v8
	ds_read_b128 v[228:231], v2 offset:13152
	s_waitcnt lgkmcnt(5)
; #define LAS __attribute__((address_space(3)))
; __device__ __forceinline__ void dk_phase(const Frame& F, const bf16* QKrm, const unsigned char* KT, const unsigned char* VT, const float* BG, unsigned char* ITEMS) {
;     ...
; #pragma unroll
;         for (int r = 0; r < 64; ++r) {
;             float acc = (lane == r) ? 1.f : 0.f;
; #pragma unroll
;             for (int s4 = 0; s4 < (r + 3) / 4; ++s4) { const f32x4 a = *(const LAS f32x4*)(Amat + r * 64 + 4 * s4);
;                 if (4 * s4 + 0 < r) acc -= a.x * t[4 * s4 + 0]; if (4 * s4 + 1 < r) acc -= a.y * t[4 * s4 + 1];
;                 if (4 * s4 + 2 < r) acc -= a.z * t[4 * s4 + 2]; if (4 * s4 + 3 < r) acc -= a.w * t[4 * s4 + 3]; }
;             t[r] = acc;
;         }
	v_fma_f32 v8, -v35, v240, v8
	v_fma_f32 v8, -v37, v241, v8
	v_fma_f32 v8, -v39, v242, v8
	v_fma_f32 v8, -v41, v243, v8
	ds_read_b128 v[240:243], v2 offset:13168
	s_waitcnt lgkmcnt(5)
	v_fma_f32 v8, -v43, v236, v8
	v_fma_f32 v8, -v45, v237, v8
	v_fma_f32 v8, -v47, v238, v8
	v_fma_f32 v8, -v49, v239, v8
	ds_read_b128 v[236:239], v2 offset:13184
	s_waitcnt lgkmcnt(5)
	v_fma_f32 v8, -v51, v212, v8
	v_fma_f32 v8, -v53, v213, v8
	v_fma_f32 v8, -v55, v214, v8
	v_fma_f32 v8, -v57, v215, v8
	ds_read_b128 v[212:215], v2 offset:13200
	s_waitcnt lgkmcnt(5)
	v_fma_f32 v8, -v59, v216, v8
	v_fma_f32 v8, -v61, v217, v8
	v_fma_f32 v8, -v63, v218, v8
	v_fma_f32 v8, -v65, v219, v8
	ds_read_b128 v[216:219], v2 offset:13216
	s_waitcnt lgkmcnt(5)
	v_fma_f32 v8, -v67, v232, v8
	v_fma_f32 v8, -v69, v233, v8
	v_fma_f32 v8, -v71, v234, v8
	v_fma_f32 v8, -v73, v235, v8
	ds_read_b128 v[232:235], v2 offset:13232
	s_waitcnt lgkmcnt(5)
	v_fma_f32 v8, -v75, v228, v8
	v_fma_f32 v8, -v77, v229, v8
	v_fma_f32 v8, -v79, v230, v8
	v_fma_f32 v8, -v81, v231, v8
	ds_read_b128 v[228:231], v2 offset:13248
	s_waitcnt lgkmcnt(5)
	v_fma_f32 v8, -v83, v240, v8
	v_fma_f32 v8, -v85, v241, v8
	v_fma_f32 v8, -v87, v242, v8
	v_fma_f32 v8, -v89, v243, v8
	ds_read_b128 v[240:243], v2 offset:13312
	s_waitcnt lgkmcnt(5)
	v_mov_b32_e32 v20, v237
	v_mov_b32_e32 v21, v238
	v_fma_f32 v8, -v91, v236, v8
	v_pk_mul_f32 v[20:21], v[122:123], v[20:21]
	v_mov_b32_e32 v4, v191
	v_sub_f32_e32 v8, v8, v20
	v_mov_b32_e32 v20, v239
	ds_read_b128 v[236:239], v2 offset:13328
	v_sub_f32_e32 v8, v8, v21
	s_waitcnt lgkmcnt(5)
	v_mov_b32_e32 v21, v212
	v_pk_mul_f32 v[20:21], v[140:141], v[20:21]
	v_mov_b32_e32 v12, v213
	v_sub_f32_e32 v8, v8, v20
	v_mov_b32_e32 v13, v214
	v_sub_f32_e32 v8, v8, v21
	v_pk_mul_f32 v[12:13], v[146:147], v[12:13]
	v_mov_b32_e32 v20, v215
	ds_read_b128 v[212:215], v2 offset:13344
	v_sub_f32_e32 v8, v8, v12
	s_waitcnt lgkmcnt(5)
	v_mov_b32_e32 v21, v216
	v_sub_f32_e32 v8, v8, v13
	v_pk_mul_f32 v[20:21], v[138:139], v[20:21]
	v_mov_b32_e32 v148, v121
	v_sub_f32_e32 v8, v8, v20
	v_sub_f32_e32 v8, v8, v21
	v_mov_b32_e32 v20, v217
	v_mov_b32_e32 v21, v218
	v_pk_mul_f32 v[20:21], v[136:137], v[20:21]
	s_waitcnt lgkmcnt(4)
	v_mov_b32_e32 v10, v233
	v_sub_f32_e32 v8, v8, v20
	v_sub_f32_e32 v8, v8, v21
	v_mov_b32_e32 v20, v219
	ds_read_b128 v[216:219], v2 offset:13360
	v_mov_b32_e32 v21, v232
	v_pk_mul_f32 v[20:21], v[130:131], v[20:21]
	v_mov_b32_e32 v13, v116
	v_sub_f32_e32 v8, v8, v20
	v_sub_f32_e32 v12, v8, v21
	v_mul_f32_e32 v14, v119, v234
	v_mul_f32_e32 v20, v121, v235
	ds_read_b128 v[232:235], v2 offset:13376
	v_pk_fma_f32 v[10:11], v[116:117], v[10:11], v[12:13] op_sel:[1,0,0] neg_lo:[1,0,0] neg_hi:[1,0,0]
	v_mov_b32_e32 v15, v6
	v_pk_add_f32 v[10:11], v[10:11], v[14:15] neg_lo:[0,1] neg_hi:[0,1]
	v_mov_b32_e32 v21, v7
	v_pk_add_f32 v[122:123], v[10:11], v[20:21] neg_lo:[0,1] neg_hi:[0,1]
	v_mov_b32_e32 v149, v123
	v_pk_mul_f32 v[24:25], v[4:5], v[148:149]
	v_cmp_eq_u32_e32 vcc, 52, v185
	s_waitcnt lgkmcnt(5)
	v_mov_b32_e32 v21, v230
	v_cndmask_b32_e64 v8, 0, 1.0, vcc
	s_waitcnt lgkmcnt(4)
	v_fma_f32 v4, -v30, v240, v8
	v_fma_f32 v4, -v29, v241, v4
	v_fma_f32 v4, -v27, v242, v4
	v_fma_f32 v8, -v33, v243, v4
	ds_read_b128 v[240:243], v2 offset:13392
	s_waitcnt lgkmcnt(4)
	v_fma_f32 v8, -v35, v236, v8
	v_fma_f32 v8, -v37, v237, v8
	v_fma_f32 v8, -v39, v238, v8
	v_fma_f32 v8, -v41, v239, v8
	ds_read_b128 v[236:239], v2 offset:13408
	s_waitcnt lgkmcnt(4)
	v_fma_f32 v4, -v43, v212, v8
	v_fma_f32 v4, -v45, v213, v4
	v_fma_f32 v4, -v47, v214, v4
	v_fma_f32 v8, -v49, v215, v4
	ds_read_b128 v[212:215], v2 offset:13424
	s_waitcnt lgkmcnt(4)
	v_fma_f32 v8, -v51, v216, v8
	v_fma_f32 v8, -v53, v217, v8
	v_fma_f32 v8, -v55, v218, v8
	v_fma_f32 v8, -v57, v219, v8
	ds_read_b128 v[216:219], v2 offset:13440
	s_waitcnt lgkmcnt(4)
	v_fma_f32 v4, -v59, v232, v8
	v_fma_f32 v4, -v61, v233, v4
	v_fma_f32 v4, -v63, v234, v4
	v_fma_f32 v8, -v65, v235, v4
	ds_read_b128 v[232:235], v2 offset:13456
	s_waitcnt lgkmcnt(4)
	v_fma_f32 v8, -v67, v240, v8
	v_fma_f32 v8, -v69, v241, v8
	v_fma_f32 v8, -v71, v242, v8
	v_fma_f32 v8, -v73, v243, v8
	ds_read_b128 v[240:243], v2 offset:13472
	s_waitcnt lgkmcnt(4)
	v_fma_f32 v4, -v75, v236, v8
	v_fma_f32 v4, -v77, v237, v4
	v_fma_f32 v4, -v79, v238, v4
	v_fma_f32 v8, -v81, v239, v4
	s_waitcnt lgkmcnt(3)
	v_fma_f32 v8, -v83, v212, v8
	v_fma_f32 v8, -v85, v213, v8
	v_fma_f32 v8, -v87, v214, v8
	v_fma_f32 v8, -v89, v215, v8
	s_waitcnt lgkmcnt(2)
	v_fma_f32 v4, -v91, v216, v8
	v_fma_f32 v8, -v93, v217, v4
	v_pk_mul_f32 v[4:5], v[124:125], v[218:219]
	v_pk_mov_b32 v[18:19], v[118:119], v[190:191] op_sel:[1,0]
	v_sub_f32_e32 v4, v8, v4
	v_sub_f32_e32 v8, v4, v5
	s_waitcnt lgkmcnt(1)
	v_pk_mul_f32 v[12:13], v[144:145], v[232:233]
	v_mov_b32_e32 v125, v24
	v_sub_f32_e32 v8, v8, v12
	v_sub_f32_e32 v8, v8, v13
	v_pk_mul_f32 v[12:13], v[142:143], v[234:235]
	s_waitcnt lgkmcnt(0)
	v_pk_mul_f32 v[4:5], v[134:135], v[240:241]
	v_sub_f32_e32 v8, v8, v12
	v_sub_f32_e32 v8, v8, v13
	ds_read_b128 v[12:15], v2 offset:13488
	v_sub_f32_e32 v4, v8, v4
	v_sub_f32_e32 v8, v4, v5
	v_pk_mul_f32 v[4:5], v[132:133], v[242:243]
	v_mov_b32_e32 v153, v25
	v_sub_f32_e32 v4, v8, v4
	v_sub_f32_e32 v8, v4, v5
	ds_read_b128 v[4:7], v2 offset:13504
	ds_read_b128 v[236:239], v2 offset:13568
	ds_read_b128 v[212:215], v2 offset:13584
	ds_read_b128 v[216:219], v2 offset:13600
	ds_read_b128 v[188:191], v2 offset:13616
	ds_read_b128 v[232:235], v2 offset:13632
	ds_read_b128 v[240:243], v2 offset:13648
	s_waitcnt lgkmcnt(7)
; #define LAS __attribute__((address_space(3)))
; __device__ __forceinline__ void dk_phase(const Frame& F, const bf16* QKrm, const unsigned char* KT, const unsigned char* VT, const float* BG, unsigned char* ITEMS) {
;     ...
; #pragma unroll
;         for (int r = 0; r < 64; ++r) {
;             float acc = (lane == r) ? 1.f : 0.f;
; #pragma unroll
;             for (int s4 = 0; s4 < (r + 3) / 4; ++s4) { const f32x4 a = *(const LAS f32x4*)(Amat + r * 64 + 4 * s4);
;                 if (4 * s4 + 0 < r) acc -= a.x * t[4 * s4 + 0]; if (4 * s4 + 1 < r) acc -= a.y * t[4 * s4 + 1];
;                 if (4 * s4 + 2 < r) acc -= a.z * t[4 * s4 + 2]; if (4 * s4 + 3 < r) acc -= a.w * t[4 * s4 + 3]; }
;             t[r] = acc;
;         }
	v_pk_mul_f32 v[12:13], v[126:127], v[12:13]
	v_mul_f32_e32 v124, v121, v15
	v_sub_f32_e32 v8, v8, v12
	v_sub_f32_e32 v12, v8, v13
	v_mov_b32_e32 v15, v119
	v_mov_b32_e32 v13, v118
	v_pk_fma_f32 v[12:13], v[18:19], v[14:15], v[12:13] neg_lo:[1,0,0] neg_hi:[1,0,0]
	s_waitcnt lgkmcnt(6)
	v_mul_f32_e32 v152, v123, v4
	v_pk_add_f32 v[12:13], v[12:13], v[124:125] neg_lo:[0,1] neg_hi:[0,1]
	v_cmp_eq_u32_e32 vcc, 53, v185
	v_pk_add_f32 v[124:125], v[12:13], v[152:153] neg_lo:[0,1] neg_hi:[0,1]
	v_mov_b32_e32 v152, v123
	v_mov_b32_e32 v153, v125
	v_pk_mul_f32 v[24:25], v[16:17], v[152:153]
	v_cndmask_b32_e64 v4, 0, 1.0, vcc
	s_waitcnt lgkmcnt(5)
	v_fma_f32 v4, -v30, v236, v4
	v_fma_f32 v4, -v29, v237, v4
	v_fma_f32 v4, -v27, v238, v4
	v_fma_f32 v4, -v33, v239, v4
	ds_read_b128 v[236:239], v2 offset:13664
	s_waitcnt lgkmcnt(5)
	v_fma_f32 v4, -v35, v212, v4
	v_fma_f32 v4, -v37, v213, v4
	v_fma_f32 v4, -v39, v214, v4
	v_fma_f32 v4, -v41, v215, v4
	ds_read_b128 v[212:215], v2 offset:13680
	s_waitcnt lgkmcnt(5)
	v_fma_f32 v4, -v43, v216, v4
	v_fma_f32 v4, -v45, v217, v4
	v_fma_f32 v4, -v47, v218, v4
	v_fma_f32 v4, -v49, v219, v4
	ds_read_b128 v[216:219], v2 offset:13696
	s_waitcnt lgkmcnt(5)
	v_fma_f32 v4, -v51, v188, v4
	v_fma_f32 v4, -v53, v189, v4
	v_fma_f32 v4, -v55, v190, v4
	v_fma_f32 v4, -v57, v191, v4
	ds_read_b128 v[188:191], v2 offset:13712
	s_waitcnt lgkmcnt(5)
	v_fma_f32 v4, -v59, v232, v4
	v_fma_f32 v4, -v61, v233, v4
	v_fma_f32 v4, -v63, v234, v4
	v_fma_f32 v4, -v65, v235, v4
	ds_read_b128 v[232:235], v2 offset:13824
	s_waitcnt lgkmcnt(5)
	v_fma_f32 v4, -v67, v240, v4
	v_fma_f32 v4, -v69, v241, v4
	v_fma_f32 v4, -v71, v242, v4
	v_fma_f32 v4, -v73, v243, v4
	ds_read_b128 v[240:243], v2 offset:15040
	s_waitcnt lgkmcnt(5)
	v_fma_f32 v4, -v75, v236, v4
	v_fma_f32 v4, -v77, v237, v4
	v_fma_f32 v4, -v79, v238, v4
	v_fma_f32 v4, -v81, v239, v4
	ds_read_b128 v[236:239], v2 offset:13728
	s_waitcnt lgkmcnt(5)
	v_fma_f32 v4, -v83, v212, v4
	v_fma_f32 v4, -v85, v213, v4
	v_fma_f32 v4, -v87, v214, v4
	v_fma_f32 v4, -v89, v215, v4
	ds_read_b128 v[212:215], v2 offset:13744
	s_waitcnt lgkmcnt(5)
	v_fma_f32 v4, -v91, v216, v4
	v_fma_f32 v4, -v93, v217, v4
	v_mov_b32_e32 v12, v219
	s_waitcnt lgkmcnt(4)
	v_mov_b32_e32 v13, v188
	v_fma_f32 v4, -v95, v218, v4
	ds_read_b128 v[216:219], v2 offset:13760
	v_pk_mul_f32 v[12:13], v[140:141], v[12:13]
	v_mov_b32_e32 v140, v191
	v_sub_f32_e32 v4, v4, v12
	v_sub_f32_e32 v4, v4, v13
	v_mov_b32_e32 v12, v189
	v_mov_b32_e32 v13, v190
	ds_read_b128 v[188:191], v2 offset:13840
	v_pk_mul_f32 v[16:17], v[146:147], v[12:13]
	v_sub_f32_e32 v4, v4, v16
	v_sub_f32_e32 v4, v4, v17
	v_mov_b32_e32 v8, v121
	s_waitcnt lgkmcnt(3)
	v_mov_b32_e32 v141, v236
	v_pk_mul_f32 v[140:141], v[138:139], v[140:141]
	v_mov_b32_e32 v12, v237
	v_sub_f32_e32 v4, v4, v140
	v_mov_b32_e32 v13, v238
	v_sub_f32_e32 v4, v4, v141
	v_pk_mul_f32 v[12:13], v[136:137], v[12:13]
	s_waitcnt lgkmcnt(2)
	v_mov_b32_e32 v140, v215
	v_sub_f32_e32 v4, v4, v12
	v_sub_f32_e32 v4, v4, v13
	v_mov_b32_e32 v12, v239
	ds_read_b128 v[236:239], v2 offset:13856
	v_mov_b32_e32 v13, v212
	v_pk_mul_f32 v[12:13], v[130:131], v[12:13]
	v_mov_b32_e32 v141, v121
	v_sub_f32_e32 v4, v4, v12
	v_mov_b32_e32 v12, v213
	v_sub_f32_e32 v4, v4, v13
	v_mov_b32_e32 v13, v214
	ds_read_b128 v[212:215], v2 offset:13872
	v_pk_mul_f32 v[12:13], v[128:129], v[12:13]
	v_cmp_eq_u32_e32 vcc, 54, v185
	v_sub_f32_e32 v4, v4, v12
	v_sub_f32_e32 v12, v4, v13
	v_mov_b32_e32 v13, v120
	s_waitcnt lgkmcnt(3)
	v_mul_f32_e32 v14, v123, v216
	v_mul_f32_e32 v18, v125, v217
	v_pk_fma_f32 v[8:9], v[8:9], v[140:141], v[12:13] neg_lo:[1,0,0] neg_hi:[1,0,0]
	v_mov_b32_e32 v15, v24
	v_pk_add_f32 v[8:9], v[8:9], v[14:15] neg_lo:[0,1] neg_hi:[0,1]
	v_cndmask_b32_e64 v4, 0, 1.0, vcc
	v_mov_b32_e32 v19, v25
	v_fma_f32 v4, -v30, v232, v4
	v_pk_add_f32 v[140:141], v[8:9], v[18:19] neg_lo:[0,1] neg_hi:[0,1]
	v_fma_f32 v4, -v29, v233, v4
	v_mov_b32_e32 v20, v229
	v_mov_b32_e32 v154, v125
	v_mov_b32_e32 v155, v141
	v_fma_f32 v4, -v27, v234, v4
	v_pk_mul_f32 v[160:161], v[20:21], v[154:155]
	v_fma_f32 v4, -v33, v235, v4
	ds_read_b128 v[232:235], v2 offset:13888
	s_waitcnt lgkmcnt(3)
	v_fma_f32 v4, -v35, v188, v4
	v_fma_f32 v4, -v37, v189, v4
	v_fma_f32 v4, -v39, v190, v4
	v_fma_f32 v4, -v41, v191, v4
	ds_read_b128 v[188:191], v2 offset:13904
	s_waitcnt lgkmcnt(3)
	v_fma_f32 v4, -v43, v236, v4
	v_fma_f32 v4, -v45, v237, v4
	v_fma_f32 v4, -v47, v238, v4
	v_fma_f32 v4, -v49, v239, v4
	ds_read_b128 v[236:239], v2 offset:13920
	s_waitcnt lgkmcnt(3)
	v_fma_f32 v4, -v51, v212, v4
	v_fma_f32 v4, -v53, v213, v4
	v_fma_f32 v4, -v55, v214, v4
	v_fma_f32 v4, -v57, v215, v4
	ds_read_b128 v[212:215], v2 offset:13936
	s_waitcnt lgkmcnt(3)
	v_fma_f32 v4, -v59, v232, v4
	v_fma_f32 v4, -v61, v233, v4
	v_fma_f32 v4, -v63, v234, v4
	v_fma_f32 v4, -v65, v235, v4
	ds_read_b128 v[232:235], v2 offset:13952
	s_waitcnt lgkmcnt(3)
	v_fma_f32 v4, -v67, v188, v4
	v_fma_f32 v4, -v69, v189, v4
	v_fma_f32 v4, -v71, v190, v4
	v_fma_f32 v4, -v73, v191, v4
	ds_read_b128 v[188:191], v2 offset:13968
	s_waitcnt lgkmcnt(3)
	v_fma_f32 v4, -v75, v236, v4
	v_fma_f32 v4, -v77, v237, v4
	v_fma_f32 v4, -v79, v238, v4
	v_fma_f32 v4, -v81, v239, v4
	ds_read_b128 v[236:239], v2 offset:13984
	s_waitcnt lgkmcnt(3)
	v_fma_f32 v4, -v83, v212, v4
	v_fma_f32 v4, -v85, v213, v4
	v_fma_f32 v4, -v87, v214, v4
	v_fma_f32 v4, -v89, v215, v4
	ds_read_b128 v[212:215], v2 offset:14000
	s_waitcnt lgkmcnt(3)
	v_fma_f32 v4, -v91, v232, v4
	v_fma_f32 v4, -v93, v233, v4
	v_fma_f32 v4, -v95, v234, v4
	v_fma_f32 v4, -v97, v235, v4
	s_waitcnt lgkmcnt(2)
; #define LAS __attribute__((address_space(3)))
; __device__ __forceinline__ void dk_phase(const Frame& F, const bf16* QKrm, const unsigned char* KT, const unsigned char* VT, const float* BG, unsigned char* ITEMS) {
;     ...
; #pragma unroll
;         for (int r = 0; r < 64; ++r) {
;             float acc = (lane == r) ? 1.f : 0.f;
; #pragma unroll
;             for (int s4 = 0; s4 < (r + 3) / 4; ++s4) { const f32x4 a = *(const LAS f32x4*)(Amat + r * 64 + 4 * s4);
;                 if (4 * s4 + 0 < r) acc -= a.x * t[4 * s4 + 0]; if (4 * s4 + 1 < r) acc -= a.y * t[4 * s4 + 1];
;                 if (4 * s4 + 2 < r) acc -= a.z * t[4 * s4 + 2]; if (4 * s4 + 3 < r) acc -= a.w * t[4 * s4 + 3]; }
;             t[r] = acc;
;         }
	v_pk_mul_f32 v[12:13], v[144:145], v[188:189]
	v_sub_f32_e32 v4, v4, v12
	v_sub_f32_e32 v4, v4, v13
	v_pk_mul_f32 v[12:13], v[142:143], v[190:191]
	ds_read2_b64 v[22:25], v22 offset0:186 offset1:218
	v_sub_f32_e32 v4, v4, v12
	v_sub_f32_e32 v4, v4, v13
	s_waitcnt lgkmcnt(2)
	v_pk_mul_f32 v[12:13], v[134:135], v[236:237]
	s_waitcnt lgkmcnt(1)
	v_pk_mul_f32 v[18:19], v[126:127], v[212:213]
	v_sub_f32_e32 v4, v4, v12
	v_sub_f32_e32 v4, v4, v13
	v_pk_mul_f32 v[12:13], v[132:133], v[238:239]
	v_mov_b32_e32 v21, v160
	v_sub_f32_e32 v4, v4, v12
	v_sub_f32_e32 v4, v4, v13
	ds_read_b128 v[12:15], v2 offset:14016
	ds_read_b128 v[232:235], v2 offset:14080
	ds_read_b128 v[188:191], v2 offset:14096
	ds_read_b128 v[236:239], v2 offset:14112
	v_sub_f32_e32 v4, v4, v18
	v_sub_f32_e32 v4, v4, v19
	v_pk_mul_f32 v[18:19], v[150:151], v[214:215]
	ds_read_b128 v[212:215], v2 offset:14128
	s_waitcnt lgkmcnt(5)
	v_mov_b32_e32 v9, v22
	v_sub_f32_e32 v4, v4, v18
	v_sub_f32_e32 v18, v4, v19
	s_waitcnt lgkmcnt(4)
	v_mul_f32_e32 v20, v125, v13
	v_mov_b32_e32 v13, v228
	ds_read_b128 v[228:231], v2 offset:14144
	v_mov_b32_e32 v19, v122
	v_pk_fma_f32 v[10:11], v[122:123], v[12:13], v[18:19] op_sel:[1,0,0] neg_lo:[1,0,0] neg_hi:[1,0,0]
	v_mul_f32_e32 v22, v141, v14
	v_pk_add_f32 v[10:11], v[10:11], v[20:21] neg_lo:[0,1] neg_hi:[0,1]
	v_mov_b32_e32 v23, v161
	v_pk_add_f32 v[144:145], v[10:11], v[22:23] neg_lo:[0,1] neg_hi:[0,1]
	v_cmp_eq_u32_e32 vcc, 55, v185
	v_mov_b32_e32 v156, v141
	s_nop 0
	v_cndmask_b32_e64 v4, 0, 1.0, vcc
	s_waitcnt lgkmcnt(4)
	v_fma_f32 v4, -v30, v232, v4
	v_fma_f32 v4, -v29, v233, v4
	v_fma_f32 v4, -v27, v234, v4
	v_fma_f32 v4, -v33, v235, v4
	ds_read_b128 v[232:235], v2 offset:14160
	s_waitcnt lgkmcnt(4)
	v_fma_f32 v4, -v35, v188, v4
	v_fma_f32 v4, -v37, v189, v4
	v_fma_f32 v4, -v39, v190, v4
	v_fma_f32 v4, -v41, v191, v4
	ds_read_b128 v[188:191], v2 offset:14176
	s_waitcnt lgkmcnt(4)
	v_fma_f32 v4, -v43, v236, v4
	v_fma_f32 v4, -v45, v237, v4
	v_fma_f32 v4, -v47, v238, v4
	v_fma_f32 v4, -v49, v239, v4
	ds_read_b128 v[236:239], v2 offset:14192
	s_waitcnt lgkmcnt(4)
	v_fma_f32 v4, -v51, v212, v4
	v_fma_f32 v4, -v53, v213, v4
	v_fma_f32 v4, -v55, v214, v4
	v_fma_f32 v4, -v57, v215, v4
	ds_read_b128 v[212:215], v2 offset:14208
	s_waitcnt lgkmcnt(4)
	v_fma_f32 v4, -v59, v228, v4
	v_fma_f32 v4, -v61, v229, v4
	v_fma_f32 v4, -v63, v230, v4
	v_fma_f32 v4, -v65, v231, v4
	ds_read_b128 v[228:231], v2 offset:14224
	s_waitcnt lgkmcnt(4)
	v_fma_f32 v4, -v67, v232, v4
	v_fma_f32 v4, -v69, v233, v4
	v_fma_f32 v4, -v71, v234, v4
	v_fma_f32 v4, -v73, v235, v4
	ds_read_b128 v[232:235], v2 offset:14240
	s_waitcnt lgkmcnt(4)
	v_fma_f32 v4, -v75, v188, v4
	v_fma_f32 v4, -v77, v189, v4
	v_fma_f32 v4, -v79, v190, v4
	v_fma_f32 v4, -v81, v191, v4
	ds_read_b128 v[188:191], v2 offset:14256
	s_waitcnt lgkmcnt(4)
	v_fma_f32 v4, -v83, v236, v4
	v_fma_f32 v4, -v85, v237, v4
	v_fma_f32 v4, -v87, v238, v4
	v_fma_f32 v4, -v89, v239, v4
	ds_read_b128 v[236:239], v2 offset:14272
	s_waitcnt lgkmcnt(4)
	v_fma_f32 v4, -v91, v212, v4
	v_fma_f32 v4, -v93, v213, v4
	v_fma_f32 v4, -v95, v214, v4
	v_fma_f32 v4, -v97, v215, v4
	ds_read_b128 v[212:215], v2 offset:14336
	s_waitcnt lgkmcnt(4)
	v_mov_b32_e32 v10, v229
	v_mov_b32_e32 v11, v230
	v_fma_f32 v4, -v99, v228, v4
	v_pk_mul_f32 v[18:19], v[146:147], v[10:11]
	v_sub_f32_e32 v4, v4, v18
	v_sub_f32_e32 v4, v4, v19
	v_mov_b32_e32 v22, v231
	ds_read_b128 v[228:231], v2 offset:14352
	s_waitcnt lgkmcnt(4)
	v_mov_b32_e32 v23, v232
	v_pk_mul_f32 v[22:23], v[138:139], v[22:23]
	v_mov_b32_e32 v10, v233
	v_sub_f32_e32 v4, v4, v22
	v_mov_b32_e32 v11, v234
	v_sub_f32_e32 v4, v4, v23
	v_pk_mul_f32 v[10:11], v[136:137], v[10:11]
	v_mov_b32_e32 v157, v145
	v_sub_f32_e32 v4, v4, v10
	v_sub_f32_e32 v4, v4, v11
	v_mov_b32_e32 v10, v235
	ds_read_b128 v[232:235], v2 offset:14288
	s_waitcnt lgkmcnt(4)
	v_mov_b32_e32 v11, v188
	v_pk_mul_f32 v[10:11], v[130:131], v[10:11]
	v_pk_mul_f32 v[6:7], v[6:7], v[156:157]
	v_sub_f32_e32 v4, v4, v10
	v_sub_f32_e32 v4, v4, v11
	v_mov_b32_e32 v10, v189
	v_mov_b32_e32 v11, v190
	v_pk_mul_f32 v[18:19], v[128:129], v[10:11]
	v_sub_f32_e32 v4, v4, v18
	v_sub_f32_e32 v4, v4, v19
	v_mov_b32_e32 v18, v191
	ds_read_b128 v[188:191], v2 offset:14368
	v_mov_b32_e32 v8, v219
	s_waitcnt lgkmcnt(4)
	v_mov_b32_e32 v19, v236
	v_pk_mul_f32 v[18:19], v[148:149], v[18:19]
	v_mul_f32_e32 v12, v141, v238
	v_sub_f32_e32 v4, v4, v18
	v_sub_f32_e32 v10, v4, v19
	v_mov_b32_e32 v4, v237
	v_mov_b32_e32 v11, v124
	v_mul_f32_e32 v18, v145, v239
	ds_read_b128 v[236:239], v2 offset:14384
	v_pk_fma_f32 v[4:5], v[124:125], v[4:5], v[10:11] op_sel:[1,0,0] neg_lo:[1,0,0] neg_hi:[1,0,0]
	v_mov_b32_e32 v13, v6
	v_pk_add_f32 v[4:5], v[4:5], v[12:13] neg_lo:[0,1] neg_hi:[0,1]
	v_mov_b32_e32 v19, v7
	v_pk_add_f32 v[146:147], v[4:5], v[18:19] neg_lo:[0,1] neg_hi:[0,1]
	v_mov_b32_e32 v158, v145
	v_mov_b32_e32 v159, v147
	v_pk_mul_f32 v[18:19], v[8:9], v[158:159]
	v_cmp_eq_u32_e32 vcc, 56, v185
	s_nop 1
	v_cndmask_b32_e64 v14, 0, 1.0, vcc
	s_waitcnt lgkmcnt(4)
	v_fma_f32 v6, -v30, v212, v14
	v_fma_f32 v6, -v29, v213, v6
	v_fma_f32 v6, -v27, v214, v6
	v_fma_f32 v6, -v33, v215, v6
	ds_read_b128 v[212:215], v2 offset:14400
	s_waitcnt lgkmcnt(4)
	v_fma_f32 v10, -v35, v228, v6
	v_fma_f32 v10, -v37, v229, v10
	v_fma_f32 v10, -v39, v230, v10
	v_fma_f32 v14, -v41, v231, v10
	ds_read_b128 v[228:231], v2 offset:14416
	s_waitcnt lgkmcnt(3)
	v_fma_f32 v6, -v43, v188, v14
	v_fma_f32 v6, -v45, v189, v6
	v_fma_f32 v6, -v47, v190, v6
	v_fma_f32 v6, -v49, v191, v6
	ds_read_b128 v[188:191], v2 offset:14432
	s_waitcnt lgkmcnt(3)
; #define LAS __attribute__((address_space(3)))
; __device__ __forceinline__ void dk_phase(const Frame& F, const bf16* QKrm, const unsigned char* KT, const unsigned char* VT, const float* BG, unsigned char* ITEMS) {
;     ...
; #pragma unroll
;         for (int r = 0; r < 64; ++r) {
;             float acc = (lane == r) ? 1.f : 0.f;
; #pragma unroll
;             for (int s4 = 0; s4 < (r + 3) / 4; ++s4) { const f32x4 a = *(const LAS f32x4*)(Amat + r * 64 + 4 * s4);
;                 if (4 * s4 + 0 < r) acc -= a.x * t[4 * s4 + 0]; if (4 * s4 + 1 < r) acc -= a.y * t[4 * s4 + 1];
;                 if (4 * s4 + 2 < r) acc -= a.z * t[4 * s4 + 2]; if (4 * s4 + 3 < r) acc -= a.w * t[4 * s4 + 3]; }
;             t[r] = acc;
;         }
	v_fma_f32 v10, -v51, v236, v6
	v_fma_f32 v10, -v53, v237, v10
	v_fma_f32 v10, -v55, v238, v10
	v_fma_f32 v14, -v57, v239, v10
	ds_read_b128 v[236:239], v2 offset:14448
	s_waitcnt lgkmcnt(3)
	v_fma_f32 v6, -v59, v212, v14
	v_fma_f32 v6, -v61, v213, v6
	v_fma_f32 v6, -v63, v214, v6
	v_fma_f32 v6, -v65, v215, v6
	ds_read_b128 v[212:215], v2 offset:14464
	s_waitcnt lgkmcnt(3)
	v_fma_f32 v10, -v67, v228, v6
	v_fma_f32 v10, -v69, v229, v10
	v_fma_f32 v10, -v71, v230, v10
	v_fma_f32 v14, -v73, v231, v10
	ds_read_b128 v[228:231], v2 offset:14480
	s_waitcnt lgkmcnt(3)
	v_fma_f32 v6, -v75, v188, v14
	v_fma_f32 v6, -v77, v189, v6
	v_fma_f32 v6, -v79, v190, v6
	v_fma_f32 v6, -v81, v191, v6
	ds_read_b128 v[188:191], v2 offset:14496
	s_waitcnt lgkmcnt(3)
	v_fma_f32 v10, -v83, v236, v6
	v_fma_f32 v10, -v85, v237, v10
	v_fma_f32 v10, -v87, v238, v10
	v_fma_f32 v14, -v89, v239, v10
	ds_read_b128 v[236:239], v2 offset:14512
	s_waitcnt lgkmcnt(3)
	v_fma_f32 v6, -v91, v212, v14
	v_fma_f32 v6, -v93, v213, v6
	v_fma_f32 v6, -v95, v214, v6
	v_fma_f32 v6, -v97, v215, v6
	s_waitcnt lgkmcnt(2)
	v_fma_f32 v6, -v99, v228, v6
	v_fma_f32 v14, -v101, v229, v6
	v_pk_mul_f32 v[10:11], v[142:143], v[230:231]
	v_mov_b32_e32 v5, v234
	v_sub_f32_e32 v10, v14, v10
	v_sub_f32_e32 v14, v10, v11
	s_waitcnt lgkmcnt(1)
	v_pk_mul_f32 v[6:7], v[134:135], v[188:189]
	v_pk_mov_b32 v[16:17], v[140:141], v[218:219] op_sel:[1,0]
	v_sub_f32_e32 v6, v14, v6
	v_sub_f32_e32 v14, v6, v7
	v_pk_mul_f32 v[6:7], v[132:133], v[190:191]
	v_mov_b32_e32 v23, v18
	v_sub_f32_e32 v6, v14, v6
	v_sub_f32_e32 v8, v6, v7
	s_waitcnt lgkmcnt(0)
	v_pk_mul_f32 v[6:7], v[126:127], v[236:237]
	v_pk_mul_f32 v[10:11], v[150:151], v[238:239]
	v_sub_f32_e32 v6, v8, v6
	v_sub_f32_e32 v14, v6, v7
	ds_read_b128 v[6:9], v2 offset:14528
	v_sub_f32_e32 v10, v14, v10
	v_sub_f32_e32 v14, v10, v11
	ds_read_b128 v[10:13], v2 offset:14544
	ds_read_b128 v[212:215], v2 offset:14592
	ds_read_b128 v[228:231], v2 offset:14608
	ds_read_b128 v[216:219], v2 offset:14624
	ds_read_b128 v[188:191], v2 offset:14640
	ds_read_b128 v[236:239], v2 offset:14656
	v_mov_b32_e32 v143, v19
	s_waitcnt lgkmcnt(6)
	v_pk_mul_f32 v[6:7], v[152:153], v[6:7]
	v_mul_f32_e32 v22, v145, v9
	v_sub_f32_e32 v6, v14, v6
	v_sub_f32_e32 v6, v6, v7
	v_mov_b32_e32 v9, v141
	v_mov_b32_e32 v7, v140
	v_pk_fma_f32 v[6:7], v[16:17], v[8:9], v[6:7] neg_lo:[1,0,0] neg_hi:[1,0,0]
	s_waitcnt lgkmcnt(5)
	v_mul_f32_e32 v142, v147, v10
	v_pk_add_f32 v[6:7], v[6:7], v[22:23] neg_lo:[0,1] neg_hi:[0,1]
	v_cmp_eq_u32_e32 vcc, 57, v185
	v_pk_add_f32 v[22:23], v[6:7], v[142:143] neg_lo:[0,1] neg_hi:[0,1]
	s_nop 0
	v_cndmask_b32_e64 v10, 0, 1.0, vcc
	v_mov_b32_e32 v142, v147
	v_mov_b32_e32 v143, v23
	s_waitcnt lgkmcnt(4)
	v_fma_f32 v6, -v30, v212, v10
	v_fma_f32 v6, -v29, v213, v6
	v_fma_f32 v6, -v27, v214, v6
	v_fma_f32 v6, -v33, v215, v6
	ds_read_b128 v[212:215], v2 offset:14672
	s_waitcnt lgkmcnt(4)
	v_fma_f32 v10, -v35, v228, v6
	v_fma_f32 v10, -v37, v229, v10
	v_fma_f32 v10, -v39, v230, v10
	v_fma_f32 v10, -v41, v231, v10
	ds_read_b128 v[228:231], v2 offset:14688
	s_waitcnt lgkmcnt(4)
	v_fma_f32 v6, -v43, v216, v10
	v_fma_f32 v6, -v45, v217, v6
	v_fma_f32 v6, -v47, v218, v6
	v_fma_f32 v6, -v49, v219, v6
	ds_read_b128 v[216:219], v2 offset:14704
	s_waitcnt lgkmcnt(4)
	v_fma_f32 v10, -v51, v188, v6
	v_fma_f32 v10, -v53, v189, v10
	v_fma_f32 v10, -v55, v190, v10
	v_fma_f32 v10, -v57, v191, v10
	ds_read_b128 v[188:191], v2 offset:14720
	s_waitcnt lgkmcnt(4)
	v_fma_f32 v6, -v59, v236, v10
	v_fma_f32 v6, -v61, v237, v6
	v_fma_f32 v6, -v63, v238, v6
	v_fma_f32 v6, -v65, v239, v6
	ds_read_b128 v[236:239], v2 offset:14736
	s_waitcnt lgkmcnt(4)
	v_fma_f32 v10, -v67, v212, v6
	v_fma_f32 v10, -v69, v213, v10
	v_fma_f32 v10, -v71, v214, v10
	v_fma_f32 v10, -v73, v215, v10
	ds_read_b128 v[212:215], v2 offset:14752
	s_waitcnt lgkmcnt(4)
	v_fma_f32 v6, -v75, v228, v10
	v_fma_f32 v6, -v77, v229, v6
	v_fma_f32 v6, -v79, v230, v6
	v_fma_f32 v6, -v81, v231, v6
	ds_read_b128 v[228:231], v2 offset:14768
	s_waitcnt lgkmcnt(4)
	v_fma_f32 v10, -v83, v216, v6
	v_fma_f32 v10, -v85, v217, v10
	v_fma_f32 v10, -v87, v218, v10
	v_fma_f32 v10, -v89, v219, v10
	ds_read_b128 v[216:219], v2 offset:14784
	s_waitcnt lgkmcnt(4)
	v_fma_f32 v6, -v91, v188, v10
	v_fma_f32 v6, -v93, v189, v6
	v_fma_f32 v6, -v95, v190, v6
	v_fma_f32 v6, -v97, v191, v6
	ds_read_b128 v[188:191], v2 offset:14800
	s_waitcnt lgkmcnt(4)
	v_fma_f32 v10, -v99, v236, v6
	v_fma_f32 v10, -v101, v237, v10
	v_mov_b32_e32 v160, v239
	v_fma_f32 v10, -v103, v238, v10
	ds_read_b128 v[236:239], v2 offset:14864
	s_waitcnt lgkmcnt(4)
	v_mov_b32_e32 v161, v212
	v_pk_mul_f32 v[138:139], v[138:139], v[160:161]
	v_pk_mul_f32 v[24:25], v[24:25], v[142:143]
	v_sub_f32_e32 v6, v10, v138
	v_sub_f32_e32 v10, v6, v139
	v_mov_b32_e32 v6, v213
	v_mov_b32_e32 v7, v214
	v_pk_mul_f32 v[6:7], v[136:137], v[6:7]
	s_waitcnt lgkmcnt(3)
	v_mov_b32_e32 v138, v231
	v_sub_f32_e32 v6, v10, v6
	v_sub_f32_e32 v8, v6, v7
	v_mov_b32_e32 v6, v215
	ds_read_b128 v[212:215], v2 offset:14848
	v_mov_b32_e32 v7, v228
	v_pk_mul_f32 v[6:7], v[130:131], v[6:7]
	v_mov_b32_e32 v14, v145
	v_sub_f32_e32 v6, v8, v6
	v_sub_f32_e32 v10, v6, v7
	v_mov_b32_e32 v6, v229
	v_mov_b32_e32 v7, v230
	v_pk_mul_f32 v[16:17], v[128:129], v[6:7]
	v_sub_f32_e32 v10, v10, v16
	v_sub_f32_e32 v10, v10, v17
	v_cmp_eq_u32_e32 vcc, 58, v185
	s_waitcnt lgkmcnt(3)
	v_mov_b32_e32 v139, v216
	v_pk_mul_f32 v[138:139], v[148:149], v[138:139]
	v_sub_f32_e32 v6, v10, v138
	v_sub_f32_e32 v10, v6, v139
	v_mov_b32_e32 v6, v217
	v_mov_b32_e32 v7, v218
	v_pk_mul_f32 v[6:7], v[154:155], v[6:7]
	v_mov_b32_e32 v138, v219
	v_sub_f32_e32 v6, v10, v6
	v_sub_f32_e32 v6, v6, v7
	v_mov_b32_e32 v139, v145
	v_mov_b32_e32 v7, v144
	s_waitcnt lgkmcnt(2)
; #define LAS __attribute__((address_space(3)))
; __device__ __forceinline__ void dk_phase(const Frame& F, const bf16* QKrm, const unsigned char* KT, const unsigned char* VT, const float* BG, unsigned char* ITEMS) {
;     ...
; #pragma unroll
;         for (int r = 0; r < 64; ++r) {
;             float acc = (lane == r) ? 1.f : 0.f;
; #pragma unroll
;             for (int s4 = 0; s4 < (r + 3) / 4; ++s4) { const f32x4 a = *(const LAS f32x4*)(Amat + r * 64 + 4 * s4);
;                 if (4 * s4 + 0 < r) acc -= a.x * t[4 * s4 + 0]; if (4 * s4 + 1 < r) acc -= a.y * t[4 * s4 + 1];
;                 if (4 * s4 + 2 < r) acc -= a.z * t[4 * s4 + 2]; if (4 * s4 + 3 < r) acc -= a.w * t[4 * s4 + 3]; }
;             t[r] = acc;
;         }
	v_mul_f32_e32 v8, v147, v188
	v_pk_fma_f32 v[6:7], v[14:15], v[138:139], v[6:7] neg_lo:[1,0,0] neg_hi:[1,0,0]
	v_mov_b32_e32 v9, v24
	v_mul_f32_e32 v16, v23, v189
	v_pk_add_f32 v[6:7], v[6:7], v[8:9] neg_lo:[0,1] neg_hi:[0,1]
	v_mov_b32_e32 v17, v25
	v_pk_add_f32 v[24:25], v[6:7], v[16:17] neg_lo:[0,1] neg_hi:[0,1]
	v_cndmask_b32_e64 v10, 0, 1.0, vcc
	v_add_u32_e32 v31, 0x3800, v2
	ds_read2_b64 v[14:17], v31 offset0:60 offset1:92
	ds_read_b128 v[228:231], v2 offset:14880
	ds_read_b128 v[216:219], v2 offset:14896
	v_mov_b32_e32 v4, v233
	s_waitcnt lgkmcnt(3)
	v_fma_f32 v6, -v30, v212, v10
	v_fma_f32 v6, -v29, v213, v6
	v_fma_f32 v6, -v27, v214, v6
	v_fma_f32 v6, -v33, v215, v6
	ds_read_b128 v[212:215], v2 offset:14912
	v_fma_f32 v10, -v35, v236, v6
	v_fma_f32 v10, -v37, v237, v10
	v_fma_f32 v10, -v39, v238, v10
	v_fma_f32 v10, -v41, v239, v10
	ds_read_b128 v[236:239], v2 offset:14928
	s_waitcnt lgkmcnt(3)
	v_fma_f32 v6, -v43, v228, v10
	v_fma_f32 v6, -v45, v229, v6
	v_fma_f32 v6, -v47, v230, v6
	v_fma_f32 v6, -v49, v231, v6
	ds_read_b128 v[228:231], v2 offset:14944
	s_waitcnt lgkmcnt(3)
	v_fma_f32 v10, -v51, v216, v6
	v_fma_f32 v10, -v53, v217, v10
	v_fma_f32 v10, -v55, v218, v10
	v_fma_f32 v10, -v57, v219, v10
	ds_read_b128 v[216:219], v2 offset:14960
	s_waitcnt lgkmcnt(3)
	v_fma_f32 v6, -v59, v212, v10
	v_fma_f32 v6, -v61, v213, v6
	v_fma_f32 v6, -v63, v214, v6
	v_fma_f32 v6, -v65, v215, v6
	ds_read_b128 v[212:215], v2 offset:14976
	s_waitcnt lgkmcnt(3)
	v_fma_f32 v10, -v67, v236, v6
	v_fma_f32 v10, -v69, v237, v10
	v_fma_f32 v10, -v71, v238, v10
	v_fma_f32 v10, -v73, v239, v10
	ds_read_b128 v[236:239], v2 offset:14992
	s_waitcnt lgkmcnt(3)
	v_fma_f32 v6, -v75, v228, v10
	v_fma_f32 v6, -v77, v229, v6
	v_fma_f32 v6, -v79, v230, v6
	v_fma_f32 v6, -v81, v231, v6
	ds_read_b128 v[228:231], v2 offset:15008
	s_waitcnt lgkmcnt(3)
	v_fma_f32 v10, -v83, v216, v6
	v_fma_f32 v10, -v85, v217, v10
	v_fma_f32 v10, -v87, v218, v10
	v_fma_f32 v10, -v89, v219, v10
	ds_read_b128 v[216:219], v2 offset:15024
	s_waitcnt lgkmcnt(3)
	v_fma_f32 v6, -v91, v212, v10
	v_fma_f32 v6, -v93, v213, v6
	v_fma_f32 v6, -v95, v214, v6
	v_fma_f32 v6, -v97, v215, v6
	s_waitcnt lgkmcnt(2)
	v_fma_f32 v10, -v99, v236, v6
	v_fma_f32 v10, -v101, v237, v10
	v_fma_f32 v10, -v103, v238, v10
	v_fma_f32 v10, -v105, v239, v10
	s_waitcnt lgkmcnt(1)
	v_pk_mul_f32 v[6:7], v[134:135], v[228:229]
	v_mov_b32_e32 v138, v23
	v_sub_f32_e32 v6, v10, v6
	v_sub_f32_e32 v10, v6, v7
	v_pk_mul_f32 v[6:7], v[132:133], v[230:231]
	v_mov_b32_e32 v139, v25
	v_sub_f32_e32 v6, v10, v6
	v_sub_f32_e32 v8, v6, v7
	s_waitcnt lgkmcnt(0)
	v_pk_mul_f32 v[6:7], v[126:127], v[216:217]
	v_pk_mul_f32 v[180:181], v[4:5], v[138:139]
	v_sub_f32_e32 v6, v8, v6
	v_sub_f32_e32 v8, v6, v7
	v_pk_mul_f32 v[6:7], v[150:151], v[218:219]
	v_mov_b32_e32 v5, v14
	v_sub_f32_e32 v6, v8, v6
	v_sub_f32_e32 v10, v6, v7
	ds_read_b128 v[6:9], v2 offset:15056
	ds_read_b128 v[212:215], v2 offset:15104
	ds_read_b128 v[236:239], v2 offset:15120
	ds_read_b128 v[228:231], v2 offset:15136
	ds_read_b128 v[216:219], v2 offset:15152
	v_pk_mul_f32 v[14:15], v[152:153], v[240:241]
	v_mov_b32_e32 v135, v180
	v_sub_f32_e32 v10, v10, v14
	v_sub_f32_e32 v10, v10, v15
	v_pk_mul_f32 v[14:15], v[156:157], v[242:243]
	ds_read_b128 v[240:243], v2 offset:15168
	s_waitcnt lgkmcnt(5)
	v_mul_f32_e32 v134, v23, v7
	v_sub_f32_e32 v10, v10, v14
	v_sub_f32_e32 v14, v10, v15
	v_mov_b32_e32 v7, v232
	ds_read_b128 v[232:235], v2 offset:15184
	v_mov_b32_e32 v15, v146
	v_pk_fma_f32 v[6:7], v[146:147], v[6:7], v[14:15] op_sel:[1,0,0] neg_lo:[1,0,0] neg_hi:[1,0,0]
	v_mul_f32_e32 v160, v25, v8
	v_pk_add_f32 v[6:7], v[6:7], v[134:135] neg_lo:[0,1] neg_hi:[0,1]
	v_mov_b32_e32 v161, v181
	v_pk_add_f32 v[20:21], v[6:7], v[160:161] neg_lo:[0,1] neg_hi:[0,1]
	v_mov_b32_e32 v160, v25
	v_mov_b32_e32 v161, v21
	v_cmp_eq_u32_e32 vcc, 59, v185
	v_pk_mul_f32 v[6:7], v[12:13], v[160:161]
	s_nop 0
	v_cndmask_b32_e64 v8, 0, 1.0, vcc
	s_waitcnt lgkmcnt(5)
	v_fma_f32 v8, -v30, v212, v8
	v_fma_f32 v8, -v29, v213, v8
	v_fma_f32 v8, -v27, v214, v8
	v_fma_f32 v8, -v33, v215, v8
	ds_read_b128 v[212:215], v2 offset:15200
	s_waitcnt lgkmcnt(5)
	v_fma_f32 v8, -v35, v236, v8
	v_fma_f32 v8, -v37, v237, v8
	v_fma_f32 v8, -v39, v238, v8
	v_fma_f32 v8, -v41, v239, v8
	ds_read_b128 v[236:239], v2 offset:15216
	s_waitcnt lgkmcnt(5)
	v_fma_f32 v8, -v43, v228, v8
	v_fma_f32 v8, -v45, v229, v8
	v_fma_f32 v8, -v47, v230, v8
	v_fma_f32 v8, -v49, v231, v8
	ds_read_b128 v[228:231], v2 offset:15232
	s_waitcnt lgkmcnt(5)
	v_fma_f32 v8, -v51, v216, v8
	v_fma_f32 v8, -v53, v217, v8
	v_fma_f32 v8, -v55, v218, v8
	v_fma_f32 v8, -v57, v219, v8
	ds_read_b128 v[216:219], v2 offset:15248
	s_waitcnt lgkmcnt(5)
	v_fma_f32 v8, -v59, v240, v8
	v_fma_f32 v8, -v61, v241, v8
	v_fma_f32 v8, -v63, v242, v8
	v_fma_f32 v8, -v65, v243, v8
	ds_read_b128 v[240:243], v2 offset:15264
	s_waitcnt lgkmcnt(5)
	v_fma_f32 v8, -v67, v232, v8
	v_fma_f32 v8, -v69, v233, v8
	v_fma_f32 v8, -v71, v234, v8
	v_fma_f32 v8, -v73, v235, v8
	ds_read_b128 v[232:235], v2 offset:15280
	s_waitcnt lgkmcnt(5)
	v_fma_f32 v8, -v75, v212, v8
	v_fma_f32 v8, -v77, v213, v8
	v_fma_f32 v8, -v79, v214, v8
	v_fma_f32 v8, -v81, v215, v8
	ds_read_b128 v[212:215], v2 offset:15296
	s_waitcnt lgkmcnt(5)
	v_fma_f32 v8, -v83, v236, v8
	v_fma_f32 v8, -v85, v237, v8
	v_fma_f32 v8, -v87, v238, v8
	v_fma_f32 v8, -v89, v239, v8
	ds_read_b128 v[236:239], v2 offset:15312
	s_waitcnt lgkmcnt(5)
	v_fma_f32 v8, -v91, v228, v8
	v_fma_f32 v8, -v93, v229, v8
	v_fma_f32 v8, -v95, v230, v8
	v_fma_f32 v8, -v97, v231, v8
	ds_read_b128 v[228:231], v2 offset:15328
	s_waitcnt lgkmcnt(5)
; #define LAS __attribute__((address_space(3)))
; __device__ __forceinline__ void dk_phase(const Frame& F, const bf16* QKrm, const unsigned char* KT, const unsigned char* VT, const float* BG, unsigned char* ITEMS) {
;     ...
; #pragma unroll
;         for (int r = 0; r < 64; ++r) {
;             float acc = (lane == r) ? 1.f : 0.f;
; #pragma unroll
;             for (int s4 = 0; s4 < (r + 3) / 4; ++s4) { const f32x4 a = *(const LAS f32x4*)(Amat + r * 64 + 4 * s4);
;                 if (4 * s4 + 0 < r) acc -= a.x * t[4 * s4 + 0]; if (4 * s4 + 1 < r) acc -= a.y * t[4 * s4 + 1];
;                 if (4 * s4 + 2 < r) acc -= a.z * t[4 * s4 + 2]; if (4 * s4 + 3 < r) acc -= a.w * t[4 * s4 + 3]; }
;             t[r] = acc;
;         }
	v_fma_f32 v8, -v99, v216, v8
	v_fma_f32 v8, -v101, v217, v8
	v_fma_f32 v8, -v103, v218, v8
	v_fma_f32 v8, -v105, v219, v8
	ds_read_b128 v[216:219], v2 offset:15360
	s_waitcnt lgkmcnt(5)
	v_mov_b32_e32 v134, v241
	v_mov_b32_e32 v135, v242
	v_fma_f32 v8, -v107, v240, v8
	v_pk_mul_f32 v[134:135], v[136:137], v[134:135]
	s_waitcnt lgkmcnt(4)
	v_mov_b32_e32 v162, v235
	v_sub_f32_e32 v8, v8, v134
	v_sub_f32_e32 v8, v8, v135
	v_mov_b32_e32 v134, v243
	ds_read_b128 v[240:243], v2 offset:15376
	v_mov_b32_e32 v135, v232
	v_pk_mul_f32 v[134:135], v[130:131], v[134:135]
	v_mov_b32_e32 v12, v233
	v_sub_f32_e32 v8, v8, v134
	v_sub_f32_e32 v8, v8, v135
	v_mov_b32_e32 v13, v234
	ds_read_b128 v[232:235], v2 offset:15392
	v_pk_mul_f32 v[12:13], v[128:129], v[12:13]
	v_mov_b32_e32 v4, v191
	v_sub_f32_e32 v8, v8, v12
	v_sub_f32_e32 v8, v8, v13
	s_waitcnt lgkmcnt(5)
	v_mov_b32_e32 v163, v212
	v_pk_mul_f32 v[162:163], v[148:149], v[162:163]
	v_mov_b32_e32 v134, v213
	v_sub_f32_e32 v8, v8, v162
	v_mov_b32_e32 v135, v214
	v_sub_f32_e32 v8, v8, v163
	v_pk_mul_f32 v[134:135], v[154:155], v[134:135]
	s_waitcnt lgkmcnt(4)
	v_mov_b32_e32 v10, v237
	v_sub_f32_e32 v8, v8, v134
	v_sub_f32_e32 v8, v8, v135
	v_mov_b32_e32 v134, v215
	ds_read_b128 v[212:215], v2 offset:15408
	v_mov_b32_e32 v135, v236
	v_pk_mul_f32 v[134:135], v[158:159], v[134:135]
	v_mov_b32_e32 v13, v22
	v_sub_f32_e32 v8, v8, v134
	v_sub_f32_e32 v12, v8, v135
	v_mul_f32_e32 v14, v25, v238
	v_mul_f32_e32 v134, v21, v239
	ds_read_b128 v[236:239], v2 offset:15424
	v_pk_fma_f32 v[10:11], v[22:23], v[10:11], v[12:13] op_sel:[1,0,0] neg_lo:[1,0,0] neg_hi:[1,0,0]
	v_mov_b32_e32 v15, v6
	v_pk_add_f32 v[10:11], v[10:11], v[14:15] neg_lo:[0,1] neg_hi:[0,1]
	v_mov_b32_e32 v135, v7
	v_pk_add_f32 v[134:135], v[10:11], v[134:135] neg_lo:[0,1] neg_hi:[0,1]
	v_mov_b32_e32 v136, v21
	v_mov_b32_e32 v137, v135
	v_pk_mul_f32 v[176:177], v[4:5], v[136:137]
	v_cmp_eq_u32_e32 vcc, 60, v185
	s_waitcnt lgkmcnt(5)
	v_mov_b32_e32 v163, v230
	v_cndmask_b32_e64 v8, 0, 1.0, vcc
	s_waitcnt lgkmcnt(4)
	v_fma_f32 v4, -v30, v216, v8
	v_fma_f32 v4, -v29, v217, v4
	v_fma_f32 v4, -v27, v218, v4
	v_fma_f32 v8, -v33, v219, v4
	ds_read_b128 v[216:219], v2 offset:15440
	s_waitcnt lgkmcnt(4)
	v_fma_f32 v8, -v35, v240, v8
	v_fma_f32 v8, -v37, v241, v8
	v_fma_f32 v8, -v39, v242, v8
	v_fma_f32 v8, -v41, v243, v8
	ds_read_b128 v[240:243], v2 offset:15456
	s_waitcnt lgkmcnt(4)
	v_fma_f32 v4, -v43, v232, v8
	v_fma_f32 v4, -v45, v233, v4
	v_fma_f32 v4, -v47, v234, v4
	v_fma_f32 v8, -v49, v235, v4
	ds_read_b128 v[232:235], v2 offset:15472
	s_waitcnt lgkmcnt(4)
	v_fma_f32 v8, -v51, v212, v8
	v_fma_f32 v8, -v53, v213, v8
	v_fma_f32 v8, -v55, v214, v8
	v_fma_f32 v8, -v57, v215, v8
	ds_read_b128 v[212:215], v2 offset:15488
	s_waitcnt lgkmcnt(4)
	v_fma_f32 v4, -v59, v236, v8
	v_fma_f32 v4, -v61, v237, v4
	v_fma_f32 v4, -v63, v238, v4
	v_fma_f32 v8, -v65, v239, v4
	ds_read_b128 v[236:239], v2 offset:15504
	s_waitcnt lgkmcnt(4)
	v_fma_f32 v8, -v67, v216, v8
	v_fma_f32 v8, -v69, v217, v8
	v_fma_f32 v8, -v71, v218, v8
	v_fma_f32 v8, -v73, v219, v8
	ds_read_b128 v[216:219], v2 offset:15520
	s_waitcnt lgkmcnt(4)
	v_fma_f32 v4, -v75, v240, v8
	v_fma_f32 v4, -v77, v241, v4
	v_fma_f32 v4, -v79, v242, v4
	v_fma_f32 v8, -v81, v243, v4
	ds_read_b128 v[240:243], v2 offset:15536
	s_waitcnt lgkmcnt(4)
	v_fma_f32 v8, -v83, v232, v8
	v_fma_f32 v8, -v85, v233, v8
	v_fma_f32 v8, -v87, v234, v8
	v_fma_f32 v8, -v89, v235, v8
	ds_read_b128 v[232:235], v2 offset:15552
	s_waitcnt lgkmcnt(4)
	v_fma_f32 v4, -v91, v212, v8
	v_fma_f32 v4, -v93, v213, v4
	v_fma_f32 v4, -v95, v214, v4
	v_fma_f32 v8, -v97, v215, v4
	s_waitcnt lgkmcnt(3)
	v_fma_f32 v8, -v99, v236, v8
	v_fma_f32 v8, -v101, v237, v8
	v_fma_f32 v8, -v103, v238, v8
	v_fma_f32 v8, -v105, v239, v8
	s_waitcnt lgkmcnt(2)
	v_fma_f32 v4, -v107, v216, v8
	v_fma_f32 v8, -v109, v217, v4
	v_pk_mul_f32 v[4:5], v[132:133], v[218:219]
	v_pk_mov_b32 v[18:19], v[24:25], v[190:191] op_sel:[1,0]
	v_sub_f32_e32 v4, v8, v4
	v_sub_f32_e32 v8, v4, v5
	s_waitcnt lgkmcnt(1)
	v_pk_mul_f32 v[12:13], v[126:127], v[240:241]
	v_mov_b32_e32 v133, v176
	v_sub_f32_e32 v8, v8, v12
	v_sub_f32_e32 v8, v8, v13
	v_pk_mul_f32 v[12:13], v[150:151], v[242:243]
	s_waitcnt lgkmcnt(0)
	v_pk_mul_f32 v[4:5], v[152:153], v[232:233]
	v_sub_f32_e32 v8, v8, v12
	v_sub_f32_e32 v8, v8, v13
	ds_read_b128 v[12:15], v2 offset:15568
	v_sub_f32_e32 v4, v8, v4
	v_sub_f32_e32 v8, v4, v5
	v_pk_mul_f32 v[4:5], v[156:157], v[234:235]
	v_mov_b32_e32 v179, v177
	v_sub_f32_e32 v4, v8, v4
	v_sub_f32_e32 v8, v4, v5
	ds_read_b128 v[4:7], v2 offset:15584
	ds_read_b128 v[212:215], v2 offset:15616
	ds_read_b128 v[236:239], v2 offset:15632
	ds_read_b128 v[216:219], v2 offset:15648
	ds_read_b128 v[188:191], v2 offset:15664
	ds_read_b128 v[240:243], v2 offset:15680
	ds_read_b128 v[232:235], v2 offset:15696
	s_waitcnt lgkmcnt(7)
	v_pk_mul_f32 v[12:13], v[142:143], v[12:13]
	v_mul_f32_e32 v132, v21, v15
	v_sub_f32_e32 v8, v8, v12
	v_sub_f32_e32 v12, v8, v13
	v_mov_b32_e32 v15, v25
	v_mov_b32_e32 v13, v24
	v_pk_fma_f32 v[12:13], v[18:19], v[14:15], v[12:13] neg_lo:[1,0,0] neg_hi:[1,0,0]
	s_waitcnt lgkmcnt(6)
	v_mul_f32_e32 v178, v135, v4
	v_pk_add_f32 v[12:13], v[12:13], v[132:133] neg_lo:[0,1] neg_hi:[0,1]
	v_cmp_eq_u32_e32 vcc, 61, v185
	v_pk_add_f32 v[18:19], v[12:13], v[178:179] neg_lo:[0,1] neg_hi:[0,1]
	s_nop 0
	v_cndmask_b32_e64 v4, 0, 1.0, vcc
	v_mov_b32_e32 v132, v135
	v_mov_b32_e32 v133, v19
	s_waitcnt lgkmcnt(5)
	v_fma_f32 v4, -v30, v212, v4
	v_fma_f32 v4, -v29, v213, v4
	v_fma_f32 v4, -v27, v214, v4
	v_fma_f32 v4, -v33, v215, v4
	ds_read_b128 v[212:215], v2 offset:15712
	s_waitcnt lgkmcnt(5)
; #define LAS __attribute__((address_space(3)))
; __device__ __forceinline__ void dk_phase(const Frame& F, const bf16* QKrm, const unsigned char* KT, const unsigned char* VT, const float* BG, unsigned char* ITEMS) {
;     ...
; #pragma unroll
;         for (int r = 0; r < 64; ++r) {
;             float acc = (lane == r) ? 1.f : 0.f;
; #pragma unroll
;             for (int s4 = 0; s4 < (r + 3) / 4; ++s4) { const f32x4 a = *(const LAS f32x4*)(Amat + r * 64 + 4 * s4);
;                 if (4 * s4 + 0 < r) acc -= a.x * t[4 * s4 + 0]; if (4 * s4 + 1 < r) acc -= a.y * t[4 * s4 + 1];
;                 if (4 * s4 + 2 < r) acc -= a.z * t[4 * s4 + 2]; if (4 * s4 + 3 < r) acc -= a.w * t[4 * s4 + 3]; }
;             t[r] = acc;
;         }
	v_fma_f32 v4, -v35, v236, v4
	v_fma_f32 v4, -v37, v237, v4
	v_fma_f32 v4, -v39, v238, v4
	v_fma_f32 v4, -v41, v239, v4
	ds_read_b128 v[236:239], v2 offset:15728
	s_waitcnt lgkmcnt(5)
	v_fma_f32 v4, -v43, v216, v4
	v_fma_f32 v4, -v45, v217, v4
	v_fma_f32 v4, -v47, v218, v4
	v_fma_f32 v4, -v49, v219, v4
	ds_read_b128 v[216:219], v2 offset:15744
	s_waitcnt lgkmcnt(5)
	v_fma_f32 v4, -v51, v188, v4
	v_fma_f32 v4, -v53, v189, v4
	v_fma_f32 v4, -v55, v190, v4
	v_fma_f32 v4, -v57, v191, v4
	ds_read_b128 v[188:191], v2 offset:15760
	s_waitcnt lgkmcnt(5)
	v_fma_f32 v4, -v59, v240, v4
	v_fma_f32 v4, -v61, v241, v4
	v_fma_f32 v4, -v63, v242, v4
	v_fma_f32 v4, -v65, v243, v4
	ds_read_b128 v[240:243], v2 offset:15776
	s_waitcnt lgkmcnt(5)
	v_fma_f32 v4, -v67, v232, v4
	v_fma_f32 v4, -v69, v233, v4
	v_fma_f32 v4, -v71, v234, v4
	v_fma_f32 v4, -v73, v235, v4
	ds_read_b128 v[232:235], v2 offset:15792
	s_waitcnt lgkmcnt(5)
	v_fma_f32 v4, -v75, v212, v4
	v_fma_f32 v4, -v77, v213, v4
	v_fma_f32 v4, -v79, v214, v4
	v_fma_f32 v4, -v81, v215, v4
	ds_read_b128 v[212:215], v2 offset:15824
	s_waitcnt lgkmcnt(5)
	v_fma_f32 v4, -v83, v236, v4
	v_fma_f32 v4, -v85, v237, v4
	v_fma_f32 v4, -v87, v238, v4
	v_fma_f32 v4, -v89, v239, v4
	ds_read_b128 v[236:239], v2 offset:15808
	s_waitcnt lgkmcnt(5)
	v_fma_f32 v4, -v91, v216, v4
	v_fma_f32 v4, -v93, v217, v4
	v_fma_f32 v4, -v95, v218, v4
	v_fma_f32 v4, -v97, v219, v4
	ds_read_b128 v[216:219], v2 offset:15872
	s_waitcnt lgkmcnt(5)
	v_fma_f32 v4, -v99, v188, v4
	v_fma_f32 v4, -v101, v189, v4
	v_fma_f32 v4, -v103, v190, v4
	v_fma_f32 v4, -v105, v191, v4
	ds_read_b128 v[188:191], v2 offset:15840
	v_pk_mul_f32 v[180:181], v[16:17], v[132:133]
	s_waitcnt lgkmcnt(5)
	v_fma_f32 v4, -v107, v240, v4
	v_fma_f32 v4, -v109, v241, v4
	v_mov_b32_e32 v12, v243
	s_waitcnt lgkmcnt(4)
	v_mov_b32_e32 v13, v232
	v_fma_f32 v4, -v111, v242, v4
	ds_read_b128 v[240:243], v2 offset:15888
	v_pk_mul_f32 v[12:13], v[130:131], v[12:13]
	v_sub_f32_e32 v4, v4, v12
	v_sub_f32_e32 v4, v4, v13
	v_mov_b32_e32 v12, v233
	v_mov_b32_e32 v13, v234
	v_pk_mul_f32 v[16:17], v[128:129], v[12:13]
	v_sub_f32_e32 v4, v4, v16
	v_sub_f32_e32 v4, v4, v17
	v_mov_b32_e32 v16, v235
	ds_read_b128 v[232:235], v2 offset:15904
	v_mov_b32_e32 v8, v21
	s_waitcnt lgkmcnt(4)
	v_mov_b32_e32 v17, v236
	v_pk_mul_f32 v[16:17], v[148:149], v[16:17]
	v_mov_b32_e32 v12, v237
	v_sub_f32_e32 v4, v4, v16
	v_mov_b32_e32 v13, v238
	v_sub_f32_e32 v4, v4, v17
	v_pk_mul_f32 v[12:13], v[154:155], v[12:13]
	v_sub_f32_e32 v4, v4, v12
	v_sub_f32_e32 v4, v4, v13
	v_mov_b32_e32 v12, v239
	ds_read_b128 v[236:239], v2 offset:15920
	v_mov_b32_e32 v13, v212
	v_pk_mul_f32 v[12:13], v[158:159], v[12:13]
	v_sub_f32_e32 v4, v4, v12
	v_sub_f32_e32 v4, v4, v13
	v_mov_b32_e32 v12, v213
	v_mov_b32_e32 v13, v214
	v_pk_mul_f32 v[12:13], v[138:139], v[12:13]
	v_mov_b32_e32 v132, v215
	ds_read_b128 v[212:215], v2 offset:15936
	v_sub_f32_e32 v4, v4, v12
	v_sub_f32_e32 v12, v4, v13
	v_mov_b32_e32 v133, v21
	v_mov_b32_e32 v13, v20
	s_waitcnt lgkmcnt(4)
	v_mul_f32_e32 v14, v135, v188
	v_mul_f32_e32 v130, v19, v189
	v_pk_fma_f32 v[8:9], v[8:9], v[132:133], v[12:13] neg_lo:[1,0,0] neg_hi:[1,0,0]
	v_mov_b32_e32 v15, v180
	v_pk_add_f32 v[8:9], v[8:9], v[14:15] neg_lo:[0,1] neg_hi:[0,1]
	v_mov_b32_e32 v131, v181
	v_pk_add_f32 v[8:9], v[8:9], v[130:131] neg_lo:[0,1] neg_hi:[0,1]
	v_mov_b32_e32 v162, v229
	v_mov_b32_e32 v130, v19
	v_mov_b32_e32 v131, v9
	v_cmp_eq_u32_e32 vcc, 62, v185
	v_pk_mul_f32 v[162:163], v[162:163], v[130:131]
	s_nop 0
	v_cndmask_b32_e64 v4, 0, 1.0, vcc
	v_fma_f32 v4, -v30, v216, v4
	v_fma_f32 v4, -v29, v217, v4
	v_fma_f32 v4, -v27, v218, v4
	v_fma_f32 v4, -v33, v219, v4
	ds_read_b128 v[216:219], v2 offset:15952
	s_waitcnt lgkmcnt(4)
	v_fma_f32 v4, -v35, v240, v4
	v_fma_f32 v4, -v37, v241, v4
	v_fma_f32 v4, -v39, v242, v4
	v_fma_f32 v4, -v41, v243, v4
	ds_read_b128 v[240:243], v2 offset:15968
	s_waitcnt lgkmcnt(4)
	v_fma_f32 v4, -v43, v232, v4
	v_fma_f32 v4, -v45, v233, v4
	v_fma_f32 v4, -v47, v234, v4
	v_fma_f32 v4, -v49, v235, v4
	ds_read_b128 v[232:235], v2 offset:15984
	s_waitcnt lgkmcnt(4)
	v_fma_f32 v4, -v51, v236, v4
	v_fma_f32 v4, -v53, v237, v4
	v_fma_f32 v4, -v55, v238, v4
	v_fma_f32 v4, -v57, v239, v4
	ds_read_b128 v[236:239], v2 offset:16000
	s_waitcnt lgkmcnt(4)
	v_fma_f32 v4, -v59, v212, v4
	v_fma_f32 v4, -v61, v213, v4
	v_fma_f32 v4, -v63, v214, v4
	v_fma_f32 v4, -v65, v215, v4
	ds_read_b128 v[212:215], v2 offset:16016
	s_waitcnt lgkmcnt(4)
	v_fma_f32 v4, -v67, v216, v4
	v_fma_f32 v4, -v69, v217, v4
	v_fma_f32 v4, -v71, v218, v4
	v_fma_f32 v4, -v73, v219, v4
	ds_read_b128 v[216:219], v2 offset:16032
	s_waitcnt lgkmcnt(4)
	v_fma_f32 v4, -v75, v240, v4
	v_fma_f32 v4, -v77, v241, v4
	v_fma_f32 v4, -v79, v242, v4
	v_fma_f32 v4, -v81, v243, v4
	s_waitcnt lgkmcnt(3)
	v_fma_f32 v4, -v83, v232, v4
	v_fma_f32 v4, -v85, v233, v4
	v_fma_f32 v4, -v87, v234, v4
	v_fma_f32 v4, -v89, v235, v4
	s_waitcnt lgkmcnt(2)
	v_fma_f32 v4, -v91, v236, v4
	v_fma_f32 v4, -v93, v237, v4
	v_fma_f32 v4, -v95, v238, v4
	v_fma_f32 v4, -v97, v239, v4
	s_waitcnt lgkmcnt(1)
	v_fma_f32 v4, -v99, v212, v4
	v_fma_f32 v4, -v101, v213, v4
	v_fma_f32 v4, -v103, v214, v4
	ds_read2_b64 v[12:15], v31 offset0:190 offset1:222
	ds_read_b128 v[240:243], v2 offset:16048
	v_fma_f32 v4, -v105, v215, v4
	s_waitcnt lgkmcnt(2)
	v_fma_f32 v4, -v107, v216, v4
	v_fma_f32 v4, -v109, v217, v4
	v_fma_f32 v4, -v111, v218, v4
	v_fma_f32 v4, -v113, v219, v4
	ds_read_b128 v[176:179], v2 offset:16064
	ds_read_b128 v[232:235], v2 offset:16080
	v_fma_f32 v31, -v190, v9, v8
	v_mov_b32_e32 v16, v191
	s_waitcnt lgkmcnt(3)
	v_mov_b32_e32 v17, v12
	s_waitcnt lgkmcnt(2)
; #define LAS __attribute__((address_space(3)))
; __device__ __forceinline__ void dk_phase(const Frame& F, const bf16* QKrm, const unsigned char* KT, const unsigned char* VT, const float* BG, unsigned char* ITEMS) {
;     ...
; #pragma unroll
;         for (int r = 0; r < 64; ++r) {
;             float acc = (lane == r) ? 1.f : 0.f;
; #pragma unroll
;             for (int s4 = 0; s4 < (r + 3) / 4; ++s4) { const f32x4 a = *(const LAS f32x4*)(Amat + r * 64 + 4 * s4);
;                 if (4 * s4 + 0 < r) acc -= a.x * t[4 * s4 + 0]; if (4 * s4 + 1 < r) acc -= a.y * t[4 * s4 + 1];
;                 if (4 * s4 + 2 < r) acc -= a.z * t[4 * s4 + 2]; if (4 * s4 + 3 < r) acc -= a.w * t[4 * s4 + 3]; }
;             t[r] = acc;
;         }
;         asm volatile("" ::: "memory"); __builtin_amdgcn_sched_barrier(0);
;         {
;             const int c = dir ? 63 - lane : lane; const float bc = betaL[c], wc = bc * __expf(gamL[c]);
	v_pk_mul_f32 v[12:13], v[126:127], v[240:241]
	v_mov_b32_e32 v127, v162
	v_sub_f32_e32 v4, v4, v12
	v_sub_f32_e32 v4, v4, v13
	v_pk_mul_f32 v[12:13], v[150:151], v[242:243]
	v_sub_f32_e32 v4, v4, v12
	v_sub_f32_e32 v4, v4, v13
	s_waitcnt lgkmcnt(1)
	v_pk_mul_f32 v[12:13], v[152:153], v[176:177]
	ds_read_b128 v[150:153], v2 offset:16096
	ds_read_b128 v[236:239], v2 offset:16128
	ds_read_b128 v[212:215], v2 offset:16144
	ds_read_b128 v[216:219], v2 offset:16160
	ds_read_b128 v[188:191], v2 offset:16176
	ds_read_b128 v[240:243], v2 offset:16192
	v_sub_f32_e32 v4, v4, v12
	v_sub_f32_e32 v4, v4, v13
	v_pk_mul_f32 v[12:13], v[156:157], v[178:179]
	v_cmp_eq_u32_e32 vcc, 63, v185
	v_sub_f32_e32 v4, v4, v12
	v_sub_f32_e32 v4, v4, v13
	s_waitcnt lgkmcnt(6)
	v_pk_mul_f32 v[12:13], v[142:143], v[232:233]
	s_waitcnt lgkmcnt(5)
	v_mul_f32_e32 v126, v19, v151
	v_sub_f32_e32 v4, v4, v12
	v_sub_f32_e32 v4, v4, v13
	v_pk_mul_f32 v[12:13], v[160:161], v[234:235]
	ds_read_b128 v[232:235], v2 offset:16208
	v_mov_b32_e32 v151, v228
	ds_read_b128 v[228:231], v2 offset:16224
	v_sub_f32_e32 v4, v4, v12
	v_sub_f32_e32 v12, v4, v13
	v_mov_b32_e32 v13, v134
	v_pk_fma_f32 v[10:11], v[134:135], v[150:151], v[12:13] op_sel:[1,0,0] neg_lo:[1,0,0] neg_hi:[1,0,0]
	v_mul_f32_e32 v130, v9, v152
	v_pk_add_f32 v[10:11], v[10:11], v[126:127] neg_lo:[0,1] neg_hi:[0,1]
	v_mov_b32_e32 v131, v163
	v_pk_add_f32 v[10:11], v[10:11], v[130:131] neg_lo:[0,1] neg_hi:[0,1]
	v_fma_f32 v142, -v153, v11, v10
	v_cndmask_b32_e64 v4, 0, 1.0, vcc
	v_mov_b32_e32 v12, v9
	s_waitcnt lgkmcnt(6)
	v_fma_f32 v4, -v30, v236, v4
	v_fma_f32 v4, -v29, v237, v4
	v_fma_f32 v4, -v27, v238, v4
	v_fma_f32 v4, -v33, v239, v4
	ds_read_b128 v[236:239], v2 offset:16240
	s_waitcnt lgkmcnt(6)
	v_fma_f32 v4, -v35, v212, v4
	v_fma_f32 v4, -v37, v213, v4
	v_fma_f32 v4, -v39, v214, v4
	v_fma_f32 v4, -v41, v215, v4
	ds_read_b128 v[212:215], v2 offset:16256
	s_waitcnt lgkmcnt(6)
	v_fma_f32 v4, -v43, v216, v4
	v_fma_f32 v4, -v45, v217, v4
	v_fma_f32 v4, -v47, v218, v4
	v_fma_f32 v4, -v49, v219, v4
	ds_read_b128 v[216:219], v2 offset:16272
	s_waitcnt lgkmcnt(6)
	v_fma_f32 v4, -v51, v188, v4
	v_fma_f32 v4, -v53, v189, v4
	v_fma_f32 v4, -v55, v190, v4
	v_fma_f32 v4, -v57, v191, v4
	ds_read_b128 v[188:191], v2 offset:16288
	s_waitcnt lgkmcnt(6)
	v_fma_f32 v4, -v59, v240, v4
	v_fma_f32 v4, -v61, v241, v4
	v_fma_f32 v4, -v63, v242, v4
	v_fma_f32 v4, -v65, v243, v4
	s_waitcnt lgkmcnt(5)
	v_fma_f32 v4, -v67, v232, v4
	v_fma_f32 v4, -v69, v233, v4
	v_fma_f32 v4, -v71, v234, v4
	v_fma_f32 v4, -v73, v235, v4
	s_waitcnt lgkmcnt(4)
	v_fma_f32 v4, -v75, v228, v4
	v_fma_f32 v4, -v77, v229, v4
	v_fma_f32 v4, -v79, v230, v4
	v_fma_f32 v4, -v81, v231, v4
	s_waitcnt lgkmcnt(3)
	v_fma_f32 v4, -v83, v236, v4
	v_fma_f32 v4, -v85, v237, v4
	v_fma_f32 v4, -v87, v238, v4
	v_fma_f32 v4, -v89, v239, v4
	s_waitcnt lgkmcnt(2)
	v_fma_f32 v4, -v91, v212, v4
	v_fma_f32 v4, -v93, v213, v4
	v_fma_f32 v4, -v95, v214, v4
	v_fma_f32 v4, -v97, v215, v4
	s_waitcnt lgkmcnt(1)
	v_fma_f32 v4, -v99, v216, v4
	v_fma_f32 v4, -v101, v217, v4
	v_fma_f32 v4, -v103, v218, v4
	v_fma_f32 v4, -v105, v219, v4
	ds_read_b128 v[150:153], v2 offset:16304
	ds_read_b128 v[240:243], v2 offset:16320
	ds_read_b128 v[232:235], v2 offset:16336
	ds_read_b128 v[228:231], v2 offset:16352
	v_mov_b32_e32 v13, v11
	v_pk_mul_f32 v[6:7], v[6:7], v[12:13]
	s_waitcnt lgkmcnt(4)
	v_fma_f32 v4, -v107, v188, v4
	v_fma_f32 v4, -v109, v189, v4
	s_waitcnt lgkmcnt(3)
	v_mov_b32_e32 v12, v151
	v_mov_b32_e32 v13, v152
	v_pk_mul_f32 v[12:13], v[128:129], v[12:13]
	v_fma_f32 v4, -v111, v190, v4
	v_fma_f32 v4, -v113, v191, v4
	v_fma_f32 v4, -v115, v150, v4
	v_sub_f32_e32 v4, v4, v12
	v_sub_f32_e32 v4, v4, v13
	v_mov_b32_e32 v12, v153
	s_waitcnt lgkmcnt(2)
	v_mov_b32_e32 v13, v240
	v_pk_mul_f32 v[12:13], v[148:149], v[12:13]
	s_nop 0
	v_sub_f32_e32 v4, v4, v12
	v_sub_f32_e32 v4, v4, v13
	v_mov_b32_e32 v12, v241
	v_mov_b32_e32 v13, v242
	v_pk_mul_f32 v[12:13], v[154:155], v[12:13]
	s_nop 0
	v_sub_f32_e32 v4, v4, v12
	v_sub_f32_e32 v4, v4, v13
	v_mov_b32_e32 v12, v243
	s_waitcnt lgkmcnt(1)
	v_mov_b32_e32 v13, v232
	v_pk_mul_f32 v[12:13], v[158:159], v[12:13]
	v_sub_f32_e32 v4, v4, v12
	v_sub_f32_e32 v4, v4, v13
	v_mov_b32_e32 v12, v233
	v_mov_b32_e32 v13, v234
	v_pk_mul_f32 v[12:13], v[138:139], v[12:13]
	s_nop 0
	v_sub_f32_e32 v4, v4, v12
	v_sub_f32_e32 v4, v4, v13
	v_mov_b32_e32 v12, v235
	s_waitcnt lgkmcnt(0)
	v_mov_b32_e32 v13, v228
	v_pk_mul_f32 v[12:13], v[136:137], v[12:13]
	ds_read_b128 v[130:133], v2 offset:16368
	v_sub_f32_e32 v2, v4, v12
	v_sub_f32_e32 v12, v2, v13
	v_mov_b32_e32 v4, v229
	v_mov_b32_e32 v13, v18
	v_mul_f32_e32 v126, v9, v230
	v_pk_fma_f32 v[4:5], v[18:19], v[4:5], v[12:13] op_sel:[1,0,0] neg_lo:[1,0,0] neg_hi:[1,0,0]
	v_mov_b32_e32 v127, v6
	v_mul_f32_e32 v128, v11, v231
	v_pk_add_f32 v[4:5], v[4:5], v[126:127] neg_lo:[0,1] neg_hi:[0,1]
	v_mov_b32_e32 v129, v7
	v_pk_add_f32 v[4:5], v[4:5], v[128:129] neg_lo:[0,1] neg_hi:[0,1]
	v_mov_b32_e32 v6, v11
	v_mov_b32_e32 v7, v5
	v_pk_mul_f32 v[6:7], v[16:17], v[6:7]
	v_mov_b32_e32 v12, v5
	v_sub_f32_e32 v2, v31, v6
	v_sub_f32_e32 v13, v2, v7
	v_pk_mul_f32 v[6:7], v[14:15], v[12:13]
	s_waitcnt lgkmcnt(0)
	v_mov_b32_e32 v14, v131
	v_sub_f32_e32 v2, v142, v6
	v_sub_f32_e32 v7, v2, v7
	v_mov_b32_e32 v15, v132
	v_mov_b32_e32 v6, v13
	v_fma_f32 v16, -v5, v130, v4
	v_pk_mul_f32 v[14:15], v[14:15], v[6:7]
	s_nop 0
	v_sub_f32_e32 v2, v16, v14
	v_sub_f32_e32 v2, v2, v15
	v_sub_u32_e32 v6, 63, v185
	v_cndmask_b32_e64 v6, v6, v185, s[40:41]
	v_lshl_add_u32 v12, v6, 2, s53
	ds_read2st64_b32 v[14:15], v12 offset0:68 offset1:69
	v_lshl_add_u32 v6, v6, 1, s53
	v_readlane_b32 s21, v255, 29
	s_waitcnt lgkmcnt(0)
; #define LAS __attribute__((address_space(3)))
; __device__ __forceinline__ unsigned pk2(float lo, float hi) { const f32x2_cv v = {lo, hi}; const bf16x2_cv b = __builtin_convertvector(v, bf16x2_cv); return __builtin_bit_cast(unsigned, b); }
; __device__ __forceinline__ void dk_phase(const Frame& F, const bf16* QKrm, const unsigned char* KT, const unsigned char* VT, const float* BG, unsigned char* ITEMS) {
;     ...
;             const int c = dir ? 63 - lane : lane; const float bc = betaL[c], wc = bc * __expf(gamL[c]);
;             asm volatile("s_waitcnt lgkmcnt(0)" ::: "memory");
; #pragma unroll
;             for (int rp = 0; rp < 64; ++rp) { const int r = dir ? 63 - rp : rp;
;                 const unsigned w2 = pk2(t[rp] * wc, t[rp] * bc);
;                 *(LAS unsigned short*)(TW + r * TROW + c * 2) = (unsigned short)(w2 & 0xffffu);
;                 *(LAS unsigned short*)(TU + r * TROW + c * 2) = (unsigned short)(w2 >> 16); }
	s_waitcnt lgkmcnt(0)
	v_mul_f32_e32 v12, 0x3fb8aa3b, v14
	v_exp_f32_e32 v12, v12
	s_nop 0
	v_mul_f32_e32 v14, v15, v12
	v_pk_mul_f32 v[16:17], v[30:31], v[14:15] op_sel_hi:[0,1]
	v_cvt_pk_bf16_f32 v12, v16, v17
	v_add_u32_e32 v16, s21, v6
	ds_write_b16 v16, v12
	ds_write_b16_d16_hi v16, v12 offset:8704
	v_pk_mul_f32 v[16:17], v[28:29], v[14:15] op_sel:[1,0]
	v_readlane_b32 s21, v255, 30
	v_cvt_pk_bf16_f32 v12, v16, v17
	v_pk_mul_f32 v[8:9], v[8:9], v[14:15] op_sel:[1,0]
	v_add_u32_e32 v16, s21, v6
	ds_write_b16 v16, v12
	ds_write_b16_d16_hi v16, v12 offset:8704
	v_pk_mul_f32 v[16:17], v[26:27], v[14:15] op_sel:[1,0]
	v_readlane_b32 s21, v255, 31
	v_cvt_pk_bf16_f32 v12, v16, v17
	v_cvt_pk_bf16_f32 v8, v8, v9
	v_add_u32_e32 v16, s21, v6
	ds_write_b16 v16, v12
	ds_write_b16_d16_hi v16, v12 offset:8704
	v_pk_mul_f32 v[16:17], v[32:33], v[14:15] op_sel:[1,0]
	v_readlane_b32 s21, v255, 32
	v_cvt_pk_bf16_f32 v12, v16, v17
	v_add_u32_e32 v9, s63, v6
	v_add_u32_e32 v16, s21, v6
	ds_write_b16 v16, v12
	ds_write_b16_d16_hi v16, v12 offset:8704
	v_pk_mul_f32 v[16:17], v[34:35], v[14:15] op_sel:[1,0]
	v_readlane_b32 s21, v255, 33
	v_cvt_pk_bf16_f32 v12, v16, v17
	v_pk_mul_f32 v[4:5], v[4:5], v[14:15] op_sel:[1,0]
	v_add_u32_e32 v16, s21, v6
	ds_write_b16 v16, v12
	ds_write_b16_d16_hi v16, v12 offset:8704
	v_pk_mul_f32 v[16:17], v[36:37], v[14:15] op_sel:[1,0]
	v_readlane_b32 s21, v255, 34
	v_cvt_pk_bf16_f32 v12, v16, v17
	v_cvt_pk_bf16_f32 v4, v4, v5
	v_add_u32_e32 v16, s21, v6
	ds_write_b16 v16, v12
	ds_write_b16_d16_hi v16, v12 offset:8704
	v_pk_mul_f32 v[16:17], v[38:39], v[14:15] op_sel:[1,0]
	v_readlane_b32 s21, v255, 35
	v_cvt_pk_bf16_f32 v12, v16, v17
	v_add_u32_e32 v5, s75, v6
	v_add_u32_e32 v16, s21, v6
	ds_write_b16 v16, v12
	ds_write_b16_d16_hi v16, v12 offset:8704
	v_pk_mul_f32 v[16:17], v[40:41], v[14:15] op_sel:[1,0]
	v_readlane_b32 s21, v255, 36
	v_cvt_pk_bf16_f32 v12, v16, v17
	s_nop 0
	v_add_u32_e32 v16, s21, v6
	ds_write_b16 v16, v12
	ds_write_b16_d16_hi v16, v12 offset:8704
	v_pk_mul_f32 v[16:17], v[42:43], v[14:15] op_sel:[1,0]
	v_readlane_b32 s21, v255, 37
	v_cvt_pk_bf16_f32 v12, v16, v17
	s_nop 0
	v_add_u32_e32 v16, s21, v6
	ds_write_b16 v16, v12
	ds_write_b16_d16_hi v16, v12 offset:8704
	v_pk_mul_f32 v[16:17], v[44:45], v[14:15] op_sel:[1,0]
	v_readlane_b32 s21, v255, 38
	v_cvt_pk_bf16_f32 v12, v16, v17
	s_nop 0
	v_add_u32_e32 v16, s21, v6
	ds_write_b16 v16, v12
	ds_write_b16_d16_hi v16, v12 offset:8704
	v_pk_mul_f32 v[16:17], v[46:47], v[14:15] op_sel:[1,0]
	v_readlane_b32 s21, v255, 39
	v_cvt_pk_bf16_f32 v12, v16, v17
	s_nop 0
	v_add_u32_e32 v16, s21, v6
	ds_write_b16 v16, v12
	ds_write_b16_d16_hi v16, v12 offset:8704
	v_pk_mul_f32 v[16:17], v[48:49], v[14:15] op_sel:[1,0]
	v_readlane_b32 s21, v255, 40
	v_cvt_pk_bf16_f32 v12, v16, v17
	s_nop 0
	v_add_u32_e32 v16, s21, v6
	ds_write_b16 v16, v12
	ds_write_b16_d16_hi v16, v12 offset:8704
	v_pk_mul_f32 v[16:17], v[50:51], v[14:15] op_sel:[1,0]
	v_readlane_b32 s21, v255, 41
	v_cvt_pk_bf16_f32 v12, v16, v17
	s_nop 0
	v_add_u32_e32 v16, s21, v6
	ds_write_b16 v16, v12
	ds_write_b16_d16_hi v16, v12 offset:8704
	v_pk_mul_f32 v[16:17], v[52:53], v[14:15] op_sel:[1,0]
	v_readlane_b32 s21, v255, 42
	v_cvt_pk_bf16_f32 v12, v16, v17
	s_nop 0
	v_add_u32_e32 v16, s21, v6
	ds_write_b16 v16, v12
	ds_write_b16_d16_hi v16, v12 offset:8704
	v_pk_mul_f32 v[16:17], v[54:55], v[14:15] op_sel:[1,0]
	v_readlane_b32 s21, v255, 43
	v_cvt_pk_bf16_f32 v12, v16, v17
	s_nop 0
	v_add_u32_e32 v16, s21, v6
	ds_write_b16 v16, v12
	ds_write_b16_d16_hi v16, v12 offset:8704
	v_pk_mul_f32 v[16:17], v[56:57], v[14:15] op_sel:[1,0]
	v_readlane_b32 s21, v255, 44
	v_cvt_pk_bf16_f32 v12, v16, v17
	s_nop 0
	v_add_u32_e32 v16, s21, v6
	ds_write_b16 v16, v12
	ds_write_b16_d16_hi v16, v12 offset:8704
	v_pk_mul_f32 v[16:17], v[58:59], v[14:15] op_sel:[1,0]
	v_readlane_b32 s21, v255, 45
	v_cvt_pk_bf16_f32 v12, v16, v17
	s_nop 0
	v_add_u32_e32 v16, s21, v6
	ds_write_b16 v16, v12
	ds_write_b16_d16_hi v16, v12 offset:8704
	v_pk_mul_f32 v[16:17], v[60:61], v[14:15] op_sel:[1,0]
	v_readlane_b32 s21, v255, 46
	v_cvt_pk_bf16_f32 v12, v16, v17
	s_nop 0
	v_add_u32_e32 v16, s21, v6
	ds_write_b16 v16, v12
	ds_write_b16_d16_hi v16, v12 offset:8704
	v_pk_mul_f32 v[16:17], v[62:63], v[14:15] op_sel:[1,0]
	v_readlane_b32 s21, v255, 47
	v_cvt_pk_bf16_f32 v12, v16, v17
	s_nop 0
	v_add_u32_e32 v16, s21, v6
	ds_write_b16 v16, v12
	ds_write_b16_d16_hi v16, v12 offset:8704
	v_pk_mul_f32 v[16:17], v[64:65], v[14:15] op_sel:[1,0]
	v_readlane_b32 s21, v255, 48
	v_cvt_pk_bf16_f32 v12, v16, v17
	s_nop 0
	v_add_u32_e32 v16, s21, v6
	ds_write_b16 v16, v12
	ds_write_b16_d16_hi v16, v12 offset:8704
	v_pk_mul_f32 v[16:17], v[66:67], v[14:15] op_sel:[1,0]
	v_readlane_b32 s21, v255, 49
	v_cvt_pk_bf16_f32 v12, v16, v17
	s_nop 0
	v_add_u32_e32 v16, s21, v6
	ds_write_b16 v16, v12
	ds_write_b16_d16_hi v16, v12 offset:8704
	v_pk_mul_f32 v[16:17], v[68:69], v[14:15] op_sel:[1,0]
	s_nop 0
	v_cvt_pk_bf16_f32 v12, v16, v17
	v_add_u32_e32 v16, s91, v6
	ds_write_b16 v16, v12
	ds_write_b16_d16_hi v16, v12 offset:8704
	v_pk_mul_f32 v[16:17], v[70:71], v[14:15] op_sel:[1,0]
	s_nop 0
	v_cvt_pk_bf16_f32 v12, v16, v17
	v_add_u32_e32 v16, s92, v6
	ds_write_b16 v16, v12
	ds_write_b16_d16_hi v16, v12 offset:8704
	v_pk_mul_f32 v[16:17], v[72:73], v[14:15] op_sel:[1,0]
	s_nop 0
	v_cvt_pk_bf16_f32 v12, v16, v17
	v_add_u32_e32 v16, s93, v6
	ds_write_b16 v16, v12
	ds_write_b16_d16_hi v16, v12 offset:8704
	v_pk_mul_f32 v[16:17], v[74:75], v[14:15] op_sel:[1,0]
	s_nop 0
	v_cvt_pk_bf16_f32 v12, v16, v17
	v_add_u32_e32 v16, s94, v6
	ds_write_b16 v16, v12
	ds_write_b16_d16_hi v16, v12 offset:8704
; #define LAS __attribute__((address_space(3)))
; __device__ __forceinline__ unsigned pk2(float lo, float hi) { const f32x2_cv v = {lo, hi}; const bf16x2_cv b = __builtin_convertvector(v, bf16x2_cv); return __builtin_bit_cast(unsigned, b); }
; __device__ __forceinline__ void dk_phase(const Frame& F, const bf16* QKrm, const unsigned char* KT, const unsigned char* VT, const float* BG, unsigned char* ITEMS) {
;     ...
;         {
;             const int c = dir ? 63 - lane : lane; const float bc = betaL[c], wc = bc * __expf(gamL[c]);
;             asm volatile("s_waitcnt lgkmcnt(0)" ::: "memory");
; #pragma unroll
;             for (int rp = 0; rp < 64; ++rp) { const int r = dir ? 63 - rp : rp;
;                 const unsigned w2 = pk2(t[rp] * wc, t[rp] * bc);
;                 *(LAS unsigned short*)(TW + r * TROW + c * 2) = (unsigned short)(w2 & 0xffffu);
;                 *(LAS unsigned short*)(TU + r * TROW + c * 2) = (unsigned short)(w2 >> 16); }
;         }
	v_pk_mul_f32 v[16:17], v[76:77], v[14:15] op_sel:[1,0]
	s_nop 0
	v_cvt_pk_bf16_f32 v12, v16, v17
	v_add_u32_e32 v16, s95, v6
	ds_write_b16 v16, v12
	ds_write_b16_d16_hi v16, v12 offset:8704
	v_pk_mul_f32 v[16:17], v[78:79], v[14:15] op_sel:[1,0]
	s_nop 0
	v_cvt_pk_bf16_f32 v12, v16, v17
	v_add_u32_e32 v16, s96, v6
	ds_write_b16 v16, v12
	ds_write_b16_d16_hi v16, v12 offset:8704
	v_pk_mul_f32 v[16:17], v[80:81], v[14:15] op_sel:[1,0]
	s_nop 0
	v_cvt_pk_bf16_f32 v12, v16, v17
	v_add_u32_e32 v16, s97, v6
	ds_write_b16 v16, v12
	ds_write_b16_d16_hi v16, v12 offset:8704
	v_pk_mul_f32 v[16:17], v[82:83], v[14:15] op_sel:[1,0]
	s_nop 0
	v_cvt_pk_bf16_f32 v12, v16, v17
	v_add_u32_e32 v16, s0, v6
	ds_write_b16 v16, v12
	ds_write_b16_d16_hi v16, v12 offset:8704
	v_pk_mul_f32 v[16:17], v[84:85], v[14:15] op_sel:[1,0]
	s_nop 0
	v_cvt_pk_bf16_f32 v12, v16, v17
	v_add_u32_e32 v16, s1, v6
	ds_write_b16 v16, v12
	ds_write_b16_d16_hi v16, v12 offset:8704
	v_pk_mul_f32 v[16:17], v[86:87], v[14:15] op_sel:[1,0]
	s_nop 0
	v_cvt_pk_bf16_f32 v12, v16, v17
	v_add_u32_e32 v16, s4, v6
	ds_write_b16 v16, v12
	ds_write_b16_d16_hi v16, v12 offset:8704
	v_pk_mul_f32 v[16:17], v[88:89], v[14:15] op_sel:[1,0]
	s_nop 0
	v_cvt_pk_bf16_f32 v12, v16, v17
	v_add_u32_e32 v16, s65, v6
	ds_write_b16 v16, v12 offset:4216
	ds_write_b16_d16_hi v16, v12 offset:12920
	v_pk_mul_f32 v[16:17], v[90:91], v[14:15] op_sel:[1,0]
	s_nop 0
	v_cvt_pk_bf16_f32 v12, v16, v17
	v_add_u32_e32 v16, s82, v6
	ds_write_b16 v16, v12
	ds_write_b16_d16_hi v16, v12 offset:8704
	v_pk_mul_f32 v[16:17], v[92:93], v[14:15] op_sel:[1,0]
	s_nop 0
	v_cvt_pk_bf16_f32 v12, v16, v17
	v_add_u32_e32 v16, s5, v6
	ds_write_b16 v16, v12
	ds_write_b16_d16_hi v16, v12 offset:8704
	v_pk_mul_f32 v[16:17], v[94:95], v[14:15] op_sel:[1,0]
	s_nop 0
	v_cvt_pk_bf16_f32 v12, v16, v17
	v_add_u32_e32 v16, s6, v6
	ds_write_b16 v16, v12
	ds_write_b16_d16_hi v16, v12 offset:8704
	v_pk_mul_f32 v[16:17], v[96:97], v[14:15] op_sel:[1,0]
	s_nop 0
	v_cvt_pk_bf16_f32 v12, v16, v17
	v_add_u32_e32 v16, s7, v6
	ds_write_b16 v16, v12
	ds_write_b16_d16_hi v16, v12 offset:8704
	v_pk_mul_f32 v[16:17], v[98:99], v[14:15] op_sel:[1,0]
	s_nop 0
	v_cvt_pk_bf16_f32 v12, v16, v17
	v_add_u32_e32 v16, s8, v6
	ds_write_b16 v16, v12
	ds_write_b16_d16_hi v16, v12 offset:8704
	v_pk_mul_f32 v[16:17], v[100:101], v[14:15] op_sel:[1,0]
	s_nop 0
	v_cvt_pk_bf16_f32 v12, v16, v17
	v_add_u32_e32 v16, s9, v6
	ds_write_b16 v16, v12
	ds_write_b16_d16_hi v16, v12 offset:8704
	v_pk_mul_f32 v[16:17], v[102:103], v[14:15] op_sel:[1,0]
	s_nop 0
	v_cvt_pk_bf16_f32 v12, v16, v17
	v_add_u32_e32 v16, s10, v6
	ds_write_b16 v16, v12
	ds_write_b16_d16_hi v16, v12 offset:8704
	v_pk_mul_f32 v[16:17], v[104:105], v[14:15] op_sel:[1,0]
	s_nop 0
	v_cvt_pk_bf16_f32 v12, v16, v17
	v_add_u32_e32 v16, s11, v6
	ds_write_b16 v16, v12
	ds_write_b16_d16_hi v16, v12 offset:8704
	v_pk_mul_f32 v[16:17], v[106:107], v[14:15] op_sel:[1,0]
	s_nop 0
	v_cvt_pk_bf16_f32 v12, v16, v17
	v_add_u32_e32 v16, s12, v6
	ds_write_b16 v16, v12
	ds_write_b16_d16_hi v16, v12 offset:8704
	v_pk_mul_f32 v[16:17], v[108:109], v[14:15] op_sel:[1,0]
	s_nop 0
	v_cvt_pk_bf16_f32 v12, v16, v17
	v_add_u32_e32 v16, s13, v6
	ds_write_b16 v16, v12
	ds_write_b16_d16_hi v16, v12 offset:8704
	v_pk_mul_f32 v[16:17], v[110:111], v[14:15] op_sel:[1,0]
	s_nop 0
	v_cvt_pk_bf16_f32 v12, v16, v17
	v_add_u32_e32 v16, s80, v6
	ds_write_b16 v16, v12
	ds_write_b16_d16_hi v16, v12 offset:8704
	v_pk_mul_f32 v[16:17], v[112:113], v[14:15] op_sel:[1,0]
	s_nop 0
	v_cvt_pk_bf16_f32 v12, v16, v17
	v_add_u32_e32 v16, s68, v6
	ds_write_b16 v16, v12
	ds_write_b16_d16_hi v16, v12 offset:8704
	v_pk_mul_f32 v[16:17], v[114:115], v[14:15] op_sel:[1,0]
	s_nop 0
	v_cvt_pk_bf16_f32 v12, v16, v17
	v_add_u32_e32 v16, s69, v6
	ds_write_b16 v16, v12
	ds_write_b16_d16_hi v16, v12 offset:8704
	v_pk_mul_f32 v[16:17], v[116:117], v[14:15] op_sel:[1,0]
	s_nop 0
	v_cvt_pk_bf16_f32 v12, v16, v17
	v_add_u32_e32 v16, s72, v6
	ds_write_b16 v16, v12
	ds_write_b16_d16_hi v16, v12 offset:8704
	v_pk_mul_f32 v[16:17], v[118:119], v[14:15] op_sel:[1,0]
	s_nop 0
	v_cvt_pk_bf16_f32 v12, v16, v17
	v_add_u32_e32 v16, s73, v6
	ds_write_b16 v16, v12
	ds_write_b16_d16_hi v16, v12 offset:8704
	v_pk_mul_f32 v[16:17], v[120:121], v[14:15] op_sel:[1,0]
	s_nop 0
	v_cvt_pk_bf16_f32 v12, v16, v17
	v_add_u32_e32 v16, s14, v6
	ds_write_b16 v16, v12
	ds_write_b16_d16_hi v16, v12 offset:8704
	v_pk_mul_f32 v[16:17], v[122:123], v[14:15] op_sel:[1,0]
	s_nop 0
	v_cvt_pk_bf16_f32 v12, v16, v17
	v_add_u32_e32 v16, s15, v6
	ds_write_b16 v16, v12
	ds_write_b16_d16_hi v16, v12 offset:8704
	v_pk_mul_f32 v[16:17], v[124:125], v[14:15] op_sel:[1,0]
	s_nop 0
	v_cvt_pk_bf16_f32 v12, v16, v17
	v_add_u32_e32 v16, s28, v6
	ds_write_b16 v16, v12
	ds_write_b16_d16_hi v16, v12 offset:8704
	v_pk_mul_f32 v[16:17], v[140:141], v[14:15] op_sel:[1,0]
	s_nop 0
	v_cvt_pk_bf16_f32 v12, v16, v17
	v_add_u32_e32 v16, s29, v6
	ds_write_b16 v16, v12
	ds_write_b16_d16_hi v16, v12 offset:8704
	v_pk_mul_f32 v[16:17], v[144:145], v[14:15] op_sel:[1,0]
	s_nop 0
	v_cvt_pk_bf16_f32 v12, v16, v17
	v_add_u32_e32 v16, s38, v6
	ds_write_b16 v16, v12
	ds_write_b16_d16_hi v16, v12 offset:8704
	v_pk_mul_f32 v[16:17], v[146:147], v[14:15] op_sel:[1,0]
	s_nop 0
	v_cvt_pk_bf16_f32 v12, v16, v17
	v_add_u32_e32 v16, s39, v6
	ds_write_b16 v16, v12
	ds_write_b16_d16_hi v16, v12 offset:8704
	v_pk_mul_f32 v[16:17], v[22:23], v[14:15] op_sel:[1,0]
	s_nop 0
	v_cvt_pk_bf16_f32 v12, v16, v17
	v_add_u32_e32 v16, s56, v6
	ds_write_b16 v16, v12
	ds_write_b16_d16_hi v16, v12 offset:8704
	v_pk_mul_f32 v[16:17], v[24:25], v[14:15] op_sel:[1,0]
	s_nop 0
; __device__ __forceinline__ void dk_phase(const Frame& F, const bf16* QKrm, const unsigned char* KT, const unsigned char* VT, const float* BG, unsigned char* ITEMS) {
;     ...
;             const int c = dir ? 63 - lane : lane; const float bc = betaL[c], wc = bc * __expf(gamL[c]);
;             asm volatile("s_waitcnt lgkmcnt(0)" ::: "memory");
; #pragma unroll
;             for (int rp = 0; rp < 64; ++rp) { const int r = dir ? 63 - rp : rp;
;                 const unsigned w2 = pk2(t[rp] * wc, t[rp] * bc);
;                 *(LAS unsigned short*)(TW + r * TROW + c * 2) = (unsigned short)(w2 & 0xffffu);
;                 *(LAS unsigned short*)(TU + r * TROW + c * 2) = (unsigned short)(w2 >> 16); }
;         }
;         LDS_WAIT();
;         asm volatile("" ::: "memory"); __builtin_amdgcn_sched_barrier(0);
;         const unsigned char* ktb = KT + ((size_t)cb * 16 + hk) * 16384;
;         const unsigned char* vtb = VT + ((size_t)cb * 32 + hv) * 16384;
; #pragma unroll
;         for (int mt = 0; mt < 2; ++mt) {
;             bf16x8_t tb[2][2];
; #pragma unroll
;             for (int tt = 0; tt < 2; ++tt)
; #pragma unroll
;                 for (int s = 0; s < 2; ++s) { const LAS unsigned char* p = TW + (32 * mt + r32) * TROW + (32 * tt + 16 * s + 4 * hi) * 2;
;                     const v2u lo = *(const LAS v2u*)p, hi2 = *(const LAS v2u*)(p + 16); tb[tt][s] = as_frag((v4u){lo.x, lo.y, hi2.x, hi2.y}); }
;             bf16x8_t gf[16];
; #pragma unroll
;             for (int k = 0; k < 16; ++k) gf[k] = as_frag(*(const v4u*)(ktb + k * 1024 + lane * 16));
;             asm volatile("s_waitcnt vmcnt(0)" ::: "memory"); __builtin_amdgcn_sched_barrier(0);
; #pragma unroll
;             for (int dt = 0; dt < 4; ++dt) { f32x16_t acc = f32x16_t{};
; #pragma unroll
;                 for (int tt = 0; tt < 2; ++tt)
; #pragma unroll
;                     for (int s = 0; s < 2; ++s) { const bf16x8_t a = gf[(dt * 2 + tt) * 2 + s];
;                         acc = __builtin_amdgcn_mfma_f32_32x32x16_bf16(a, tb[tt][s], acc, 0, 0, 0); }
; #pragma unroll
;                 for (int st = 0; st < 2; ++st) { v4u wv; wv.x = pk2(acc[8 * st + 0], acc[8 * st + 1]); wv.y = pk2(acc[8 * st + 2], acc[8 * st + 3]); wv.z = pk2(acc[8 * st + 4], acc[8 * st + 5]); wv.w = pk2(acc[8 * st + 6], acc[8 * st + 7]);
;                     *(v4u*)(item + ITEM_W + ((mt * 4 + dt) * 2 + st) * 1024 + lane * 16) = wv; } }
	v_cvt_pk_bf16_f32 v12, v16, v17
	v_add_u32_e32 v16, s57, v6
	ds_write_b16 v16, v12
	ds_write_b16_d16_hi v16, v12 offset:8704
	v_pk_mul_f32 v[16:17], v[20:21], v[14:15] op_sel:[1,0]
	s_nop 0
	v_cvt_pk_bf16_f32 v12, v16, v17
	v_add_u32_e32 v16, s60, v6
	ds_write_b16 v16, v12
	ds_write_b16_d16_hi v16, v12 offset:8704
	v_pk_mul_f32 v[16:17], v[134:135], v[14:15] op_sel:[1,0]
	s_nop 0
	v_cvt_pk_bf16_f32 v12, v16, v17
	v_add_u32_e32 v16, s61, v6
	ds_write_b16 v16, v12
	ds_write_b16_d16_hi v16, v12 offset:8704
	v_pk_mul_f32 v[16:17], v[18:19], v[14:15] op_sel:[1,0]
	s_nop 0
	v_cvt_pk_bf16_f32 v12, v16, v17
	v_add_u32_e32 v16, s62, v6
	ds_write_b16 v16, v12
	ds_write_b16_d16_hi v16, v12 offset:8704
	ds_write_b16 v9, v8
	ds_write_b16_d16_hi v9, v8 offset:8704
	v_pk_mul_f32 v[8:9], v[10:11], v[14:15] op_sel:[1,0]
	s_nop 0
	v_cvt_pk_bf16_f32 v8, v8, v9
	v_add_u32_e32 v9, s74, v6
	ds_write_b16 v9, v8
	ds_write_b16_d16_hi v9, v8 offset:8704
	ds_write_b16 v5, v4
	ds_write_b16_d16_hi v5, v4 offset:8704
	v_mov_b32_e32 v4, v13
	v_pk_mul_f32 v[4:5], v[14:15], v[4:5] op_sel_hi:[1,0]
	s_nop 0
	v_cvt_pk_bf16_f32 v4, v4, v5
	v_add_u32_e32 v5, s76, v6
	ds_write_b16 v5, v4
	ds_write_b16_d16_hi v5, v4 offset:8704
	v_mov_b32_e32 v4, v7
	v_pk_mul_f32 v[4:5], v[14:15], v[4:5] op_sel_hi:[1,0]
	s_nop 0
	v_cvt_pk_bf16_f32 v4, v4, v5
	v_add_u32_e32 v5, s77, v6
	ds_write_b16 v5, v4
	ds_write_b16_d16_hi v5, v4 offset:8704
	v_pk_mul_f32 v[4:5], v[14:15], v[2:3] op_sel_hi:[1,0]
	s_nop 0
	v_cvt_pk_bf16_f32 v2, v4, v5
	v_add_u32_e32 v4, s88, v6
	ds_write_b16 v4, v2
	ds_write_b16_d16_hi v4, v2 offset:8704
	s_waitcnt lgkmcnt(0)
	s_ashr_i32 s21, s20, 31
	s_lshl_b64 s[42:43], s[20:21], 18
	s_lshl_b32 s44, s84, 14
	s_mov_b64 s[46:47], s[86:87]
	s_add_u32 s42, s46, s42
	s_addc_u32 s43, s47, s43
	s_add_u32 s42, s42, s44
	s_addc_u32 s43, s43, 0
	v_lshl_add_u64 v[56:57], s[42:43], 0, v[168:169]
	v_add_co_u32_e32 v60, vcc, s3, v56
	global_load_dwordx4 v[4:7], v[56:57], off
	global_load_dwordx4 v[8:11], v[56:57], off offset:1024
	global_load_dwordx4 v[12:15], v[56:57], off offset:2048
	global_load_dwordx4 v[16:19], v[56:57], off offset:3072
	v_addc_co_u32_e32 v61, vcc, 0, v57, vcc
	v_add_co_u32_e32 v58, vcc, s16, v56
	s_lshl_b64 s[20:21], s[20:21], 19
	s_nop 0
	v_addc_co_u32_e32 v59, vcc, 0, v57, vcc
	v_add_co_u32_e32 v62, vcc, s17, v56
	global_load_dwordx4 v[20:23], v[60:61], off offset:1024
	global_load_dwordx4 v[24:27], v[60:61], off offset:2048
	global_load_dwordx4 v[28:31], v[58:59], off
	global_load_dwordx4 v[64:67], v[58:59], off offset:1024
	global_load_dwordx4 v[68:71], v[58:59], off offset:2048
	global_load_dwordx4 v[72:75], v[58:59], off offset:3072
	v_addc_co_u32_e32 v63, vcc, 0, v57, vcc
	global_load_dwordx4 v[32:35], v[60:61], off offset:3072
	global_load_dwordx4 v[76:79], v[62:63], off
	global_load_dwordx4 v[80:83], v[62:63], off offset:1024
	global_load_dwordx4 v[84:87], v[62:63], off offset:2048
	global_load_dwordx4 v[88:91], v[58:59], off offset:-4096
	global_load_dwordx4 v[92:95], v[62:63], off offset:3072
	s_lshl_b32 s42, s83, 14
	s_add_u32 s20, s81, s20
	s_addc_u32 s21, s89, s21
	s_add_u32 s20, s20, s42
	s_addc_u32 s21, s21, 0
	v_add_u32_e32 v2, s53, v164
	v_lshl_add_u64 v[54:55], s[20:21], 0, v[168:169]
	s_movk_i32 s21, 0x88
	v_mad_u32_u24 v112, v186, s21, v2
	ds_read2_b64 v[96:99], v112 offset1:2
	ds_read2_b64 v[100:103], v112 offset0:4 offset1:6
	ds_read2_b64 v[104:107], v112 offset0:8 offset1:10
	ds_read2_b64 v[108:111], v112 offset0:12 offset1:14
	s_waitcnt vmcnt(0)
	v_lshlrev_b32_e32 v36, 5, v185
	v_ashrrev_i32_e32 v37, 31, v36
	v_lshl_add_u64 v[52:53], s[18:19], 0, v[36:37]
	s_waitcnt vmcnt(15) lgkmcnt(3)
	v_mfma_f32_32x32x16_bf16 v[36:51], v[4:7], v[96:99], 0
	s_mov_b32 s20, 0xffff6000
	s_waitcnt vmcnt(14) lgkmcnt(2)
	v_mfma_f32_32x32x16_bf16 v[36:51], v[8:11], v[100:103], v[36:51]
	s_waitcnt vmcnt(13) lgkmcnt(1)
	v_mfma_f32_32x32x16_bf16 v[36:51], v[12:15], v[104:107], v[36:51]
	s_waitcnt vmcnt(12) lgkmcnt(0)
	v_mfma_f32_32x32x16_bf16 v[36:51], v[16:19], v[108:111], v[36:51]
	s_waitcnt vmcnt(1)
	v_mfma_f32_32x32x16_bf16 v[4:19], v[88:91], v[96:99], 0
	s_nop 9
	v_cvt_pk_bf16_f32 v36, v36, v37
	v_cvt_pk_bf16_f32 v37, v38, v39
	v_cvt_pk_bf16_f32 v38, v40, v41
	v_add_co_u32_e32 v40, vcc, s20, v166
	s_mov_b32 s20, 0xffff7000
	s_nop 0
	v_addc_co_u32_e32 v41, vcc, -1, v167, vcc
	v_mfma_f32_32x32x16_bf16 v[4:19], v[20:23], v[100:103], v[4:19]
	v_cvt_pk_bf16_f32 v39, v42, v43
	global_store_dwordx4 v[40:41], v[36:39], off offset:-512
	s_nop 1
	v_cvt_pk_bf16_f32 v36, v44, v45
	v_cvt_pk_bf16_f32 v37, v46, v47
	v_cvt_pk_bf16_f32 v38, v48, v49
	v_mfma_f32_32x32x16_bf16 v[4:19], v[24:27], v[104:107], v[4:19]
	v_cvt_pk_bf16_f32 v39, v50, v51
	v_mfma_f32_32x32x16_bf16 v[4:19], v[32:35], v[108:111], v[4:19]
	v_mfma_f32_32x32x16_bf16 v[20:35], v[28:31], v[96:99], 0
	s_nop 10
	v_cvt_pk_bf16_f32 v4, v4, v5
	v_cvt_pk_bf16_f32 v5, v6, v7
	v_cvt_pk_bf16_f32 v6, v8, v9
	v_cvt_pk_bf16_f32 v7, v10, v11
	v_mfma_f32_32x32x16_bf16 v[20:35], v[64:67], v[100:103], v[20:35]
	v_add_co_u32_e32 v64, vcc, s20, v166
	s_movk_i32 s20, 0x8000
	s_nop 0
	v_addc_co_u32_e32 v65, vcc, -1, v167, vcc
	global_store_dwordx4 v[64:65], v[36:39], off offset:-3584
	global_store_dwordx4 v[64:65], v[4:7], off offset:-2560
	v_mfma_f32_32x32x16_bf16 v[20:35], v[68:71], v[104:107], v[20:35]
	s_nop 0
	v_cvt_pk_bf16_f32 v4, v12, v13
	v_cvt_pk_bf16_f32 v5, v14, v15
	v_cvt_pk_bf16_f32 v6, v16, v17
	v_cvt_pk_bf16_f32 v7, v18, v19
	global_store_dwordx4 v[64:65], v[4:7], off offset:-1536
	v_mfma_f32_32x32x16_bf16 v[36:51], v[76:79], v[96:99], 0
	v_mfma_f32_32x32x16_bf16 v[36:51], v[80:83], v[100:103], v[36:51]
	v_mfma_f32_32x32x16_bf16 v[36:51], v[84:87], v[104:107], v[36:51]
	v_mfma_f32_32x32x16_bf16 v[20:35], v[72:75], v[108:111], v[20:35]
	v_add_co_u32_e32 v72, vcc, s20, v166
	s_nop 1
	v_addc_co_u32_e32 v73, vcc, -1, v167, vcc
	v_add_co_u32_e32 v66, vcc, s3, v54
	s_waitcnt vmcnt(4)
; __device__ __forceinline__ void dk_phase(const Frame& F, const bf16* QKrm, const unsigned char* KT, const unsigned char* VT, const float* BG, unsigned char* ITEMS) {
;     ...
;         for (int mt = 0; mt < 2; ++mt) {
;             bf16x8_t tb[2][2];
; #pragma unroll
;             for (int tt = 0; tt < 2; ++tt)
; #pragma unroll
;                 for (int s = 0; s < 2; ++s) { const LAS unsigned char* p = TW + (32 * mt + r32) * TROW + (32 * tt + 16 * s + 4 * hi) * 2;
;                     const v2u lo = *(const LAS v2u*)p, hi2 = *(const LAS v2u*)(p + 16); tb[tt][s] = as_frag((v4u){lo.x, lo.y, hi2.x, hi2.y}); }
;             bf16x8_t gf[16];
; #pragma unroll
;             for (int k = 0; k < 16; ++k) gf[k] = as_frag(*(const v4u*)(ktb + k * 1024 + lane * 16));
;             asm volatile("s_waitcnt vmcnt(0)" ::: "memory"); __builtin_amdgcn_sched_barrier(0);
; #pragma unroll
;             for (int dt = 0; dt < 4; ++dt) { f32x16_t acc = f32x16_t{};
; #pragma unroll
;                 for (int tt = 0; tt < 2; ++tt)
; #pragma unroll
;                     for (int s = 0; s < 2; ++s) { const bf16x8_t a = gf[(dt * 2 + tt) * 2 + s];
;                         acc = __builtin_amdgcn_mfma_f32_32x32x16_bf16(a, tb[tt][s], acc, 0, 0, 0); }
; #pragma unroll
;                 for (int st = 0; st < 2; ++st) { v4u wv; wv.x = pk2(acc[8 * st + 0], acc[8 * st + 1]); wv.y = pk2(acc[8 * st + 2], acc[8 * st + 3]); wv.z = pk2(acc[8 * st + 4], acc[8 * st + 5]); wv.w = pk2(acc[8 * st + 6], acc[8 * st + 7]);
;                     *(v4u*)(item + ITEM_W + ((mt * 4 + dt) * 2 + st) * 1024 + lane * 16) = wv; } }
;             bf16x8_t ta[2][2];
; #pragma unroll
;             for (int tt = 0; tt < 2; ++tt)
; #pragma unroll
;                 for (int s = 0; s < 2; ++s) { const LAS unsigned char* p = TU + (32 * mt + r32) * TROW + (32 * tt + 16 * s + 4 * hi) * 2;
;                     const v2u lo = *(const LAS v2u*)p, hi2 = *(const LAS v2u*)(p + 16); ta[tt][s] = as_frag((v4u){lo.x, lo.y, hi2.x, hi2.y}); }
; #pragma unroll
;             for (int k = 0; k < 16; ++k) gf[k] = as_frag(*(const v4u*)(vtb + k * 1024 + lane * 16));
;             asm volatile("s_waitcnt vmcnt(0)" ::: "memory"); __builtin_amdgcn_sched_barrier(0);
; #pragma unroll
;             for (int vt = 0; vt < 4; ++vt) { f32x16_t acc = f32x16_t{};
; #pragma unroll
;                 for (int tt = 0; tt < 2; ++tt)
; #pragma unroll
	v_mfma_f32_32x32x16_bf16 v[36:51], v[92:95], v[108:111], v[36:51]
	s_nop 4
	v_cvt_pk_bf16_f32 v4, v20, v21
	v_cvt_pk_bf16_f32 v5, v22, v23
	v_cvt_pk_bf16_f32 v6, v24, v25
	v_cvt_pk_bf16_f32 v7, v26, v27
	global_store_dwordx4 v[64:65], v[4:7], off offset:-512
	v_addc_co_u32_e32 v67, vcc, 0, v55, vcc
	s_nop 0
	v_cvt_pk_bf16_f32 v4, v28, v29
	v_cvt_pk_bf16_f32 v5, v30, v31
	v_cvt_pk_bf16_f32 v6, v32, v33
	v_cvt_pk_bf16_f32 v7, v34, v35
	global_store_dwordx4 v[72:73], v[4:7], off offset:-3584
	v_add_co_u32_e32 v64, vcc, s16, v54
	s_nop 0
	v_cvt_pk_bf16_f32 v4, v36, v37
	v_cvt_pk_bf16_f32 v5, v38, v39
	v_cvt_pk_bf16_f32 v6, v40, v41
	v_cvt_pk_bf16_f32 v7, v42, v43
	global_store_dwordx4 v[72:73], v[4:7], off offset:-2560
	v_addc_co_u32_e32 v65, vcc, 0, v55, vcc
	s_nop 0
	v_cvt_pk_bf16_f32 v4, v44, v45
	v_cvt_pk_bf16_f32 v5, v46, v47
	v_cvt_pk_bf16_f32 v6, v48, v49
	v_cvt_pk_bf16_f32 v7, v50, v51
	global_store_dwordx4 v[72:73], v[4:7], off offset:-1536
	v_add_co_u32_e32 v68, vcc, s17, v54
	global_load_dwordx4 v[4:7], v[54:55], off
	global_load_dwordx4 v[8:11], v[54:55], off offset:1024
	global_load_dwordx4 v[12:15], v[54:55], off offset:2048
	global_load_dwordx4 v[16:19], v[54:55], off offset:3072
	global_load_dwordx4 v[20:23], v[66:67], off offset:1024
	global_load_dwordx4 v[24:27], v[66:67], off offset:2048
	global_load_dwordx4 v[28:31], v[64:65], off
	global_load_dwordx4 v[74:77], v[64:65], off offset:1024
	global_load_dwordx4 v[78:81], v[64:65], off offset:2048
	global_load_dwordx4 v[82:85], v[64:65], off offset:3072
	v_addc_co_u32_e32 v69, vcc, 0, v55, vcc
	global_load_dwordx4 v[32:35], v[66:67], off offset:3072
	global_load_dwordx4 v[86:89], v[68:69], off
	global_load_dwordx4 v[90:93], v[68:69], off offset:1024
	global_load_dwordx4 v[94:97], v[68:69], off offset:2048
	global_load_dwordx4 v[98:101], v[64:65], off offset:-4096
	global_load_dwordx4 v[102:105], v[68:69], off offset:3072
	v_add_u32_e32 v36, 0x2000, v112
	ds_read2_b64 v[106:109], v36 offset0:64 offset1:66
	ds_read2_b64 v[110:113], v36 offset0:68 offset1:70
	ds_read2_b64 v[114:117], v36 offset0:72 offset1:74
	ds_read2_b64 v[118:121], v36 offset0:76 offset1:78
	s_waitcnt vmcnt(0)
	s_waitcnt vmcnt(15) lgkmcnt(3)
	v_mfma_f32_32x32x16_bf16 v[36:51], v[106:109], v[4:7], 0
	s_movk_i32 s20, 0xd000
	v_mad_u32_u24 v2, v187, s21, v2
	s_waitcnt vmcnt(14) lgkmcnt(2)
	v_mfma_f32_32x32x16_bf16 v[36:51], v[110:113], v[8:11], v[36:51]
	s_waitcnt vmcnt(13) lgkmcnt(1)
	v_mfma_f32_32x32x16_bf16 v[36:51], v[114:117], v[12:15], v[36:51]
	s_waitcnt vmcnt(12) lgkmcnt(0)
	v_mfma_f32_32x32x16_bf16 v[36:51], v[118:121], v[16:19], v[36:51]
	s_waitcnt vmcnt(1)
	v_mfma_f32_32x32x16_bf16 v[4:19], v[106:109], v[98:101], 0
	s_nop 9
	v_cvt_pk_bf16_f32 v36, v36, v37
	v_cvt_pk_bf16_f32 v37, v38, v39
	v_cvt_pk_bf16_f32 v38, v40, v41
	v_cvt_pk_bf16_f32 v40, v44, v45
	v_add_co_u32_e32 v44, vcc, s90, v52
	v_cvt_pk_bf16_f32 v39, v42, v43
	v_mfma_f32_32x32x16_bf16 v[4:19], v[110:113], v[20:23], v[4:19]
	v_cvt_pk_bf16_f32 v41, v46, v47
	v_cvt_pk_bf16_f32 v42, v48, v49
	v_cvt_pk_bf16_f32 v43, v50, v51
	v_addc_co_u32_e32 v45, vcc, -1, v53, vcc
	global_store_dwordx4 v[44:45], v[36:39], off offset:-512
	global_store_dwordx4 v[44:45], v[40:43], off offset:-496
	v_add_co_u32_e32 v70, vcc, s20, v52
	v_mfma_f32_32x32x16_bf16 v[4:19], v[114:117], v[24:27], v[4:19]
	s_nop 0
	v_addc_co_u32_e32 v71, vcc, -1, v53, vcc
	s_movk_i32 s20, 0xe000
	v_mfma_f32_32x32x16_bf16 v[4:19], v[118:121], v[32:35], v[4:19]
	v_mfma_f32_32x32x16_bf16 v[20:35], v[106:109], v[28:31], 0
	s_nop 10
	v_cvt_pk_bf16_f32 v4, v4, v5
	v_cvt_pk_bf16_f32 v5, v6, v7
	v_cvt_pk_bf16_f32 v6, v8, v9
	v_cvt_pk_bf16_f32 v7, v10, v11
	v_cvt_pk_bf16_f32 v8, v12, v13
	v_cvt_pk_bf16_f32 v9, v14, v15
	v_cvt_pk_bf16_f32 v10, v16, v17
	v_mfma_f32_32x32x16_bf16 v[36:51], v[106:109], v[86:89], 0
	v_cvt_pk_bf16_f32 v11, v18, v19
	global_store_dwordx4 v[70:71], v[4:7], off offset:-512
	global_store_dwordx4 v[70:71], v[8:11], off offset:-496
	v_mfma_f32_32x32x16_bf16 v[20:35], v[110:113], v[74:77], v[20:35]
	v_add_co_u32_e32 v74, vcc, s20, v52
	s_movk_i32 s20, 0xf000
	s_nop 0
	v_addc_co_u32_e32 v75, vcc, -1, v53, vcc
	v_add_co_u32_e32 v76, vcc, s20, v52
	v_mfma_f32_32x32x16_bf16 v[36:51], v[110:113], v[90:93], v[36:51]
	s_nop 0
	v_addc_co_u32_e32 v77, vcc, -1, v53, vcc
	v_mfma_f32_32x32x16_bf16 v[20:35], v[114:117], v[78:81], v[20:35]
	v_mfma_f32_32x32x16_bf16 v[36:51], v[114:117], v[94:97], v[36:51]
	v_mfma_f32_32x32x16_bf16 v[20:35], v[118:121], v[82:85], v[20:35]
	s_waitcnt vmcnt(4)
	v_mfma_f32_32x32x16_bf16 v[36:51], v[118:121], v[102:105], v[36:51]
	s_nop 9
	v_cvt_pk_bf16_f32 v4, v20, v21
	v_cvt_pk_bf16_f32 v5, v22, v23
	v_cvt_pk_bf16_f32 v6, v24, v25
	v_cvt_pk_bf16_f32 v7, v26, v27
	v_cvt_pk_bf16_f32 v8, v28, v29
	v_cvt_pk_bf16_f32 v9, v30, v31
	v_cvt_pk_bf16_f32 v10, v32, v33
	v_cvt_pk_bf16_f32 v11, v34, v35
	global_store_dwordx4 v[74:75], v[4:7], off offset:-512
	global_store_dwordx4 v[74:75], v[8:11], off offset:-496
	s_nop 0
	v_cvt_pk_bf16_f32 v4, v36, v37
	v_cvt_pk_bf16_f32 v5, v38, v39
	v_cvt_pk_bf16_f32 v6, v40, v41
	v_cvt_pk_bf16_f32 v7, v42, v43
	v_cvt_pk_bf16_f32 v8, v44, v45
	v_cvt_pk_bf16_f32 v9, v46, v47
	v_cvt_pk_bf16_f32 v10, v48, v49
	v_cvt_pk_bf16_f32 v11, v50, v51
	global_store_dwordx4 v[76:77], v[4:7], off offset:-512
	global_store_dwordx4 v[76:77], v[8:11], off offset:-496
	global_load_dwordx4 v[4:7], v[56:57], off
	s_nop 0
	global_load_dwordx4 v[8:11], v[56:57], off offset:1024
	global_load_dwordx4 v[12:15], v[56:57], off offset:2048
	global_load_dwordx4 v[16:19], v[56:57], off offset:3072
	global_load_dwordx4 v[36:39], v[60:61], off offset:1024
	global_load_dwordx4 v[40:43], v[60:61], off offset:2048
	global_load_dwordx4 v[44:47], v[60:61], off offset:3072
	global_load_dwordx4 v[48:51], v[62:63], off offset:-4096
	global_load_dwordx4 v[78:81], v[58:59], off offset:-4096
	global_load_dwordx4 v[82:85], v[58:59], off offset:1024
	global_load_dwordx4 v[86:89], v[58:59], off offset:2048
	s_nop 0
	global_load_dwordx4 v[56:59], v[58:59], off offset:3072
	s_nop 0
	global_load_dwordx4 v[90:93], v[62:63], off
	global_load_dwordx4 v[94:97], v[62:63], off offset:1024
	global_load_dwordx4 v[98:101], v[62:63], off offset:2048
	s_nop 0
	global_load_dwordx4 v[60:63], v[62:63], off offset:3072
	ds_read2_b64 v[102:105], v2 offset1:2
	ds_read2_b64 v[106:109], v2 offset0:4 offset1:6
	ds_read2_b64 v[110:113], v2 offset0:8 offset1:10
	ds_read2_b64 v[114:117], v2 offset0:12 offset1:14
	s_waitcnt vmcnt(0)
; __device__ __forceinline__ void dk_phase(const Frame& F, const bf16* QKrm, const unsigned char* KT, const unsigned char* VT, const float* BG, unsigned char* ITEMS) {
;     ...
;         for (int mt = 0; mt < 2; ++mt) {
;             bf16x8_t tb[2][2];
; #pragma unroll
;             for (int tt = 0; tt < 2; ++tt)
; #pragma unroll
;                 for (int s = 0; s < 2; ++s) { const LAS unsigned char* p = TW + (32 * mt + r32) * TROW + (32 * tt + 16 * s + 4 * hi) * 2;
;                     const v2u lo = *(const LAS v2u*)p, hi2 = *(const LAS v2u*)(p + 16); tb[tt][s] = as_frag((v4u){lo.x, lo.y, hi2.x, hi2.y}); }
;             bf16x8_t gf[16];
; #pragma unroll
;             for (int k = 0; k < 16; ++k) gf[k] = as_frag(*(const v4u*)(ktb + k * 1024 + lane * 16));
;             asm volatile("s_waitcnt vmcnt(0)" ::: "memory"); __builtin_amdgcn_sched_barrier(0);
; #pragma unroll
;             for (int dt = 0; dt < 4; ++dt) { f32x16_t acc = f32x16_t{};
; #pragma unroll
;                 for (int tt = 0; tt < 2; ++tt)
; #pragma unroll
;                     for (int s = 0; s < 2; ++s) { const bf16x8_t a = gf[(dt * 2 + tt) * 2 + s];
;                         acc = __builtin_amdgcn_mfma_f32_32x32x16_bf16(a, tb[tt][s], acc, 0, 0, 0); }
; #pragma unroll
;                 for (int st = 0; st < 2; ++st) { v4u wv; wv.x = pk2(acc[8 * st + 0], acc[8 * st + 1]); wv.y = pk2(acc[8 * st + 2], acc[8 * st + 3]); wv.z = pk2(acc[8 * st + 4], acc[8 * st + 5]); wv.w = pk2(acc[8 * st + 6], acc[8 * st + 7]);
;                     *(v4u*)(item + ITEM_W + ((mt * 4 + dt) * 2 + st) * 1024 + lane * 16) = wv; } }
;             bf16x8_t ta[2][2];
; #pragma unroll
;             for (int tt = 0; tt < 2; ++tt)
; #pragma unroll
;                 for (int s = 0; s < 2; ++s) { const LAS unsigned char* p = TU + (32 * mt + r32) * TROW + (32 * tt + 16 * s + 4 * hi) * 2;
;                     const v2u lo = *(const LAS v2u*)p, hi2 = *(const LAS v2u*)(p + 16); ta[tt][s] = as_frag((v4u){lo.x, lo.y, hi2.x, hi2.y}); }
; #pragma unroll
;             for (int k = 0; k < 16; ++k) gf[k] = as_frag(*(const v4u*)(vtb + k * 1024 + lane * 16));
;             asm volatile("s_waitcnt vmcnt(0)" ::: "memory"); __builtin_amdgcn_sched_barrier(0);
; #pragma unroll
;             for (int vt = 0; vt < 4; ++vt) { f32x16_t acc = f32x16_t{};
; #pragma unroll
;                 for (int tt = 0; tt < 2; ++tt)
; #pragma unroll
	s_waitcnt vmcnt(15) lgkmcnt(3)
	v_mfma_f32_32x32x16_bf16 v[20:35], v[4:7], v[102:105], 0
	s_movk_i32 s20, 0x9000
	v_add_u32_e32 v2, 0x2000, v2
	s_waitcnt vmcnt(14) lgkmcnt(2)
	v_mfma_f32_32x32x16_bf16 v[20:35], v[8:11], v[106:109], v[20:35]
	s_waitcnt vmcnt(13) lgkmcnt(1)
	v_mfma_f32_32x32x16_bf16 v[20:35], v[12:15], v[110:113], v[20:35]
	s_waitcnt vmcnt(12) lgkmcnt(0)
	v_mfma_f32_32x32x16_bf16 v[20:35], v[16:19], v[114:117], v[20:35]
	s_waitcnt vmcnt(7)
	v_mfma_f32_32x32x16_bf16 v[4:19], v[78:81], v[102:105], 0
	s_nop 9
	v_cvt_pk_bf16_f32 v20, v20, v21
	v_cvt_pk_bf16_f32 v21, v22, v23
	v_cvt_pk_bf16_f32 v22, v24, v25
	v_cvt_pk_bf16_f32 v23, v26, v27
	global_store_dwordx4 v[72:73], v[20:23], off offset:-512
	v_cvt_pk_bf16_f32 v78, v28, v29
	v_cvt_pk_bf16_f32 v79, v30, v31
	v_mfma_f32_32x32x16_bf16 v[4:19], v[36:39], v[106:109], v[4:19]
	v_cvt_pk_bf16_f32 v80, v32, v33
	v_cvt_pk_bf16_f32 v81, v34, v35
	v_mfma_f32_32x32x16_bf16 v[4:19], v[40:43], v[110:113], v[4:19]
	v_mfma_f32_32x32x16_bf16 v[4:19], v[44:47], v[114:117], v[4:19]
	v_mfma_f32_32x32x16_bf16 v[36:51], v[48:51], v[102:105], 0
	s_nop 10
	v_cvt_pk_bf16_f32 v4, v4, v5
	v_cvt_pk_bf16_f32 v5, v6, v7
	v_cvt_pk_bf16_f32 v6, v8, v9
	v_cvt_pk_bf16_f32 v7, v10, v11
	s_waitcnt vmcnt(4)
	v_mfma_f32_32x32x16_bf16 v[20:35], v[90:93], v[102:105], 0
	v_mfma_f32_32x32x16_bf16 v[36:51], v[82:85], v[106:109], v[36:51]
	s_waitcnt vmcnt(3)
	v_mfma_f32_32x32x16_bf16 v[20:35], v[94:97], v[106:109], v[20:35]
	v_mfma_f32_32x32x16_bf16 v[36:51], v[86:89], v[110:113], v[36:51]
	s_waitcnt vmcnt(2)
	v_mfma_f32_32x32x16_bf16 v[20:35], v[98:101], v[110:113], v[20:35]
	v_mfma_f32_32x32x16_bf16 v[36:51], v[56:59], v[114:117], v[36:51]
	v_add_co_u32_e32 v56, vcc, s20, v166
	s_nop 1
	v_addc_co_u32_e32 v57, vcc, -1, v167, vcc
	global_store_dwordx4 v[56:57], v[4:7], off offset:-2560
	global_store_dwordx4 v[56:57], v[78:81], off offset:-3584
	s_waitcnt vmcnt(3)
	v_mfma_f32_32x32x16_bf16 v[20:35], v[60:63], v[114:117], v[20:35]
	v_cvt_pk_bf16_f32 v4, v12, v13
	v_cvt_pk_bf16_f32 v5, v14, v15
	v_cvt_pk_bf16_f32 v6, v16, v17
	v_cvt_pk_bf16_f32 v7, v18, v19
	global_store_dwordx4 v[56:57], v[4:7], off offset:-1536
	s_nop 1
	v_cvt_pk_bf16_f32 v4, v36, v37
	v_cvt_pk_bf16_f32 v5, v38, v39
	v_cvt_pk_bf16_f32 v6, v40, v41
	v_cvt_pk_bf16_f32 v7, v42, v43
	global_store_dwordx4 v[56:57], v[4:7], off offset:-512
	s_nop 1
	v_cvt_pk_bf16_f32 v4, v44, v45
	v_cvt_pk_bf16_f32 v5, v46, v47
	v_cvt_pk_bf16_f32 v6, v48, v49
	v_cvt_pk_bf16_f32 v7, v50, v51
	global_store_dwordx4 v[170:171], v[4:7], off offset:-3584
	s_nop 1
	v_cvt_pk_bf16_f32 v4, v20, v21
	v_cvt_pk_bf16_f32 v5, v22, v23
	v_cvt_pk_bf16_f32 v6, v24, v25
	v_cvt_pk_bf16_f32 v7, v26, v27
	global_store_dwordx4 v[170:171], v[4:7], off offset:-2560
	s_nop 1
	v_cvt_pk_bf16_f32 v4, v28, v29
	v_cvt_pk_bf16_f32 v5, v30, v31
	v_cvt_pk_bf16_f32 v6, v32, v33
	v_cvt_pk_bf16_f32 v7, v34, v35
	global_store_dwordx4 v[170:171], v[4:7], off offset:-1536
	global_load_dwordx4 v[4:7], v[54:55], off
	s_nop 0
	global_load_dwordx4 v[8:11], v[54:55], off offset:1024
	global_load_dwordx4 v[12:15], v[54:55], off offset:2048
	global_load_dwordx4 v[16:19], v[54:55], off offset:3072
	global_load_dwordx4 v[36:39], v[66:67], off offset:1024
	global_load_dwordx4 v[40:43], v[66:67], off offset:2048
	global_load_dwordx4 v[44:47], v[66:67], off offset:3072
	global_load_dwordx4 v[48:51], v[68:69], off offset:-4096
	s_nop 0
	global_load_dwordx4 v[54:57], v[64:65], off offset:-4096
	global_load_dwordx4 v[58:61], v[64:65], off offset:1024
	global_load_dwordx4 v[78:81], v[64:65], off offset:2048
	s_nop 0
	global_load_dwordx4 v[62:65], v[64:65], off offset:3072
	s_nop 0
	global_load_dwordx4 v[82:85], v[68:69], off
	global_load_dwordx4 v[86:89], v[68:69], off offset:1024
	global_load_dwordx4 v[90:93], v[68:69], off offset:2048
	s_nop 0
	global_load_dwordx4 v[66:69], v[68:69], off offset:3072
	ds_read2_b64 v[94:97], v2 offset0:64 offset1:66
	ds_read2_b64 v[98:101], v2 offset0:68 offset1:70
	ds_read2_b64 v[102:105], v2 offset0:72 offset1:74
	ds_read2_b64 v[106:109], v2 offset0:76 offset1:78
	s_waitcnt vmcnt(0)
; #define LDS_WAIT() asm volatile("s_waitcnt lgkmcnt(0)" ::: "memory")
; __device__ __forceinline__ unsigned pk2(float lo, float hi) { const f32x2_cv v = {lo, hi}; const bf16x2_cv b = __builtin_convertvector(v, bf16x2_cv); return __builtin_bit_cast(unsigned, b); }
; __device__ __forceinline__ void dk_phase(const Frame& F, const bf16* QKrm, const unsigned char* KT, const unsigned char* VT, const float* BG, unsigned char* ITEMS) {
;     ...
;     for (int it = F.gw; it < NCB * 64; it += F.NGW) {
;     ...
;             for (int vt = 0; vt < 4; ++vt) { f32x16_t acc = f32x16_t{};
; #pragma unroll
;                 for (int tt = 0; tt < 2; ++tt)
; #pragma unroll
;                     for (int s = 0; s < 2; ++s) { const bf16x8_t b = gf[(vt * 2 + tt) * 2 + s];
;                         acc = __builtin_amdgcn_mfma_f32_32x32x16_bf16(ta[tt][s], b, acc, 0, 0, 0); }
;                 v4u w0, w1; w0.x = pk2(acc[0], acc[1]); w0.y = pk2(acc[2], acc[3]); w0.z = pk2(acc[4], acc[5]); w0.w = pk2(acc[6], acc[7]);
;                 w1.x = pk2(acc[8], acc[9]); w1.y = pk2(acc[10], acc[11]); w1.z = pk2(acc[12], acc[13]); w1.w = pk2(acc[14], acc[15]);
;                 unsigned char* d = item + ITEM_U + (vt * 2 + mt) * 2048 + lane * 32;
;                 *(v4u*)d = w0; *(v4u*)(d + 16) = w1; }
;         }
;         LDS_WAIT();
;     }
	s_waitcnt vmcnt(15) lgkmcnt(3)
	v_mfma_f32_32x32x16_bf16 v[20:35], v[94:97], v[4:7], 0
	s_add_i32 s52, s52, s64
	s_mul_i32 s20, s50, 0x52000
	s_add_u32 s18, s18, s20
	s_mul_hi_i32 s20, s64, 0xa400
	s_addc_u32 s19, s19, s20
	s_cmpk_lt_i32 s52, 0x4100
	s_waitcnt vmcnt(14) lgkmcnt(2)
	v_mfma_f32_32x32x16_bf16 v[20:35], v[98:101], v[8:11], v[20:35]
	s_waitcnt vmcnt(13) lgkmcnt(1)
	v_mfma_f32_32x32x16_bf16 v[20:35], v[102:105], v[12:15], v[20:35]
	s_waitcnt vmcnt(12) lgkmcnt(0)
	v_mfma_f32_32x32x16_bf16 v[20:35], v[106:109], v[16:19], v[20:35]
	s_waitcnt vmcnt(7)
	v_mfma_f32_32x32x16_bf16 v[4:19], v[94:97], v[54:57], 0
	s_nop 9
	v_cvt_pk_bf16_f32 v20, v20, v21
	v_cvt_pk_bf16_f32 v21, v22, v23
	v_cvt_pk_bf16_f32 v22, v24, v25
	v_cvt_pk_bf16_f32 v23, v26, v27
	v_cvt_pk_bf16_f32 v54, v28, v29
	v_cvt_pk_bf16_f32 v55, v30, v31
	v_cvt_pk_bf16_f32 v56, v32, v33
	v_mfma_f32_32x32x16_bf16 v[4:19], v[98:101], v[36:39], v[4:19]
	v_cvt_pk_bf16_f32 v57, v34, v35
	global_store_dwordx4 v[70:71], v[20:23], off offset:-2560
	global_store_dwordx4 v[70:71], v[54:57], off offset:-2544
	v_mfma_f32_32x32x16_bf16 v[4:19], v[102:105], v[40:43], v[4:19]
	v_mfma_f32_32x32x16_bf16 v[4:19], v[106:109], v[44:47], v[4:19]
	v_mfma_f32_32x32x16_bf16 v[36:51], v[94:97], v[48:51], 0
	s_nop 10
	v_cvt_pk_bf16_f32 v4, v4, v5
	v_cvt_pk_bf16_f32 v5, v6, v7
	v_cvt_pk_bf16_f32 v6, v8, v9
	v_cvt_pk_bf16_f32 v7, v10, v11
	v_cvt_pk_bf16_f32 v8, v12, v13
	v_cvt_pk_bf16_f32 v9, v14, v15
	v_cvt_pk_bf16_f32 v10, v16, v17
	s_waitcnt vmcnt(5)
	v_mfma_f32_32x32x16_bf16 v[20:35], v[94:97], v[82:85], 0
	v_cvt_pk_bf16_f32 v11, v18, v19
	global_store_dwordx4 v[74:75], v[4:7], off offset:-2560
	global_store_dwordx4 v[74:75], v[8:11], off offset:-2544
	v_mfma_f32_32x32x16_bf16 v[36:51], v[98:101], v[58:61], v[36:51]
	s_waitcnt vmcnt(6)
	v_mfma_f32_32x32x16_bf16 v[20:35], v[98:101], v[86:89], v[20:35]
	v_mfma_f32_32x32x16_bf16 v[36:51], v[102:105], v[78:81], v[36:51]
	s_waitcnt vmcnt(5)
	v_mfma_f32_32x32x16_bf16 v[20:35], v[102:105], v[90:93], v[20:35]
	v_mfma_f32_32x32x16_bf16 v[36:51], v[106:109], v[62:65], v[36:51]
	s_waitcnt vmcnt(4)
	v_mfma_f32_32x32x16_bf16 v[20:35], v[106:109], v[66:69], v[20:35]
	s_nop 9
	v_cvt_pk_bf16_f32 v4, v36, v37
	v_cvt_pk_bf16_f32 v5, v38, v39
	v_cvt_pk_bf16_f32 v6, v40, v41
	v_cvt_pk_bf16_f32 v7, v42, v43
	v_cvt_pk_bf16_f32 v8, v44, v45
	v_cvt_pk_bf16_f32 v9, v46, v47
	v_cvt_pk_bf16_f32 v10, v48, v49
	v_cvt_pk_bf16_f32 v11, v50, v51
	global_store_dwordx4 v[76:77], v[4:7], off offset:-2560
	global_store_dwordx4 v[76:77], v[8:11], off offset:-2544
	s_nop 0
	v_cvt_pk_bf16_f32 v4, v20, v21
	v_cvt_pk_bf16_f32 v5, v22, v23
	v_cvt_pk_bf16_f32 v6, v24, v25
	v_cvt_pk_bf16_f32 v7, v26, v27
	v_cvt_pk_bf16_f32 v8, v28, v29
	v_cvt_pk_bf16_f32 v9, v30, v31
	v_cvt_pk_bf16_f32 v10, v32, v33
	v_cvt_pk_bf16_f32 v11, v34, v35
	global_store_dwordx4 v[52:53], v[4:7], off offset:-2560
	global_store_dwordx4 v[52:53], v[8:11], off offset:-2544
	s_waitcnt lgkmcnt(0)
	s_cbranch_scc0 .LBB0_595
